# GEMM loops: s_setprio moved off the barrier-to-MFMA handoff (prio 1 raised before the barrier, lowered after the closing barrier), mid-block prio flips and redundant post-barrier lgkmcnt wait removed
# speedup vs baseline: 1.0089x; 1.0089x over previous
; #define PG8_STAGE(bufoff, gbase, voff) do { _Pragma("unroll") for (int _i = 0; _i < 2; ++_i) \
;         __builtin_amdgcn_global_load_lds((const unsigned*)((const char*)(gbase) + (voff)[_i]), (LAS unsigned*)(lds + (bufoff) + ldsw + _i * 8192), 16, 0, 0); } while (0)
; #define PG8_LDA(dst, b, h) do { _Pragma("unroll") for (int m = 0; m < 4; ++m) _Pragma("unroll") for (int k = 0; k < 2; ++k) dst[m][k] = *(const LAS half8*)(lds + PG8_SA(b, h) + aoff + m * 2048 + k * 1024); } while (0)
; #define PG8_LDB(dst, b, h) do { _Pragma("unroll") for (int n = 0; n < 2; ++n) _Pragma("unroll") for (int k = 0; k < 2; ++k) dst[n][k] = *(const LAS half8*)(lds + PG8_SB(b, h) + boff + n * 2048 + k * 1024); } while (0)
; #define PG8_MMA(ai, bj, At, Bt) do { __builtin_amdgcn_s_setprio(1); _Pragma("unroll") for (int m = 0; m < 4; ++m) _Pragma("unroll") for (int n = 0; n < 2; ++n) _Pragma("unroll") for (int k = 0; k < 2; ++k) \
;         acc[ai][bj][m][n] = __builtin_amdgcn_mfma_f32_16x16x32_f16(Bt[n][k], At[m][k], acc[ai][bj][m][n], 0, 0, 0); __builtin_amdgcn_s_setprio(0); } while (0)
; #define PG8_WAIT_V(n) asm volatile("s_waitcnt vmcnt(" #n ")" ::: "memory")
; template <class Epi, class Sched, bool ALIGN_EPI = false, bool SP2 = false>
; __device__ __forceinline__ void gemm_phase(LAS unsigned char* lds, const Gemm g, const Sched& S, const Epi& E) {
;     ...
;             PG8_LDB(B0, 0, 0); PG8_LDB(B1, 0, 1); PG8_SCHED; PG8_LDA(At, 0, 0); PG8_STAGE(PG8_SA(1, 1), a1 + hstepA, voffA);
;             PG8_WAIT_V(8); PG8_WAIT_L(0); PG8_BAR; PG8_MMA(0, 0, At, B0); PG8_MMA(0, 1, At, B1); PG8_BAR; PG8_SCHED;
;             PG8_LDA(At, 0, 1); PG8_STAGE(PG8_SB(0, 0), b2, voffB); PG8_STAGE(PG8_SB(0, 1), b2 + hstepB, voffB); PG8_STAGE(PG8_SA(0, 0), a2, voffA);
;             PG8_WAIT_V(8); PG8_WAIT_L(0); PG8_BAR; PG8_MMA(1, 0, At, B0); PG8_MMA(1, 1, At, B1); PG8_BAR; PG8_SCHED;
;             PG8_LDB(B0, 1, 0); PG8_LDB(B1, 1, 1); PG8_SCHED; PG8_LDA(At, 1, 0); PG8_STAGE(PG8_SA(0, 1), a2 + hstepA, voffA);
;             PG8_WAIT_V(8); PG8_WAIT_L(0); PG8_BAR; PG8_MMA(0, 0, At, B0); PG8_MMA(0, 1, At, B1); PG8_BAR; PG8_SCHED;
;             PG8_LDA(At, 1, 1); PG8_STAGE(PG8_SB(1, 0), b3, voffB); PG8_STAGE(PG8_SB(1, 1), b3 + hstepB, voffB); PG8_STAGE(PG8_SA(1, 0), a3, voffA);
;             PG8_WAIT_V(8); PG8_WAIT_L(0); PG8_BAR; PG8_MMA(1, 0, At, B0); PG8_MMA(1, 1, At, B1); PG8_BAR; PG8_SCHED;
.LBB0_415:
	s_add_u32 s16, s48, 0xfff80080
	s_addc_u32 s17, s49, -1
	s_add_i32 s65, 0, 0x10000
	s_cmp_eq_u32 s64, 28
	s_cselect_b32 s23, s13, s17
	s_cselect_b32 s22, s60, s16
	s_cselect_b32 s17, s11, s63
	s_cselect_b32 s16, s61, s62
	s_add_i32 s68, 0, 0x14000
	v_add_u32_e32 v158, s65, v144
	v_add_u32_e32 v174, s68, v144
	ds_read_b128 v[146:149], v158
	ds_read_b128 v[150:153], v158 offset:1024
	ds_read_b128 v[154:157], v158 offset:2048
	ds_read_b128 v[158:161], v158 offset:3072
	ds_read_b128 v[162:165], v174
	ds_read_b128 v[166:169], v174 offset:1024
	ds_read_b128 v[170:173], v174 offset:2048
	ds_read_b128 v[174:177], v174 offset:3072
	v_lshl_add_u64 v[208:209], s[48:49], 0, v[140:141]
	s_add_i32 m0, s37, 0xc000
	ds_read_b128 v[178:181], v145
	ds_read_b128 v[182:185], v145 offset:1024
	ds_read_b128 v[186:189], v145 offset:2048
	ds_read_b128 v[190:193], v145 offset:3072
	ds_read_b128 v[194:197], v145 offset:4096
	ds_read_b128 v[204:207], v145 offset:5120
	ds_read_b128 v[220:223], v145 offset:6144
	ds_read_b128 v[224:227], v145 offset:7168
	global_load_lds_dwordx4 v[208:209], off
	v_lshl_add_u64 v[208:209], s[48:49], 0, v[142:143]
	s_add_i32 m0, s37, 0xe000
	s_nop 0
	global_load_lds_dwordx4 v[208:209], off
	s_waitcnt vmcnt(8)
	s_waitcnt lgkmcnt(0)
	s_setprio 1
	s_barrier
	v_mfma_f32_16x16x32_f16 v[128:131], v[146:149], v[178:181], v[128:131]
	v_mfma_f32_16x16x32_f16 v[124:127], v[154:157], v[178:181], v[124:127]
	v_mfma_f32_16x16x32_f16 v[120:123], v[146:149], v[186:189], v[120:123]
	v_mfma_f32_16x16x32_f16 v[116:119], v[154:157], v[186:189], v[116:119]
	v_mfma_f32_16x16x32_f16 v[104:107], v[146:149], v[194:197], v[104:107]
	v_mfma_f32_16x16x32_f16 v[100:103], v[154:157], v[194:197], v[100:103]
	v_mfma_f32_16x16x32_f16 v[88:91], v[146:149], v[220:223], v[88:91]
	v_mfma_f32_16x16x32_f16 v[84:87], v[154:157], v[220:223], v[84:87]
	v_mfma_f32_16x16x32_f16 v[128:131], v[150:153], v[182:185], v[128:131]
	v_mfma_f32_16x16x32_f16 v[124:127], v[158:161], v[182:185], v[124:127]
	v_mfma_f32_16x16x32_f16 v[120:123], v[150:153], v[190:193], v[120:123]
	v_mfma_f32_16x16x32_f16 v[116:119], v[158:161], v[190:193], v[116:119]
	v_mfma_f32_16x16x32_f16 v[104:107], v[150:153], v[204:207], v[104:107]
	v_mfma_f32_16x16x32_f16 v[100:103], v[158:161], v[204:207], v[100:103]
	v_mfma_f32_16x16x32_f16 v[88:91], v[150:153], v[224:227], v[88:91]
	v_mfma_f32_16x16x32_f16 v[84:87], v[158:161], v[224:227], v[84:87]
	v_mfma_f32_16x16x32_f16 v[112:115], v[162:165], v[178:181], v[112:115]
	v_mfma_f32_16x16x32_f16 v[108:111], v[170:173], v[178:181], v[108:111]
	v_mfma_f32_16x16x32_f16 v[96:99], v[162:165], v[186:189], v[96:99]
	v_mfma_f32_16x16x32_f16 v[92:95], v[170:173], v[186:189], v[92:95]
	v_mfma_f32_16x16x32_f16 v[80:83], v[162:165], v[194:197], v[80:83]
	v_mfma_f32_16x16x32_f16 v[76:79], v[170:173], v[194:197], v[76:79]
	v_mfma_f32_16x16x32_f16 v[72:75], v[162:165], v[220:223], v[72:75]
	v_mfma_f32_16x16x32_f16 v[68:71], v[170:173], v[220:223], v[68:71]
	v_mfma_f32_16x16x32_f16 v[112:115], v[166:169], v[182:185], v[112:115]
	v_mfma_f32_16x16x32_f16 v[108:111], v[174:177], v[182:185], v[108:111]
	v_mfma_f32_16x16x32_f16 v[96:99], v[166:169], v[190:193], v[96:99]
	v_mfma_f32_16x16x32_f16 v[92:95], v[174:177], v[190:193], v[92:95]
	v_mfma_f32_16x16x32_f16 v[80:83], v[166:169], v[204:207], v[80:83]
	v_mfma_f32_16x16x32_f16 v[76:79], v[174:177], v[204:207], v[76:79]
	v_mfma_f32_16x16x32_f16 v[72:75], v[166:169], v[224:227], v[72:75]
	v_mfma_f32_16x16x32_f16 v[68:71], v[174:177], v[224:227], v[68:71]
	s_barrier
	s_setprio 0
	s_add_i32 s65, s65, s25
	v_lshl_add_u64 v[208:209], s[16:17], 0, v[2:3]
	s_mov_b32 m0, s65
	ds_read_b128 v[178:181], v145 offset:16384
	ds_read_b128 v[182:185], v145 offset:17408
	ds_read_b128 v[186:189], v145 offset:18432
	ds_read_b128 v[190:193], v145 offset:19456
	ds_read_b128 v[194:197], v145 offset:20480
	ds_read_b128 v[204:207], v145 offset:21504
	ds_read_b128 v[220:223], v145 offset:22528
	ds_read_b128 v[224:227], v145 offset:23552
	global_load_lds_dwordx4 v[208:209], off
	s_add_i32 m0, s65, 0x2000
	s_add_u32 s66, s16, 0x80000
	v_lshl_add_u64 v[228:229], s[16:17], 0, v[132:133]
	s_addc_u32 s67, s17, 0
	s_add_i32 s65, s68, s25
	global_load_lds_dwordx4 v[228:229], off
	v_lshl_add_u64 v[230:231], s[66:67], 0, v[2:3]
	s_mov_b32 m0, s65
	v_lshl_add_u64 v[232:233], s[22:23], 0, v[134:135]
	global_load_lds_dwordx4 v[230:231], off
	v_lshl_add_u64 v[230:231], s[66:67], 0, v[132:133]
	s_add_i32 m0, s65, 0x2000
	s_nop 0
	global_load_lds_dwordx4 v[230:231], off
	v_lshl_add_u64 v[230:231], s[22:23], 0, v[136:137]
	s_mov_b32 m0, s37
	s_nop 0
	global_load_lds_dwordx4 v[230:231], off
	s_mov_b32 m0, s52
	s_nop 0
	global_load_lds_dwordx4 v[232:233], off
	s_waitcnt vmcnt(8)
	s_waitcnt lgkmcnt(0)
	s_setprio 1
	s_barrier
; #define PG8_STAGE(bufoff, gbase, voff) do { _Pragma("unroll") for (int _i = 0; _i < 2; ++_i) \
;         __builtin_amdgcn_global_load_lds((const unsigned*)((const char*)(gbase) + (voff)[_i]), (LAS unsigned*)(lds + (bufoff) + ldsw + _i * 8192), 16, 0, 0); } while (0)
; #define PG8_LDA(dst, b, h) do { _Pragma("unroll") for (int m = 0; m < 4; ++m) _Pragma("unroll") for (int k = 0; k < 2; ++k) dst[m][k] = *(const LAS half8*)(lds + PG8_SA(b, h) + aoff + m * 2048 + k * 1024); } while (0)
; #define PG8_LDB(dst, b, h) do { _Pragma("unroll") for (int n = 0; n < 2; ++n) _Pragma("unroll") for (int k = 0; k < 2; ++k) dst[n][k] = *(const LAS half8*)(lds + PG8_SB(b, h) + boff + n * 2048 + k * 1024); } while (0)
; #define PG8_MMA(ai, bj, At, Bt) do { __builtin_amdgcn_s_setprio(1); _Pragma("unroll") for (int m = 0; m < 4; ++m) _Pragma("unroll") for (int n = 0; n < 2; ++n) _Pragma("unroll") for (int k = 0; k < 2; ++k) \
;         acc[ai][bj][m][n] = __builtin_amdgcn_mfma_f32_16x16x32_f16(Bt[n][k], At[m][k], acc[ai][bj][m][n], 0, 0, 0); __builtin_amdgcn_s_setprio(0); } while (0)
; #define PG8_WAIT_V(n) asm volatile("s_waitcnt vmcnt(" #n ")" ::: "memory")
; template <class Epi, class Sched, bool ALIGN_EPI = false, bool SP2 = false>
; __device__ __forceinline__ void gemm_phase(LAS unsigned char* lds, const Gemm g, const Sched& S, const Epi& E) {
;     ...
;             PG8_LDB(B0, 0, 0); PG8_LDB(B1, 0, 1); PG8_SCHED; PG8_LDA(At, 0, 0); PG8_STAGE(PG8_SA(1, 1), a1 + hstepA, voffA);
;             PG8_WAIT_V(8); PG8_WAIT_L(0); PG8_BAR; PG8_MMA(0, 0, At, B0); PG8_MMA(0, 1, At, B1); PG8_BAR; PG8_SCHED;
;             PG8_LDA(At, 0, 1); PG8_STAGE(PG8_SB(0, 0), b2, voffB); PG8_STAGE(PG8_SB(0, 1), b2 + hstepB, voffB); PG8_STAGE(PG8_SA(0, 0), a2, voffA);
;             PG8_WAIT_V(8); PG8_WAIT_L(0); PG8_BAR; PG8_MMA(1, 0, At, B0); PG8_MMA(1, 1, At, B1); PG8_BAR; PG8_SCHED;
;             PG8_LDB(B0, 1, 0); PG8_LDB(B1, 1, 1); PG8_SCHED; PG8_LDA(At, 1, 0); PG8_STAGE(PG8_SA(0, 1), a2 + hstepA, voffA);
;             PG8_WAIT_V(8); PG8_WAIT_L(0); PG8_BAR; PG8_MMA(0, 0, At, B0); PG8_MMA(0, 1, At, B1); PG8_BAR; PG8_SCHED;
;             PG8_LDA(At, 1, 1); PG8_STAGE(PG8_SB(1, 0), b3, voffB); PG8_STAGE(PG8_SB(1, 1), b3 + hstepB, voffB); PG8_STAGE(PG8_SA(1, 0), a3, voffA);
;             PG8_WAIT_V(8); PG8_WAIT_L(0); PG8_BAR; PG8_MMA(1, 0, At, B0); PG8_MMA(1, 1, At, B1); PG8_BAR; PG8_SCHED;
	v_mfma_f32_16x16x32_f16 v[64:67], v[146:149], v[178:181], v[64:67]
	v_mfma_f32_16x16x32_f16 v[60:63], v[154:157], v[178:181], v[60:63]
	v_mfma_f32_16x16x32_f16 v[56:59], v[146:149], v[186:189], v[56:59]
	v_mfma_f32_16x16x32_f16 v[52:55], v[154:157], v[186:189], v[52:55]
	v_mfma_f32_16x16x32_f16 v[40:43], v[146:149], v[194:197], v[40:43]
	v_mfma_f32_16x16x32_f16 v[36:39], v[154:157], v[194:197], v[36:39]
	v_mfma_f32_16x16x32_f16 v[24:27], v[146:149], v[220:223], v[24:27]
	v_mfma_f32_16x16x32_f16 v[20:23], v[154:157], v[220:223], v[20:23]
	v_mfma_f32_16x16x32_f16 v[64:67], v[150:153], v[182:185], v[64:67]
	v_mfma_f32_16x16x32_f16 v[60:63], v[158:161], v[182:185], v[60:63]
	v_mfma_f32_16x16x32_f16 v[56:59], v[150:153], v[190:193], v[56:59]
	v_mfma_f32_16x16x32_f16 v[52:55], v[158:161], v[190:193], v[52:55]
	v_mfma_f32_16x16x32_f16 v[40:43], v[150:153], v[204:207], v[40:43]
	v_mfma_f32_16x16x32_f16 v[36:39], v[158:161], v[204:207], v[36:39]
	v_mfma_f32_16x16x32_f16 v[24:27], v[150:153], v[224:227], v[24:27]
	v_mfma_f32_16x16x32_f16 v[20:23], v[158:161], v[224:227], v[20:23]
	v_mfma_f32_16x16x32_f16 v[48:51], v[162:165], v[178:181], v[48:51]
	v_mfma_f32_16x16x32_f16 v[44:47], v[170:173], v[178:181], v[44:47]
	v_mfma_f32_16x16x32_f16 v[32:35], v[162:165], v[186:189], v[32:35]
	v_mfma_f32_16x16x32_f16 v[28:31], v[170:173], v[186:189], v[28:31]
	v_mfma_f32_16x16x32_f16 v[16:19], v[162:165], v[194:197], v[16:19]
	v_mfma_f32_16x16x32_f16 v[12:15], v[170:173], v[194:197], v[12:15]
	v_mfma_f32_16x16x32_f16 v[8:11], v[162:165], v[220:223], v[8:11]
	v_mfma_f32_16x16x32_f16 v[4:7], v[170:173], v[220:223], v[4:7]
	v_mfma_f32_16x16x32_f16 v[48:51], v[166:169], v[182:185], v[48:51]
	v_mfma_f32_16x16x32_f16 v[44:47], v[174:177], v[182:185], v[44:47]
	v_mfma_f32_16x16x32_f16 v[32:35], v[166:169], v[190:193], v[32:35]
	v_mfma_f32_16x16x32_f16 v[28:31], v[174:177], v[190:193], v[28:31]
	v_mfma_f32_16x16x32_f16 v[16:19], v[166:169], v[204:207], v[16:19]
	v_mfma_f32_16x16x32_f16 v[12:15], v[174:177], v[204:207], v[12:15]
	v_mfma_f32_16x16x32_f16 v[8:11], v[166:169], v[224:227], v[8:11]
	v_mfma_f32_16x16x32_f16 v[4:7], v[174:177], v[224:227], v[4:7]
	s_barrier
	s_setprio 0
	s_add_i32 s65, 0, 0x18000
	s_add_i32 s66, 0, 0x1c000
	v_add_u32_e32 v158, s65, v144
	v_add_u32_e32 v174, s66, v144
	ds_read_b128 v[146:149], v158
	ds_read_b128 v[150:153], v158 offset:1024
	ds_read_b128 v[154:157], v158 offset:2048
	ds_read_b128 v[158:161], v158 offset:3072
	ds_read_b128 v[162:165], v174
	ds_read_b128 v[166:169], v174 offset:1024
	ds_read_b128 v[170:173], v174 offset:2048
	ds_read_b128 v[174:177], v174 offset:3072
	s_add_u32 s22, s22, 0x80000
	s_addc_u32 s23, s23, 0
	s_mov_b32 m0, s53
	v_lshl_add_u64 v[234:235], s[22:23], 0, v[136:137]
	ds_read_b128 v[178:181], v145 offset:32768
	ds_read_b128 v[182:185], v145 offset:33792
	ds_read_b128 v[186:189], v145 offset:34816
	ds_read_b128 v[190:193], v145 offset:35840
	ds_read_b128 v[194:197], v145 offset:36864
	ds_read_b128 v[204:207], v145 offset:37888
	ds_read_b128 v[220:223], v145 offset:38912
	ds_read_b128 v[224:227], v145 offset:39936
	global_load_lds_dwordx4 v[234:235], off
	v_lshl_add_u64 v[234:235], s[22:23], 0, v[134:135]
	s_mov_b32 m0, s54
	s_nop 0
	global_load_lds_dwordx4 v[234:235], off
	s_waitcnt vmcnt(8)
	s_waitcnt lgkmcnt(0)
	s_setprio 1
	s_barrier
	v_mfma_f32_16x16x32_f16 v[128:131], v[146:149], v[178:181], v[128:131]
	v_mfma_f32_16x16x32_f16 v[124:127], v[154:157], v[178:181], v[124:127]
	v_mfma_f32_16x16x32_f16 v[120:123], v[146:149], v[186:189], v[120:123]
	v_mfma_f32_16x16x32_f16 v[116:119], v[154:157], v[186:189], v[116:119]
	v_mfma_f32_16x16x32_f16 v[104:107], v[146:149], v[194:197], v[104:107]
	v_mfma_f32_16x16x32_f16 v[100:103], v[154:157], v[194:197], v[100:103]
	v_mfma_f32_16x16x32_f16 v[88:91], v[146:149], v[220:223], v[88:91]
	v_mfma_f32_16x16x32_f16 v[84:87], v[154:157], v[220:223], v[84:87]
	v_mfma_f32_16x16x32_f16 v[128:131], v[150:153], v[182:185], v[128:131]
	v_mfma_f32_16x16x32_f16 v[124:127], v[158:161], v[182:185], v[124:127]
	v_mfma_f32_16x16x32_f16 v[120:123], v[150:153], v[190:193], v[120:123]
	v_mfma_f32_16x16x32_f16 v[116:119], v[158:161], v[190:193], v[116:119]
	v_mfma_f32_16x16x32_f16 v[104:107], v[150:153], v[204:207], v[104:107]
	v_mfma_f32_16x16x32_f16 v[100:103], v[158:161], v[204:207], v[100:103]
	v_mfma_f32_16x16x32_f16 v[88:91], v[150:153], v[224:227], v[88:91]
	v_mfma_f32_16x16x32_f16 v[84:87], v[158:161], v[224:227], v[84:87]
	v_mfma_f32_16x16x32_f16 v[112:115], v[162:165], v[178:181], v[112:115]
	v_mfma_f32_16x16x32_f16 v[108:111], v[170:173], v[178:181], v[108:111]
	v_mfma_f32_16x16x32_f16 v[96:99], v[162:165], v[186:189], v[96:99]
	v_mfma_f32_16x16x32_f16 v[92:95], v[170:173], v[186:189], v[92:95]
	v_mfma_f32_16x16x32_f16 v[80:83], v[162:165], v[194:197], v[80:83]
	v_mfma_f32_16x16x32_f16 v[76:79], v[170:173], v[194:197], v[76:79]
	v_mfma_f32_16x16x32_f16 v[72:75], v[162:165], v[220:223], v[72:75]
	v_mfma_f32_16x16x32_f16 v[68:71], v[170:173], v[220:223], v[68:71]
	v_mfma_f32_16x16x32_f16 v[112:115], v[166:169], v[182:185], v[112:115]
	v_mfma_f32_16x16x32_f16 v[108:111], v[174:177], v[182:185], v[108:111]
	v_mfma_f32_16x16x32_f16 v[96:99], v[166:169], v[190:193], v[96:99]
	v_mfma_f32_16x16x32_f16 v[92:95], v[174:177], v[190:193], v[92:95]
	v_mfma_f32_16x16x32_f16 v[80:83], v[166:169], v[204:207], v[80:83]
	v_mfma_f32_16x16x32_f16 v[76:79], v[174:177], v[204:207], v[76:79]
	v_mfma_f32_16x16x32_f16 v[72:75], v[166:169], v[224:227], v[72:75]
	v_mfma_f32_16x16x32_f16 v[68:71], v[174:177], v[224:227], v[68:71]
	s_barrier
; #define PG8_STAGE(bufoff, gbase, voff) do { _Pragma("unroll") for (int _i = 0; _i < 2; ++_i) \
;         __builtin_amdgcn_global_load_lds((const unsigned*)((const char*)(gbase) + (voff)[_i]), (LAS unsigned*)(lds + (bufoff) + ldsw + _i * 8192), 16, 0, 0); } while (0)
; #define PG8_LDA(dst, b, h) do { _Pragma("unroll") for (int m = 0; m < 4; ++m) _Pragma("unroll") for (int k = 0; k < 2; ++k) dst[m][k] = *(const LAS half8*)(lds + PG8_SA(b, h) + aoff + m * 2048 + k * 1024); } while (0)
; #define PG8_LDB(dst, b, h) do { _Pragma("unroll") for (int n = 0; n < 2; ++n) _Pragma("unroll") for (int k = 0; k < 2; ++k) dst[n][k] = *(const LAS half8*)(lds + PG8_SB(b, h) + boff + n * 2048 + k * 1024); } while (0)
; template <class Epi, class Sched, bool ALIGN_EPI = false, bool SP2 = false>
; __device__ __forceinline__ void gemm_phase(LAS unsigned char* lds, const Gemm g, const Sched& S, const Epi& E) {
;     ...
;         for (int t = 0; t < nt; t += 2) {
;             const bool last = (t == nt - 2);
;             const char* a1 = cA + (size_t)(t + 1) * kstep;
;             const char* a2 = last ? nA : cA + (size_t)(t + 2) * kstep; const char* b2 = last ? nB : cB + (size_t)(t + 2) * kstep;
;             const char* a3 = a2 + kstep; const char* b3 = b2 + kstep;
;             if (last && has_next) S.a_ready(nxt);
;             if constexpr (SP2) {
;             PG8_LDB(B0, 0, 0); PG8_LDB(B1, 0, 1); PG8_SCHED; PG8_LDA(At, 0, 0); PG8_STAGE(PG8_SA(1, 1), a1 + hstepA, voffA);
;             PG8_WAIT_V(8); PG8_WAIT_L(0); PG8_BAR; PG8_MMA(0, 0, At, B0); PG8_MMA(0, 1, At, B1); PG8_BAR; PG8_SCHED;
;             PG8_LDA(At, 0, 1); PG8_STAGE(PG8_SB(0, 0), b2, voffB); PG8_STAGE(PG8_SB(0, 1), b2 + hstepB, voffB); PG8_STAGE(PG8_SA(0, 0), a2, voffA);
;             PG8_WAIT_V(8); PG8_WAIT_L(0); PG8_BAR; PG8_MMA(1, 0, At, B0); PG8_MMA(1, 1, At, B1); PG8_BAR; PG8_SCHED;
;             PG8_LDB(B0, 1, 0); PG8_LDB(B1, 1, 1); PG8_SCHED; PG8_LDA(At, 1, 0); PG8_STAGE(PG8_SA(0, 1), a2 + hstepA, voffA);
;             PG8_WAIT_V(8); PG8_WAIT_L(0); PG8_BAR; PG8_MMA(0, 0, At, B0); PG8_MMA(0, 1, At, B1); PG8_BAR; PG8_SCHED;
;             PG8_LDA(At, 1, 1); PG8_STAGE(PG8_SB(1, 0), b3, voffB); PG8_STAGE(PG8_SB(1, 1), b3 + hstepB, voffB); PG8_STAGE(PG8_SA(1, 0), a3, voffA);
;             PG8_WAIT_V(8); PG8_WAIT_L(0); PG8_BAR; PG8_MMA(1, 0, At, B0); PG8_MMA(1, 1, At, B1); PG8_BAR; PG8_SCHED;
	s_setprio 0
	s_add_i32 s22, s65, s25
	v_lshl_add_u64 v[208:209], v[208:209], 0, s[96:97]
	s_mov_b32 m0, s22
	ds_read_b128 v[178:181], v145 offset:49152
	ds_read_b128 v[182:185], v145 offset:50176
	ds_read_b128 v[186:189], v145 offset:51200
	ds_read_b128 v[190:193], v145 offset:52224
	ds_read_b128 v[194:197], v145 offset:53248
	ds_read_b128 v[204:207], v145 offset:54272
	ds_read_b128 v[220:223], v145 offset:55296
	ds_read_b128 v[224:227], v145 offset:56320
	global_load_lds_dwordx4 v[208:209], off
	s_add_i32 m0, s22, 0x2000
	s_add_u32 s16, s16, 0x80080
	v_lshl_add_u64 v[208:209], v[228:229], 0, s[96:97]
	s_addc_u32 s17, s17, 0
	s_add_i32 s22, s66, s25
	global_load_lds_dwordx4 v[208:209], off
	v_lshl_add_u64 v[208:209], s[16:17], 0, v[2:3]
	s_mov_b32 m0, s22
	s_nop 0
	global_load_lds_dwordx4 v[208:209], off
	v_lshl_add_u64 v[208:209], s[16:17], 0, v[132:133]
	s_add_i32 m0, s22, 0x2000
	s_nop 0
	global_load_lds_dwordx4 v[208:209], off
	v_lshl_add_u64 v[208:209], v[230:231], 0, s[96:97]
	s_mov_b32 m0, s55
	s_nop 0
	global_load_lds_dwordx4 v[208:209], off
	v_lshl_add_u64 v[208:209], v[232:233], 0, s[96:97]
	s_mov_b32 m0, s56
	s_nop 0
	global_load_lds_dwordx4 v[208:209], off
	s_waitcnt vmcnt(8)
	s_waitcnt lgkmcnt(0)
	s_setprio 1
	s_barrier
	v_mfma_f32_16x16x32_f16 v[64:67], v[146:149], v[178:181], v[64:67]
	v_mfma_f32_16x16x32_f16 v[60:63], v[154:157], v[178:181], v[60:63]
	v_mfma_f32_16x16x32_f16 v[56:59], v[146:149], v[186:189], v[56:59]
	v_mfma_f32_16x16x32_f16 v[52:55], v[154:157], v[186:189], v[52:55]
	v_mfma_f32_16x16x32_f16 v[40:43], v[146:149], v[194:197], v[40:43]
	v_mfma_f32_16x16x32_f16 v[36:39], v[154:157], v[194:197], v[36:39]
	v_mfma_f32_16x16x32_f16 v[24:27], v[146:149], v[220:223], v[24:27]
	v_mfma_f32_16x16x32_f16 v[20:23], v[154:157], v[220:223], v[20:23]
	v_mfma_f32_16x16x32_f16 v[64:67], v[150:153], v[182:185], v[64:67]
	v_mfma_f32_16x16x32_f16 v[60:63], v[158:161], v[182:185], v[60:63]
	v_mfma_f32_16x16x32_f16 v[56:59], v[150:153], v[190:193], v[56:59]
	v_mfma_f32_16x16x32_f16 v[52:55], v[158:161], v[190:193], v[52:55]
	v_mfma_f32_16x16x32_f16 v[40:43], v[150:153], v[204:207], v[40:43]
	v_mfma_f32_16x16x32_f16 v[36:39], v[158:161], v[204:207], v[36:39]
	v_mfma_f32_16x16x32_f16 v[24:27], v[150:153], v[224:227], v[24:27]
	v_mfma_f32_16x16x32_f16 v[20:23], v[158:161], v[224:227], v[20:23]
	v_mfma_f32_16x16x32_f16 v[48:51], v[162:165], v[178:181], v[48:51]
	v_mfma_f32_16x16x32_f16 v[44:47], v[170:173], v[178:181], v[44:47]
	v_mfma_f32_16x16x32_f16 v[32:35], v[162:165], v[186:189], v[32:35]
	v_mfma_f32_16x16x32_f16 v[28:31], v[170:173], v[186:189], v[28:31]
	v_mfma_f32_16x16x32_f16 v[16:19], v[162:165], v[194:197], v[16:19]
	v_mfma_f32_16x16x32_f16 v[12:15], v[170:173], v[194:197], v[12:15]
	v_mfma_f32_16x16x32_f16 v[8:11], v[162:165], v[220:223], v[8:11]
	v_mfma_f32_16x16x32_f16 v[4:7], v[170:173], v[220:223], v[4:7]
	v_mfma_f32_16x16x32_f16 v[48:51], v[166:169], v[182:185], v[48:51]
	v_mfma_f32_16x16x32_f16 v[44:47], v[174:177], v[182:185], v[44:47]
	v_mfma_f32_16x16x32_f16 v[32:35], v[166:169], v[190:193], v[32:35]
	v_mfma_f32_16x16x32_f16 v[28:31], v[174:177], v[190:193], v[28:31]
	v_mfma_f32_16x16x32_f16 v[16:19], v[166:169], v[204:207], v[16:19]
	v_mfma_f32_16x16x32_f16 v[12:15], v[174:177], v[204:207], v[12:15]
	v_mfma_f32_16x16x32_f16 v[8:11], v[166:169], v[224:227], v[8:11]
	v_mfma_f32_16x16x32_f16 v[4:7], v[174:177], v[224:227], v[4:7]
	s_barrier
	s_setprio 0
	s_add_i32 s64, s64, 2
	s_add_u32 s48, s48, 0x100
	s_addc_u32 s49, s49, 0
	s_add_u32 s62, s62, 0x100
	s_addc_u32 s63, s63, 0
	s_cmp_gt_u32 s64, 29
	s_cbranch_scc0 .LBB0_415
	s_and_b64 vcc, exec, s[6:7]
	s_cbranch_vccz .LBB0_418
	s_barrier

; #define PG8_STAGE(bufoff, gbase, voff) do { _Pragma("unroll") for (int _i = 0; _i < 2; ++_i) \
;         __builtin_amdgcn_global_load_lds((const unsigned*)((const char*)(gbase) + (voff)[_i]), (LAS unsigned*)(lds + (bufoff) + ldsw + _i * 8192), 16, 0, 0); } while (0)
; #define PG8_LDA(dst, b, h) do { _Pragma("unroll") for (int m = 0; m < 4; ++m) _Pragma("unroll") for (int k = 0; k < 2; ++k) dst[m][k] = *(const LAS half8*)(lds + PG8_SA(b, h) + aoff + m * 2048 + k * 1024); } while (0)
; #define PG8_LDB(dst, b, h) do { _Pragma("unroll") for (int n = 0; n < 2; ++n) _Pragma("unroll") for (int k = 0; k < 2; ++k) dst[n][k] = *(const LAS half8*)(lds + PG8_SB(b, h) + boff + n * 2048 + k * 1024); } while (0)
; #define PG8_MMA(ai, bj, At, Bt) do { __builtin_amdgcn_s_setprio(1); _Pragma("unroll") for (int m = 0; m < 4; ++m) _Pragma("unroll") for (int n = 0; n < 2; ++n) _Pragma("unroll") for (int k = 0; k < 2; ++k) \
;         acc[ai][bj][m][n] = __builtin_amdgcn_mfma_f32_16x16x32_f16(Bt[n][k], At[m][k], acc[ai][bj][m][n], 0, 0, 0); __builtin_amdgcn_s_setprio(0); } while (0)
; #define PG8_WAIT_V(n) asm volatile("s_waitcnt vmcnt(" #n ")" ::: "memory")
; template <class Epi, class Sched, bool ALIGN_EPI = false, bool SP2 = false>
; __device__ __forceinline__ void gemm_phase(LAS unsigned char* lds, const Gemm g, const Sched& S, const Epi& E) {
;     ...
;             PG8_LDB(B0, 0, 0); PG8_LDB(B1, 0, 1); PG8_SCHED; PG8_LDA(At, 0, 0); PG8_STAGE(PG8_SA(1, 1), a1 + hstepA, voffA);
;             PG8_WAIT_V(8); PG8_WAIT_L(0); PG8_BAR; PG8_MMA(0, 0, At, B0); PG8_MMA(0, 1, At, B1); PG8_BAR; PG8_SCHED;
;             PG8_LDA(At, 0, 1); PG8_STAGE(PG8_SB(0, 0), b2, voffB); PG8_STAGE(PG8_SB(0, 1), b2 + hstepB, voffB); PG8_STAGE(PG8_SA(0, 0), a2, voffA);
;             PG8_WAIT_V(8); PG8_WAIT_L(0); PG8_BAR; PG8_MMA(1, 0, At, B0); PG8_MMA(1, 1, At, B1); PG8_BAR; PG8_SCHED;
;             PG8_LDB(B0, 1, 0); PG8_LDB(B1, 1, 1); PG8_SCHED; PG8_LDA(At, 1, 0); PG8_STAGE(PG8_SA(0, 1), a2 + hstepA, voffA);
;             PG8_WAIT_V(8); PG8_WAIT_L(0); PG8_BAR; PG8_MMA(0, 0, At, B0); PG8_MMA(0, 1, At, B1); PG8_BAR; PG8_SCHED;
;             PG8_LDA(At, 1, 1); PG8_STAGE(PG8_SB(1, 0), b3, voffB); PG8_STAGE(PG8_SB(1, 1), b3 + hstepB, voffB); PG8_STAGE(PG8_SA(1, 0), a3, voffA);
;             PG8_WAIT_V(8); PG8_WAIT_L(0); PG8_BAR; PG8_MMA(1, 0, At, B0); PG8_MMA(1, 1, At, B1); PG8_BAR; PG8_SCHED;
.LBB0_426:
	s_add_u32 s8, s6, 0x3c000100
	s_addc_u32 s9, s7, 0
	s_add_u32 s44, s6, s22
	s_addc_u32 s45, s7, s23
	s_add_i32 s48, 0, 0x10000
	s_cmp_eq_u32 s37, 28
	s_cselect_b32 s11, s53, s9
	s_cselect_b32 s10, s52, s8
	v_add_u32_e32 v145, s48, v133
	s_cselect_b32 s9, s1, s45
	s_cselect_b32 s8, s0, s44
	s_add_i32 s49, 0, 0x14000
	ds_read_b128 v[146:149], v145
	ds_read_b128 v[150:153], v145 offset:1024
	ds_read_b128 v[154:157], v145 offset:2048
	ds_read_b128 v[158:161], v145 offset:3072
	v_add_u32_e32 v145, s49, v133
	ds_read_b128 v[162:165], v145
	ds_read_b128 v[166:169], v145 offset:1024
	ds_read_b128 v[170:173], v145 offset:2048
	ds_read_b128 v[174:177], v145 offset:3072
	v_lshl_add_u64 v[208:209], s[6:7], 0, v[140:141]
	s_add_i32 m0, s14, 0xc000
	ds_read_b128 v[178:181], v144
	ds_read_b128 v[182:185], v144 offset:1024
	ds_read_b128 v[186:189], v144 offset:2048
	ds_read_b128 v[190:193], v144 offset:3072
	ds_read_b128 v[194:197], v144 offset:4096
	ds_read_b128 v[204:207], v144 offset:5120
	ds_read_b128 v[220:223], v144 offset:6144
	ds_read_b128 v[224:227], v144 offset:7168
	global_load_lds_dwordx4 v[208:209], off
	v_lshl_add_u64 v[208:209], s[6:7], 0, v[142:143]
	s_add_i32 m0, s14, 0xe000
	s_nop 0
	global_load_lds_dwordx4 v[208:209], off
	s_waitcnt vmcnt(8)
	s_waitcnt lgkmcnt(0)
	s_setprio 1
	s_barrier
	v_mfma_f32_16x16x32_f16 v[128:131], v[146:149], v[178:181], v[128:131]
	v_mfma_f32_16x16x32_f16 v[124:127], v[154:157], v[178:181], v[124:127]
	v_mfma_f32_16x16x32_f16 v[120:123], v[146:149], v[186:189], v[120:123]
	v_mfma_f32_16x16x32_f16 v[116:119], v[154:157], v[186:189], v[116:119]
	v_mfma_f32_16x16x32_f16 v[104:107], v[146:149], v[194:197], v[104:107]
	v_mfma_f32_16x16x32_f16 v[100:103], v[154:157], v[194:197], v[100:103]
	v_mfma_f32_16x16x32_f16 v[88:91], v[146:149], v[220:223], v[88:91]
	v_mfma_f32_16x16x32_f16 v[84:87], v[154:157], v[220:223], v[84:87]
	v_mfma_f32_16x16x32_f16 v[128:131], v[150:153], v[182:185], v[128:131]
	v_mfma_f32_16x16x32_f16 v[124:127], v[158:161], v[182:185], v[124:127]
	v_mfma_f32_16x16x32_f16 v[120:123], v[150:153], v[190:193], v[120:123]
	v_mfma_f32_16x16x32_f16 v[116:119], v[158:161], v[190:193], v[116:119]
	v_mfma_f32_16x16x32_f16 v[104:107], v[150:153], v[204:207], v[104:107]
	v_mfma_f32_16x16x32_f16 v[100:103], v[158:161], v[204:207], v[100:103]
	v_mfma_f32_16x16x32_f16 v[88:91], v[150:153], v[224:227], v[88:91]
	v_mfma_f32_16x16x32_f16 v[84:87], v[158:161], v[224:227], v[84:87]
	v_mfma_f32_16x16x32_f16 v[112:115], v[162:165], v[178:181], v[112:115]
	v_mfma_f32_16x16x32_f16 v[108:111], v[170:173], v[178:181], v[108:111]
	v_mfma_f32_16x16x32_f16 v[96:99], v[162:165], v[186:189], v[96:99]
	v_mfma_f32_16x16x32_f16 v[92:95], v[170:173], v[186:189], v[92:95]
	v_mfma_f32_16x16x32_f16 v[80:83], v[162:165], v[194:197], v[80:83]
	v_mfma_f32_16x16x32_f16 v[76:79], v[170:173], v[194:197], v[76:79]
	v_mfma_f32_16x16x32_f16 v[72:75], v[162:165], v[220:223], v[72:75]
	v_mfma_f32_16x16x32_f16 v[68:71], v[170:173], v[220:223], v[68:71]
	v_mfma_f32_16x16x32_f16 v[112:115], v[166:169], v[182:185], v[112:115]
	v_mfma_f32_16x16x32_f16 v[108:111], v[174:177], v[182:185], v[108:111]
	v_mfma_f32_16x16x32_f16 v[96:99], v[166:169], v[190:193], v[96:99]
	v_mfma_f32_16x16x32_f16 v[92:95], v[174:177], v[190:193], v[92:95]
	v_mfma_f32_16x16x32_f16 v[80:83], v[166:169], v[204:207], v[80:83]
	v_mfma_f32_16x16x32_f16 v[76:79], v[174:177], v[204:207], v[76:79]
	v_mfma_f32_16x16x32_f16 v[72:75], v[166:169], v[224:227], v[72:75]
	v_mfma_f32_16x16x32_f16 v[68:71], v[174:177], v[224:227], v[68:71]
	s_barrier
	s_setprio 0
	s_add_i32 s44, s48, s13
	v_lshl_add_u64 v[208:209], s[8:9], 0, v[2:3]
	s_mov_b32 m0, s44
	ds_read_b128 v[178:181], v144 offset:16384
	ds_read_b128 v[182:185], v144 offset:17408
	ds_read_b128 v[186:189], v144 offset:18432
	ds_read_b128 v[190:193], v144 offset:19456
	ds_read_b128 v[194:197], v144 offset:20480
	ds_read_b128 v[204:207], v144 offset:21504
	ds_read_b128 v[220:223], v144 offset:22528
	ds_read_b128 v[224:227], v144 offset:23552
	global_load_lds_dwordx4 v[208:209], off
	s_add_i32 m0, s44, 0x2000
	s_add_u32 s44, s8, 0x80000
	v_lshl_add_u64 v[228:229], s[8:9], 0, v[134:135]
	s_addc_u32 s45, s9, 0
	s_add_i32 s48, s49, s13
	global_load_lds_dwordx4 v[228:229], off
	v_lshl_add_u64 v[230:231], s[44:45], 0, v[2:3]
	s_mov_b32 m0, s48
	v_lshl_add_u64 v[232:233], s[10:11], 0, v[136:137]
	global_load_lds_dwordx4 v[230:231], off
	v_lshl_add_u64 v[230:231], s[44:45], 0, v[134:135]
	s_add_i32 m0, s48, 0x2000
	s_nop 0
	global_load_lds_dwordx4 v[230:231], off
	v_lshl_add_u64 v[230:231], s[10:11], 0, v[138:139]
	s_mov_b32 m0, s14
	s_nop 0
	global_load_lds_dwordx4 v[230:231], off
	s_mov_b32 m0, s15
	s_nop 0
	global_load_lds_dwordx4 v[232:233], off
	s_waitcnt vmcnt(8)
	s_waitcnt lgkmcnt(0)
	s_setprio 1
	s_barrier
; #define PG8_STAGE(bufoff, gbase, voff) do { _Pragma("unroll") for (int _i = 0; _i < 2; ++_i) \
;         __builtin_amdgcn_global_load_lds((const unsigned*)((const char*)(gbase) + (voff)[_i]), (LAS unsigned*)(lds + (bufoff) + ldsw + _i * 8192), 16, 0, 0); } while (0)
; #define PG8_LDA(dst, b, h) do { _Pragma("unroll") for (int m = 0; m < 4; ++m) _Pragma("unroll") for (int k = 0; k < 2; ++k) dst[m][k] = *(const LAS half8*)(lds + PG8_SA(b, h) + aoff + m * 2048 + k * 1024); } while (0)
; #define PG8_LDB(dst, b, h) do { _Pragma("unroll") for (int n = 0; n < 2; ++n) _Pragma("unroll") for (int k = 0; k < 2; ++k) dst[n][k] = *(const LAS half8*)(lds + PG8_SB(b, h) + boff + n * 2048 + k * 1024); } while (0)
; #define PG8_MMA(ai, bj, At, Bt) do { __builtin_amdgcn_s_setprio(1); _Pragma("unroll") for (int m = 0; m < 4; ++m) _Pragma("unroll") for (int n = 0; n < 2; ++n) _Pragma("unroll") for (int k = 0; k < 2; ++k) \
;         acc[ai][bj][m][n] = __builtin_amdgcn_mfma_f32_16x16x32_f16(Bt[n][k], At[m][k], acc[ai][bj][m][n], 0, 0, 0); __builtin_amdgcn_s_setprio(0); } while (0)
; #define PG8_WAIT_V(n) asm volatile("s_waitcnt vmcnt(" #n ")" ::: "memory")
; template <class Epi, class Sched, bool ALIGN_EPI = false, bool SP2 = false>
; __device__ __forceinline__ void gemm_phase(LAS unsigned char* lds, const Gemm g, const Sched& S, const Epi& E) {
;     ...
;             PG8_LDB(B0, 0, 0); PG8_LDB(B1, 0, 1); PG8_SCHED; PG8_LDA(At, 0, 0); PG8_STAGE(PG8_SA(1, 1), a1 + hstepA, voffA);
;             PG8_WAIT_V(8); PG8_WAIT_L(0); PG8_BAR; PG8_MMA(0, 0, At, B0); PG8_MMA(0, 1, At, B1); PG8_BAR; PG8_SCHED;
;             PG8_LDA(At, 0, 1); PG8_STAGE(PG8_SB(0, 0), b2, voffB); PG8_STAGE(PG8_SB(0, 1), b2 + hstepB, voffB); PG8_STAGE(PG8_SA(0, 0), a2, voffA);
;             PG8_WAIT_V(8); PG8_WAIT_L(0); PG8_BAR; PG8_MMA(1, 0, At, B0); PG8_MMA(1, 1, At, B1); PG8_BAR; PG8_SCHED;
;             PG8_LDB(B0, 1, 0); PG8_LDB(B1, 1, 1); PG8_SCHED; PG8_LDA(At, 1, 0); PG8_STAGE(PG8_SA(0, 1), a2 + hstepA, voffA);
;             PG8_WAIT_V(8); PG8_WAIT_L(0); PG8_BAR; PG8_MMA(0, 0, At, B0); PG8_MMA(0, 1, At, B1); PG8_BAR; PG8_SCHED;
;             PG8_LDA(At, 1, 1); PG8_STAGE(PG8_SB(1, 0), b3, voffB); PG8_STAGE(PG8_SB(1, 1), b3 + hstepB, voffB); PG8_STAGE(PG8_SA(1, 0), a3, voffA);
;             PG8_WAIT_V(8); PG8_WAIT_L(0); PG8_BAR; PG8_MMA(1, 0, At, B0); PG8_MMA(1, 1, At, B1); PG8_BAR; PG8_SCHED;
	v_mfma_f32_16x16x32_f16 v[64:67], v[146:149], v[178:181], v[64:67]
	v_mfma_f32_16x16x32_f16 v[60:63], v[154:157], v[178:181], v[60:63]
	v_mfma_f32_16x16x32_f16 v[56:59], v[146:149], v[186:189], v[56:59]
	v_mfma_f32_16x16x32_f16 v[52:55], v[154:157], v[186:189], v[52:55]
	v_mfma_f32_16x16x32_f16 v[40:43], v[146:149], v[194:197], v[40:43]
	v_mfma_f32_16x16x32_f16 v[36:39], v[154:157], v[194:197], v[36:39]
	v_mfma_f32_16x16x32_f16 v[24:27], v[146:149], v[220:223], v[24:27]
	v_mfma_f32_16x16x32_f16 v[20:23], v[154:157], v[220:223], v[20:23]
	v_mfma_f32_16x16x32_f16 v[64:67], v[150:153], v[182:185], v[64:67]
	v_mfma_f32_16x16x32_f16 v[60:63], v[158:161], v[182:185], v[60:63]
	v_mfma_f32_16x16x32_f16 v[56:59], v[150:153], v[190:193], v[56:59]
	v_mfma_f32_16x16x32_f16 v[52:55], v[158:161], v[190:193], v[52:55]
	v_mfma_f32_16x16x32_f16 v[40:43], v[150:153], v[204:207], v[40:43]
	v_mfma_f32_16x16x32_f16 v[36:39], v[158:161], v[204:207], v[36:39]
	v_mfma_f32_16x16x32_f16 v[24:27], v[150:153], v[224:227], v[24:27]
	v_mfma_f32_16x16x32_f16 v[20:23], v[158:161], v[224:227], v[20:23]
	v_mfma_f32_16x16x32_f16 v[48:51], v[162:165], v[178:181], v[48:51]
	v_mfma_f32_16x16x32_f16 v[44:47], v[170:173], v[178:181], v[44:47]
	v_mfma_f32_16x16x32_f16 v[32:35], v[162:165], v[186:189], v[32:35]
	v_mfma_f32_16x16x32_f16 v[28:31], v[170:173], v[186:189], v[28:31]
	v_mfma_f32_16x16x32_f16 v[16:19], v[162:165], v[194:197], v[16:19]
	v_mfma_f32_16x16x32_f16 v[12:15], v[170:173], v[194:197], v[12:15]
	v_mfma_f32_16x16x32_f16 v[8:11], v[162:165], v[220:223], v[8:11]
	v_mfma_f32_16x16x32_f16 v[4:7], v[170:173], v[220:223], v[4:7]
	v_mfma_f32_16x16x32_f16 v[48:51], v[166:169], v[182:185], v[48:51]
	v_mfma_f32_16x16x32_f16 v[44:47], v[174:177], v[182:185], v[44:47]
	v_mfma_f32_16x16x32_f16 v[32:35], v[166:169], v[190:193], v[32:35]
	v_mfma_f32_16x16x32_f16 v[28:31], v[174:177], v[190:193], v[28:31]
	v_mfma_f32_16x16x32_f16 v[16:19], v[166:169], v[204:207], v[16:19]
	v_mfma_f32_16x16x32_f16 v[12:15], v[174:177], v[204:207], v[12:15]
	v_mfma_f32_16x16x32_f16 v[8:11], v[166:169], v[224:227], v[8:11]
	v_mfma_f32_16x16x32_f16 v[4:7], v[174:177], v[224:227], v[4:7]
	s_barrier
	s_setprio 0
	s_add_i32 s44, 0, 0x18000
	v_add_u32_e32 v145, s44, v133
	s_add_i32 s45, 0, 0x1c000
	ds_read_b128 v[146:149], v145
	ds_read_b128 v[150:153], v145 offset:1024
	ds_read_b128 v[154:157], v145 offset:2048
	ds_read_b128 v[158:161], v145 offset:3072
	v_add_u32_e32 v145, s45, v133
	ds_read_b128 v[162:165], v145
	ds_read_b128 v[166:169], v145 offset:1024
	ds_read_b128 v[170:173], v145 offset:2048
	ds_read_b128 v[174:177], v145 offset:3072
	s_add_u32 s10, s10, 0x80000
	s_addc_u32 s11, s11, 0
	s_mov_b32 m0, s16
	v_lshl_add_u64 v[234:235], s[10:11], 0, v[138:139]
	ds_read_b128 v[178:181], v144 offset:32768
	ds_read_b128 v[182:185], v144 offset:33792
	ds_read_b128 v[186:189], v144 offset:34816
	ds_read_b128 v[190:193], v144 offset:35840
	ds_read_b128 v[194:197], v144 offset:36864
	ds_read_b128 v[204:207], v144 offset:37888
	ds_read_b128 v[220:223], v144 offset:38912
	ds_read_b128 v[224:227], v144 offset:39936
	global_load_lds_dwordx4 v[234:235], off
	v_lshl_add_u64 v[234:235], s[10:11], 0, v[136:137]
	s_mov_b32 m0, s17
	s_nop 0
	global_load_lds_dwordx4 v[234:235], off
	s_waitcnt vmcnt(8)
	s_waitcnt lgkmcnt(0)
	s_setprio 1
	s_barrier
	v_mfma_f32_16x16x32_f16 v[128:131], v[146:149], v[178:181], v[128:131]
	v_mfma_f32_16x16x32_f16 v[124:127], v[154:157], v[178:181], v[124:127]
	v_mfma_f32_16x16x32_f16 v[120:123], v[146:149], v[186:189], v[120:123]
	v_mfma_f32_16x16x32_f16 v[116:119], v[154:157], v[186:189], v[116:119]
	v_mfma_f32_16x16x32_f16 v[104:107], v[146:149], v[194:197], v[104:107]
	v_mfma_f32_16x16x32_f16 v[100:103], v[154:157], v[194:197], v[100:103]
	v_mfma_f32_16x16x32_f16 v[88:91], v[146:149], v[220:223], v[88:91]
	v_mfma_f32_16x16x32_f16 v[84:87], v[154:157], v[220:223], v[84:87]
	v_mfma_f32_16x16x32_f16 v[128:131], v[150:153], v[182:185], v[128:131]
	v_mfma_f32_16x16x32_f16 v[124:127], v[158:161], v[182:185], v[124:127]
	v_mfma_f32_16x16x32_f16 v[120:123], v[150:153], v[190:193], v[120:123]
	v_mfma_f32_16x16x32_f16 v[116:119], v[158:161], v[190:193], v[116:119]
	v_mfma_f32_16x16x32_f16 v[104:107], v[150:153], v[204:207], v[104:107]
	v_mfma_f32_16x16x32_f16 v[100:103], v[158:161], v[204:207], v[100:103]
	v_mfma_f32_16x16x32_f16 v[88:91], v[150:153], v[224:227], v[88:91]
	v_mfma_f32_16x16x32_f16 v[84:87], v[158:161], v[224:227], v[84:87]
	v_mfma_f32_16x16x32_f16 v[112:115], v[162:165], v[178:181], v[112:115]
	v_mfma_f32_16x16x32_f16 v[108:111], v[170:173], v[178:181], v[108:111]
	v_mfma_f32_16x16x32_f16 v[96:99], v[162:165], v[186:189], v[96:99]
	v_mfma_f32_16x16x32_f16 v[92:95], v[170:173], v[186:189], v[92:95]
	v_mfma_f32_16x16x32_f16 v[80:83], v[162:165], v[194:197], v[80:83]
	v_mfma_f32_16x16x32_f16 v[76:79], v[170:173], v[194:197], v[76:79]
	v_mfma_f32_16x16x32_f16 v[72:75], v[162:165], v[220:223], v[72:75]
	v_mfma_f32_16x16x32_f16 v[68:71], v[170:173], v[220:223], v[68:71]
	v_mfma_f32_16x16x32_f16 v[112:115], v[166:169], v[182:185], v[112:115]
	v_mfma_f32_16x16x32_f16 v[108:111], v[174:177], v[182:185], v[108:111]
	v_mfma_f32_16x16x32_f16 v[96:99], v[166:169], v[190:193], v[96:99]
	v_mfma_f32_16x16x32_f16 v[92:95], v[174:177], v[190:193], v[92:95]
	v_mfma_f32_16x16x32_f16 v[80:83], v[166:169], v[204:207], v[80:83]
	v_mfma_f32_16x16x32_f16 v[76:79], v[174:177], v[204:207], v[76:79]
	v_mfma_f32_16x16x32_f16 v[72:75], v[166:169], v[224:227], v[72:75]
	v_mfma_f32_16x16x32_f16 v[68:71], v[174:177], v[224:227], v[68:71]
	s_barrier
; #define PG8_STAGE(bufoff, gbase, voff) do { _Pragma("unroll") for (int _i = 0; _i < 2; ++_i) \
;         __builtin_amdgcn_global_load_lds((const unsigned*)((const char*)(gbase) + (voff)[_i]), (LAS unsigned*)(lds + (bufoff) + ldsw + _i * 8192), 16, 0, 0); } while (0)
; #define PG8_LDA(dst, b, h) do { _Pragma("unroll") for (int m = 0; m < 4; ++m) _Pragma("unroll") for (int k = 0; k < 2; ++k) dst[m][k] = *(const LAS half8*)(lds + PG8_SA(b, h) + aoff + m * 2048 + k * 1024); } while (0)
; #define PG8_LDB(dst, b, h) do { _Pragma("unroll") for (int n = 0; n < 2; ++n) _Pragma("unroll") for (int k = 0; k < 2; ++k) dst[n][k] = *(const LAS half8*)(lds + PG8_SB(b, h) + boff + n * 2048 + k * 1024); } while (0)
; template <class Epi, class Sched, bool ALIGN_EPI = false, bool SP2 = false>
; __device__ __forceinline__ void gemm_phase(LAS unsigned char* lds, const Gemm g, const Sched& S, const Epi& E) {
;     ...
;         for (int t = 0; t < nt; t += 2) {
;             const bool last = (t == nt - 2);
;             const char* a1 = cA + (size_t)(t + 1) * kstep;
;             const char* a2 = last ? nA : cA + (size_t)(t + 2) * kstep; const char* b2 = last ? nB : cB + (size_t)(t + 2) * kstep;
;             const char* a3 = a2 + kstep; const char* b3 = b2 + kstep;
;             if (last && has_next) S.a_ready(nxt);
;             if constexpr (SP2) {
;             PG8_LDB(B0, 0, 0); PG8_LDB(B1, 0, 1); PG8_SCHED; PG8_LDA(At, 0, 0); PG8_STAGE(PG8_SA(1, 1), a1 + hstepA, voffA);
;             PG8_WAIT_V(8); PG8_WAIT_L(0); PG8_BAR; PG8_MMA(0, 0, At, B0); PG8_MMA(0, 1, At, B1); PG8_BAR; PG8_SCHED;
;             PG8_LDA(At, 0, 1); PG8_STAGE(PG8_SB(0, 0), b2, voffB); PG8_STAGE(PG8_SB(0, 1), b2 + hstepB, voffB); PG8_STAGE(PG8_SA(0, 0), a2, voffA);
;             PG8_WAIT_V(8); PG8_WAIT_L(0); PG8_BAR; PG8_MMA(1, 0, At, B0); PG8_MMA(1, 1, At, B1); PG8_BAR; PG8_SCHED;
;             PG8_LDB(B0, 1, 0); PG8_LDB(B1, 1, 1); PG8_SCHED; PG8_LDA(At, 1, 0); PG8_STAGE(PG8_SA(0, 1), a2 + hstepA, voffA);
;             PG8_WAIT_V(8); PG8_WAIT_L(0); PG8_BAR; PG8_MMA(0, 0, At, B0); PG8_MMA(0, 1, At, B1); PG8_BAR; PG8_SCHED;
;             PG8_LDA(At, 1, 1); PG8_STAGE(PG8_SB(1, 0), b3, voffB); PG8_STAGE(PG8_SB(1, 1), b3 + hstepB, voffB); PG8_STAGE(PG8_SA(1, 0), a3, voffA);
;             PG8_WAIT_V(8); PG8_WAIT_L(0); PG8_BAR; PG8_MMA(1, 0, At, B0); PG8_MMA(1, 1, At, B1); PG8_BAR; PG8_SCHED;
	s_setprio 0
	s_add_i32 s10, s44, s13
	v_lshl_add_u64 v[208:209], v[208:209], 0, s[96:97]
	s_mov_b32 m0, s10
	ds_read_b128 v[178:181], v144 offset:49152
	ds_read_b128 v[182:185], v144 offset:50176
	ds_read_b128 v[186:189], v144 offset:51200
	ds_read_b128 v[190:193], v144 offset:52224
	ds_read_b128 v[194:197], v144 offset:53248
	ds_read_b128 v[204:207], v144 offset:54272
	ds_read_b128 v[220:223], v144 offset:55296
	ds_read_b128 v[224:227], v144 offset:56320
	global_load_lds_dwordx4 v[208:209], off
	s_add_i32 m0, s10, 0x2000
	s_add_u32 s8, s8, 0x80080
	v_lshl_add_u64 v[208:209], v[228:229], 0, s[96:97]
	s_addc_u32 s9, s9, 0
	s_add_i32 s10, s45, s13
	global_load_lds_dwordx4 v[208:209], off
	v_lshl_add_u64 v[208:209], s[8:9], 0, v[2:3]
	s_mov_b32 m0, s10
	s_nop 0
	global_load_lds_dwordx4 v[208:209], off
	v_lshl_add_u64 v[208:209], s[8:9], 0, v[134:135]
	s_add_i32 m0, s10, 0x2000
	s_nop 0
	global_load_lds_dwordx4 v[208:209], off
	v_lshl_add_u64 v[208:209], v[230:231], 0, s[96:97]
	s_mov_b32 m0, s24
	s_nop 0
	global_load_lds_dwordx4 v[208:209], off
	v_lshl_add_u64 v[208:209], v[232:233], 0, s[96:97]
	s_mov_b32 m0, s25
	s_nop 0
	global_load_lds_dwordx4 v[208:209], off
	s_waitcnt vmcnt(8)
	s_waitcnt lgkmcnt(0)
	s_setprio 1
	s_barrier
	v_mfma_f32_16x16x32_f16 v[64:67], v[146:149], v[178:181], v[64:67]
	v_mfma_f32_16x16x32_f16 v[60:63], v[154:157], v[178:181], v[60:63]
	v_mfma_f32_16x16x32_f16 v[56:59], v[146:149], v[186:189], v[56:59]
	v_mfma_f32_16x16x32_f16 v[52:55], v[154:157], v[186:189], v[52:55]
	v_mfma_f32_16x16x32_f16 v[40:43], v[146:149], v[194:197], v[40:43]
	v_mfma_f32_16x16x32_f16 v[36:39], v[154:157], v[194:197], v[36:39]
	v_mfma_f32_16x16x32_f16 v[24:27], v[146:149], v[220:223], v[24:27]
	v_mfma_f32_16x16x32_f16 v[20:23], v[154:157], v[220:223], v[20:23]
	v_mfma_f32_16x16x32_f16 v[64:67], v[150:153], v[182:185], v[64:67]
	v_mfma_f32_16x16x32_f16 v[60:63], v[158:161], v[182:185], v[60:63]
	v_mfma_f32_16x16x32_f16 v[56:59], v[150:153], v[190:193], v[56:59]
	v_mfma_f32_16x16x32_f16 v[52:55], v[158:161], v[190:193], v[52:55]
	v_mfma_f32_16x16x32_f16 v[40:43], v[150:153], v[204:207], v[40:43]
	v_mfma_f32_16x16x32_f16 v[36:39], v[158:161], v[204:207], v[36:39]
	v_mfma_f32_16x16x32_f16 v[24:27], v[150:153], v[224:227], v[24:27]
	v_mfma_f32_16x16x32_f16 v[20:23], v[158:161], v[224:227], v[20:23]
	v_mfma_f32_16x16x32_f16 v[48:51], v[162:165], v[178:181], v[48:51]
	v_mfma_f32_16x16x32_f16 v[44:47], v[170:173], v[178:181], v[44:47]
	v_mfma_f32_16x16x32_f16 v[32:35], v[162:165], v[186:189], v[32:35]
	v_mfma_f32_16x16x32_f16 v[28:31], v[170:173], v[186:189], v[28:31]
	v_mfma_f32_16x16x32_f16 v[16:19], v[162:165], v[194:197], v[16:19]
	v_mfma_f32_16x16x32_f16 v[12:15], v[170:173], v[194:197], v[12:15]
	v_mfma_f32_16x16x32_f16 v[8:11], v[162:165], v[220:223], v[8:11]
	v_mfma_f32_16x16x32_f16 v[4:7], v[170:173], v[220:223], v[4:7]
	v_mfma_f32_16x16x32_f16 v[48:51], v[166:169], v[182:185], v[48:51]
	v_mfma_f32_16x16x32_f16 v[44:47], v[174:177], v[182:185], v[44:47]
	v_mfma_f32_16x16x32_f16 v[32:35], v[166:169], v[190:193], v[32:35]
	v_mfma_f32_16x16x32_f16 v[28:31], v[174:177], v[190:193], v[28:31]
	v_mfma_f32_16x16x32_f16 v[16:19], v[166:169], v[204:207], v[16:19]
	v_mfma_f32_16x16x32_f16 v[12:15], v[174:177], v[204:207], v[12:15]
	v_mfma_f32_16x16x32_f16 v[8:11], v[166:169], v[224:227], v[8:11]
	v_mfma_f32_16x16x32_f16 v[4:7], v[174:177], v[224:227], v[4:7]
	s_barrier
	s_setprio 0
	s_add_i32 s37, s37, 2
	s_add_u32 s6, s6, 0x100
	s_addc_u32 s7, s7, 0
	s_cmp_gt_u32 s37, 29
	s_cbranch_scc0 .LBB0_426
	s_cmpk_lt_u32 s12, 0x100
	s_cbranch_scc0 .LBB0_429
	s_barrier

; #define PG8_STAGE(bufoff, gbase, voff) do { _Pragma("unroll") for (int _i = 0; _i < 2; ++_i) \
;         __builtin_amdgcn_global_load_lds((const unsigned*)((const char*)(gbase) + (voff)[_i]), (LAS unsigned*)(lds + (bufoff) + ldsw + _i * 8192), 16, 0, 0); } while (0)
; #define PG8_LDA(dst, b, h) do { _Pragma("unroll") for (int m = 0; m < 4; ++m) _Pragma("unroll") for (int k = 0; k < 2; ++k) dst[m][k] = *(const LAS half8*)(lds + PG8_SA(b, h) + aoff + m * 2048 + k * 1024); } while (0)
; #define PG8_LDB(dst, b, h) do { _Pragma("unroll") for (int n = 0; n < 2; ++n) _Pragma("unroll") for (int k = 0; k < 2; ++k) dst[n][k] = *(const LAS half8*)(lds + PG8_SB(b, h) + boff + n * 2048 + k * 1024); } while (0)
; #define PG8_MMA(ai, bj, At, Bt) do { __builtin_amdgcn_s_setprio(1); _Pragma("unroll") for (int m = 0; m < 4; ++m) _Pragma("unroll") for (int n = 0; n < 2; ++n) _Pragma("unroll") for (int k = 0; k < 2; ++k) \
;         acc[ai][bj][m][n] = __builtin_amdgcn_mfma_f32_16x16x32_f16(Bt[n][k], At[m][k], acc[ai][bj][m][n], 0, 0, 0); __builtin_amdgcn_s_setprio(0); } while (0)
; #define PG8_WAIT_V(n) asm volatile("s_waitcnt vmcnt(" #n ")" ::: "memory")
; template <class Epi, class Sched, bool ALIGN_EPI = false, bool SP2 = false>
; __device__ __forceinline__ void gemm_phase(LAS unsigned char* lds, const Gemm g, const Sched& S, const Epi& E) {
;     ...
;             PG8_LDB(B0, 0, 0); PG8_LDB(B1, 0, 1); PG8_SCHED; PG8_LDA(At, 0, 0); PG8_STAGE(PG8_SA(1, 1), a1 + hstepA, voffA);
;             PG8_WAIT_V(8); PG8_WAIT_L(0); PG8_BAR; PG8_MMA(0, 0, At, B0); PG8_MMA(0, 1, At, B1); PG8_BAR; PG8_SCHED;
;             PG8_LDA(At, 0, 1); PG8_STAGE(PG8_SB(0, 0), b2, voffB); PG8_STAGE(PG8_SB(0, 1), b2 + hstepB, voffB); PG8_STAGE(PG8_SA(0, 0), a2, voffA);
;             PG8_WAIT_V(8); PG8_WAIT_L(0); PG8_BAR; PG8_MMA(1, 0, At, B0); PG8_MMA(1, 1, At, B1); PG8_BAR; PG8_SCHED;
;             PG8_LDB(B0, 1, 0); PG8_LDB(B1, 1, 1); PG8_SCHED; PG8_LDA(At, 1, 0); PG8_STAGE(PG8_SA(0, 1), a2 + hstepA, voffA);
;             PG8_WAIT_V(8); PG8_WAIT_L(0); PG8_BAR; PG8_MMA(0, 0, At, B0); PG8_MMA(0, 1, At, B1); PG8_BAR; PG8_SCHED;
;             PG8_LDA(At, 1, 1); PG8_STAGE(PG8_SB(1, 0), b3, voffB); PG8_STAGE(PG8_SB(1, 1), b3 + hstepB, voffB); PG8_STAGE(PG8_SA(1, 0), a3, voffA);
;             PG8_WAIT_V(8); PG8_WAIT_L(0); PG8_BAR; PG8_MMA(1, 0, At, B0); PG8_MMA(1, 1, At, B1); PG8_BAR; PG8_SCHED;
.LBB0_1101:
	s_add_u32 s16, s46, 0xfff80080
	s_addc_u32 s17, s47, -1
	s_add_i32 s63, 0, 0x10000
	s_cmp_eq_u32 s62, 28
	s_cselect_b32 s23, s15, s17
	s_cselect_b32 s22, s58, s16
	v_add_u32_e32 v145, s63, v142
	s_cselect_b32 s17, s13, s61
	s_cselect_b32 s16, s59, s60
	s_add_i32 s66, 0, 0x14000
	ds_read_b128 v[146:149], v145
	ds_read_b128 v[150:153], v145 offset:1024
	ds_read_b128 v[154:157], v145 offset:2048
	ds_read_b128 v[158:161], v145 offset:3072
	v_add_u32_e32 v145, s66, v142
	ds_read_b128 v[162:165], v145
	ds_read_b128 v[166:169], v145 offset:1024
	ds_read_b128 v[170:173], v145 offset:2048
	ds_read_b128 v[174:177], v145 offset:3072
	v_lshl_add_u64 v[194:195], s[46:47], 0, v[138:139]
	s_add_i32 m0, s37, 0xc000
	ds_read_b128 v[178:181], v144
	ds_read_b128 v[182:185], v144 offset:1024
	ds_read_b128 v[186:189], v144 offset:2048
	ds_read_b128 v[190:193], v144 offset:3072
	ds_read_b128 v[204:207], v144 offset:4096
	ds_read_b128 v[220:223], v144 offset:5120
	ds_read_b128 v[224:227], v144 offset:6144
	ds_read_b128 v[228:231], v144 offset:7168
	global_load_lds_dwordx4 v[194:195], off
	v_lshl_add_u64 v[194:195], s[46:47], 0, v[140:141]
	s_add_i32 m0, s37, 0xe000
	s_nop 0
	global_load_lds_dwordx4 v[194:195], off
	s_waitcnt vmcnt(8)
	s_waitcnt lgkmcnt(0)
	s_setprio 1
	s_barrier
	v_mfma_f32_16x16x32_f16 v[128:131], v[146:149], v[178:181], v[128:131]
	v_mfma_f32_16x16x32_f16 v[124:127], v[154:157], v[178:181], v[124:127]
	v_mfma_f32_16x16x32_f16 v[112:115], v[146:149], v[186:189], v[112:115]
	v_mfma_f32_16x16x32_f16 v[108:111], v[154:157], v[186:189], v[108:111]
	v_mfma_f32_16x16x32_f16 v[96:99], v[146:149], v[204:207], v[96:99]
	v_mfma_f32_16x16x32_f16 v[92:95], v[154:157], v[204:207], v[92:95]
	v_mfma_f32_16x16x32_f16 v[80:83], v[146:149], v[224:227], v[80:83]
	v_mfma_f32_16x16x32_f16 v[76:79], v[154:157], v[224:227], v[76:79]
	v_mfma_f32_16x16x32_f16 v[128:131], v[150:153], v[182:185], v[128:131]
	v_mfma_f32_16x16x32_f16 v[124:127], v[158:161], v[182:185], v[124:127]
	v_mfma_f32_16x16x32_f16 v[112:115], v[150:153], v[190:193], v[112:115]
	v_mfma_f32_16x16x32_f16 v[108:111], v[158:161], v[190:193], v[108:111]
	v_mfma_f32_16x16x32_f16 v[96:99], v[150:153], v[220:223], v[96:99]
	v_mfma_f32_16x16x32_f16 v[92:95], v[158:161], v[220:223], v[92:95]
	v_mfma_f32_16x16x32_f16 v[80:83], v[150:153], v[228:231], v[80:83]
	v_mfma_f32_16x16x32_f16 v[76:79], v[158:161], v[228:231], v[76:79]
	v_mfma_f32_16x16x32_f16 v[120:123], v[162:165], v[178:181], v[120:123]
	v_mfma_f32_16x16x32_f16 v[116:119], v[170:173], v[178:181], v[116:119]
	v_mfma_f32_16x16x32_f16 v[104:107], v[162:165], v[186:189], v[104:107]
	v_mfma_f32_16x16x32_f16 v[100:103], v[170:173], v[186:189], v[100:103]
	v_mfma_f32_16x16x32_f16 v[88:91], v[162:165], v[204:207], v[88:91]
	v_mfma_f32_16x16x32_f16 v[84:87], v[170:173], v[204:207], v[84:87]
	v_mfma_f32_16x16x32_f16 v[72:75], v[162:165], v[224:227], v[72:75]
	v_mfma_f32_16x16x32_f16 v[68:71], v[170:173], v[224:227], v[68:71]
	v_mfma_f32_16x16x32_f16 v[120:123], v[166:169], v[182:185], v[120:123]
	v_mfma_f32_16x16x32_f16 v[116:119], v[174:177], v[182:185], v[116:119]
	v_mfma_f32_16x16x32_f16 v[104:107], v[166:169], v[190:193], v[104:107]
	v_mfma_f32_16x16x32_f16 v[100:103], v[174:177], v[190:193], v[100:103]
	v_mfma_f32_16x16x32_f16 v[88:91], v[166:169], v[220:223], v[88:91]
	v_mfma_f32_16x16x32_f16 v[84:87], v[174:177], v[220:223], v[84:87]
	v_mfma_f32_16x16x32_f16 v[72:75], v[166:169], v[228:231], v[72:75]
	v_mfma_f32_16x16x32_f16 v[68:71], v[174:177], v[228:231], v[68:71]
	s_barrier
	s_setprio 0
	s_add_i32 s63, s63, s25
	v_lshl_add_u64 v[194:195], s[16:17], 0, v[2:3]
	s_mov_b32 m0, s63
	ds_read_b128 v[178:181], v144 offset:16384
	ds_read_b128 v[182:185], v144 offset:17408
	ds_read_b128 v[186:189], v144 offset:18432
	ds_read_b128 v[190:193], v144 offset:19456
	ds_read_b128 v[204:207], v144 offset:20480
	ds_read_b128 v[220:223], v144 offset:21504
	ds_read_b128 v[224:227], v144 offset:22528
	ds_read_b128 v[228:231], v144 offset:23552
	global_load_lds_dwordx4 v[194:195], off
	s_add_i32 m0, s63, 0x2000
	s_add_u32 s64, s16, 0x80000
	v_lshl_add_u64 v[196:197], s[16:17], 0, v[132:133]
	s_addc_u32 s65, s17, 0
	s_add_i32 s63, s66, s25
	global_load_lds_dwordx4 v[196:197], off
	v_lshl_add_u64 v[208:209], s[64:65], 0, v[2:3]
	s_mov_b32 m0, s63
	v_lshl_add_u64 v[232:233], s[22:23], 0, v[134:135]
	global_load_lds_dwordx4 v[208:209], off
	v_lshl_add_u64 v[208:209], s[64:65], 0, v[132:133]
	s_add_i32 m0, s63, 0x2000
	s_nop 0
	global_load_lds_dwordx4 v[208:209], off
	v_lshl_add_u64 v[208:209], s[22:23], 0, v[136:137]
	s_mov_b32 m0, s37
	s_nop 0
	global_load_lds_dwordx4 v[208:209], off
	s_mov_b32 m0, s48
	s_nop 0
	global_load_lds_dwordx4 v[232:233], off
	s_waitcnt vmcnt(8)
	s_waitcnt lgkmcnt(0)
	s_setprio 1
	s_barrier
; #define PG8_STAGE(bufoff, gbase, voff) do { _Pragma("unroll") for (int _i = 0; _i < 2; ++_i) \
;         __builtin_amdgcn_global_load_lds((const unsigned*)((const char*)(gbase) + (voff)[_i]), (LAS unsigned*)(lds + (bufoff) + ldsw + _i * 8192), 16, 0, 0); } while (0)
; #define PG8_LDA(dst, b, h) do { _Pragma("unroll") for (int m = 0; m < 4; ++m) _Pragma("unroll") for (int k = 0; k < 2; ++k) dst[m][k] = *(const LAS half8*)(lds + PG8_SA(b, h) + aoff + m * 2048 + k * 1024); } while (0)
; #define PG8_LDB(dst, b, h) do { _Pragma("unroll") for (int n = 0; n < 2; ++n) _Pragma("unroll") for (int k = 0; k < 2; ++k) dst[n][k] = *(const LAS half8*)(lds + PG8_SB(b, h) + boff + n * 2048 + k * 1024); } while (0)
; #define PG8_MMA(ai, bj, At, Bt) do { __builtin_amdgcn_s_setprio(1); _Pragma("unroll") for (int m = 0; m < 4; ++m) _Pragma("unroll") for (int n = 0; n < 2; ++n) _Pragma("unroll") for (int k = 0; k < 2; ++k) \
;         acc[ai][bj][m][n] = __builtin_amdgcn_mfma_f32_16x16x32_f16(Bt[n][k], At[m][k], acc[ai][bj][m][n], 0, 0, 0); __builtin_amdgcn_s_setprio(0); } while (0)
; #define PG8_WAIT_V(n) asm volatile("s_waitcnt vmcnt(" #n ")" ::: "memory")
; template <class Epi, class Sched, bool ALIGN_EPI = false, bool SP2 = false>
; __device__ __forceinline__ void gemm_phase(LAS unsigned char* lds, const Gemm g, const Sched& S, const Epi& E) {
;     ...
;             PG8_LDB(B0, 0, 0); PG8_LDB(B1, 0, 1); PG8_SCHED; PG8_LDA(At, 0, 0); PG8_STAGE(PG8_SA(1, 1), a1 + hstepA, voffA);
;             PG8_WAIT_V(8); PG8_WAIT_L(0); PG8_BAR; PG8_MMA(0, 0, At, B0); PG8_MMA(0, 1, At, B1); PG8_BAR; PG8_SCHED;
;             PG8_LDA(At, 0, 1); PG8_STAGE(PG8_SB(0, 0), b2, voffB); PG8_STAGE(PG8_SB(0, 1), b2 + hstepB, voffB); PG8_STAGE(PG8_SA(0, 0), a2, voffA);
;             PG8_WAIT_V(8); PG8_WAIT_L(0); PG8_BAR; PG8_MMA(1, 0, At, B0); PG8_MMA(1, 1, At, B1); PG8_BAR; PG8_SCHED;
;             PG8_LDB(B0, 1, 0); PG8_LDB(B1, 1, 1); PG8_SCHED; PG8_LDA(At, 1, 0); PG8_STAGE(PG8_SA(0, 1), a2 + hstepA, voffA);
;             PG8_WAIT_V(8); PG8_WAIT_L(0); PG8_BAR; PG8_MMA(0, 0, At, B0); PG8_MMA(0, 1, At, B1); PG8_BAR; PG8_SCHED;
;             PG8_LDA(At, 1, 1); PG8_STAGE(PG8_SB(1, 0), b3, voffB); PG8_STAGE(PG8_SB(1, 1), b3 + hstepB, voffB); PG8_STAGE(PG8_SA(1, 0), a3, voffA);
;             PG8_WAIT_V(8); PG8_WAIT_L(0); PG8_BAR; PG8_MMA(1, 0, At, B0); PG8_MMA(1, 1, At, B1); PG8_BAR; PG8_SCHED;
	v_mfma_f32_16x16x32_f16 v[64:67], v[146:149], v[178:181], v[64:67]
	v_mfma_f32_16x16x32_f16 v[60:63], v[154:157], v[178:181], v[60:63]
	v_mfma_f32_16x16x32_f16 v[48:51], v[146:149], v[186:189], v[48:51]
	v_mfma_f32_16x16x32_f16 v[44:47], v[154:157], v[186:189], v[44:47]
	v_mfma_f32_16x16x32_f16 v[32:35], v[146:149], v[204:207], v[32:35]
	v_mfma_f32_16x16x32_f16 v[28:31], v[154:157], v[204:207], v[28:31]
	v_mfma_f32_16x16x32_f16 v[16:19], v[146:149], v[224:227], v[16:19]
	v_mfma_f32_16x16x32_f16 v[12:15], v[154:157], v[224:227], v[12:15]
	v_mfma_f32_16x16x32_f16 v[64:67], v[150:153], v[182:185], v[64:67]
	v_mfma_f32_16x16x32_f16 v[60:63], v[158:161], v[182:185], v[60:63]
	v_mfma_f32_16x16x32_f16 v[48:51], v[150:153], v[190:193], v[48:51]
	v_mfma_f32_16x16x32_f16 v[44:47], v[158:161], v[190:193], v[44:47]
	v_mfma_f32_16x16x32_f16 v[32:35], v[150:153], v[220:223], v[32:35]
	v_mfma_f32_16x16x32_f16 v[28:31], v[158:161], v[220:223], v[28:31]
	v_mfma_f32_16x16x32_f16 v[16:19], v[150:153], v[228:231], v[16:19]
	v_mfma_f32_16x16x32_f16 v[12:15], v[158:161], v[228:231], v[12:15]
	v_mfma_f32_16x16x32_f16 v[56:59], v[162:165], v[178:181], v[56:59]
	v_mfma_f32_16x16x32_f16 v[52:55], v[170:173], v[178:181], v[52:55]
	v_mfma_f32_16x16x32_f16 v[40:43], v[162:165], v[186:189], v[40:43]
	v_mfma_f32_16x16x32_f16 v[36:39], v[170:173], v[186:189], v[36:39]
	v_mfma_f32_16x16x32_f16 v[24:27], v[162:165], v[204:207], v[24:27]
	v_mfma_f32_16x16x32_f16 v[20:23], v[170:173], v[204:207], v[20:23]
	v_mfma_f32_16x16x32_f16 v[8:11], v[162:165], v[224:227], v[8:11]
	v_mfma_f32_16x16x32_f16 v[4:7], v[170:173], v[224:227], v[4:7]
	v_mfma_f32_16x16x32_f16 v[56:59], v[166:169], v[182:185], v[56:59]
	v_mfma_f32_16x16x32_f16 v[52:55], v[174:177], v[182:185], v[52:55]
	v_mfma_f32_16x16x32_f16 v[40:43], v[166:169], v[190:193], v[40:43]
	v_mfma_f32_16x16x32_f16 v[36:39], v[174:177], v[190:193], v[36:39]
	v_mfma_f32_16x16x32_f16 v[24:27], v[166:169], v[220:223], v[24:27]
	v_mfma_f32_16x16x32_f16 v[20:23], v[174:177], v[220:223], v[20:23]
	v_mfma_f32_16x16x32_f16 v[8:11], v[166:169], v[228:231], v[8:11]
	v_mfma_f32_16x16x32_f16 v[4:7], v[174:177], v[228:231], v[4:7]
	s_barrier
	s_setprio 0
	s_add_i32 s63, 0, 0x18000
	v_add_u32_e32 v145, s63, v142
	s_add_i32 s64, 0, 0x1c000
	ds_read_b128 v[146:149], v145
	ds_read_b128 v[150:153], v145 offset:1024
	ds_read_b128 v[154:157], v145 offset:2048
	ds_read_b128 v[158:161], v145 offset:3072
	v_add_u32_e32 v145, s64, v142
	ds_read_b128 v[162:165], v145
	ds_read_b128 v[166:169], v145 offset:1024
	ds_read_b128 v[170:173], v145 offset:2048
	ds_read_b128 v[174:177], v145 offset:3072
	s_add_u32 s22, s22, 0x80000
	s_addc_u32 s23, s23, 0
	s_mov_b32 m0, s49
	v_lshl_add_u64 v[234:235], s[22:23], 0, v[136:137]
	ds_read_b128 v[178:181], v144 offset:32768
	ds_read_b128 v[182:185], v144 offset:33792
	ds_read_b128 v[186:189], v144 offset:34816
	ds_read_b128 v[190:193], v144 offset:35840
	ds_read_b128 v[204:207], v144 offset:36864
	ds_read_b128 v[220:223], v144 offset:37888
	ds_read_b128 v[224:227], v144 offset:38912
	ds_read_b128 v[228:231], v144 offset:39936
	global_load_lds_dwordx4 v[234:235], off
	v_lshl_add_u64 v[234:235], s[22:23], 0, v[134:135]
	s_mov_b32 m0, s52
	s_nop 0
	global_load_lds_dwordx4 v[234:235], off
	s_waitcnt vmcnt(8)
	s_waitcnt lgkmcnt(0)
	s_setprio 1
	s_barrier
	v_mfma_f32_16x16x32_f16 v[128:131], v[146:149], v[178:181], v[128:131]
	v_mfma_f32_16x16x32_f16 v[124:127], v[154:157], v[178:181], v[124:127]
	v_mfma_f32_16x16x32_f16 v[112:115], v[146:149], v[186:189], v[112:115]
	v_mfma_f32_16x16x32_f16 v[108:111], v[154:157], v[186:189], v[108:111]
	v_mfma_f32_16x16x32_f16 v[96:99], v[146:149], v[204:207], v[96:99]
	v_mfma_f32_16x16x32_f16 v[92:95], v[154:157], v[204:207], v[92:95]
	v_mfma_f32_16x16x32_f16 v[80:83], v[146:149], v[224:227], v[80:83]
	v_mfma_f32_16x16x32_f16 v[76:79], v[154:157], v[224:227], v[76:79]
	v_mfma_f32_16x16x32_f16 v[128:131], v[150:153], v[182:185], v[128:131]
	v_mfma_f32_16x16x32_f16 v[124:127], v[158:161], v[182:185], v[124:127]
	v_mfma_f32_16x16x32_f16 v[112:115], v[150:153], v[190:193], v[112:115]
	v_mfma_f32_16x16x32_f16 v[108:111], v[158:161], v[190:193], v[108:111]
	v_mfma_f32_16x16x32_f16 v[96:99], v[150:153], v[220:223], v[96:99]
	v_mfma_f32_16x16x32_f16 v[92:95], v[158:161], v[220:223], v[92:95]
	v_mfma_f32_16x16x32_f16 v[80:83], v[150:153], v[228:231], v[80:83]
	v_mfma_f32_16x16x32_f16 v[76:79], v[158:161], v[228:231], v[76:79]
	v_mfma_f32_16x16x32_f16 v[120:123], v[162:165], v[178:181], v[120:123]
	v_mfma_f32_16x16x32_f16 v[116:119], v[170:173], v[178:181], v[116:119]
	v_mfma_f32_16x16x32_f16 v[104:107], v[162:165], v[186:189], v[104:107]
	v_mfma_f32_16x16x32_f16 v[100:103], v[170:173], v[186:189], v[100:103]
	v_mfma_f32_16x16x32_f16 v[88:91], v[162:165], v[204:207], v[88:91]
	v_mfma_f32_16x16x32_f16 v[84:87], v[170:173], v[204:207], v[84:87]
	v_mfma_f32_16x16x32_f16 v[72:75], v[162:165], v[224:227], v[72:75]
	v_mfma_f32_16x16x32_f16 v[68:71], v[170:173], v[224:227], v[68:71]
	v_mfma_f32_16x16x32_f16 v[120:123], v[166:169], v[182:185], v[120:123]
	v_mfma_f32_16x16x32_f16 v[116:119], v[174:177], v[182:185], v[116:119]
	v_mfma_f32_16x16x32_f16 v[104:107], v[166:169], v[190:193], v[104:107]
	v_mfma_f32_16x16x32_f16 v[100:103], v[174:177], v[190:193], v[100:103]
	v_mfma_f32_16x16x32_f16 v[88:91], v[166:169], v[220:223], v[88:91]
	v_mfma_f32_16x16x32_f16 v[84:87], v[174:177], v[220:223], v[84:87]
	v_mfma_f32_16x16x32_f16 v[72:75], v[166:169], v[228:231], v[72:75]
	v_mfma_f32_16x16x32_f16 v[68:71], v[174:177], v[228:231], v[68:71]
	s_barrier
; #define PG8_STAGE(bufoff, gbase, voff) do { _Pragma("unroll") for (int _i = 0; _i < 2; ++_i) \
;         __builtin_amdgcn_global_load_lds((const unsigned*)((const char*)(gbase) + (voff)[_i]), (LAS unsigned*)(lds + (bufoff) + ldsw + _i * 8192), 16, 0, 0); } while (0)
; #define PG8_LDA(dst, b, h) do { _Pragma("unroll") for (int m = 0; m < 4; ++m) _Pragma("unroll") for (int k = 0; k < 2; ++k) dst[m][k] = *(const LAS half8*)(lds + PG8_SA(b, h) + aoff + m * 2048 + k * 1024); } while (0)
; #define PG8_LDB(dst, b, h) do { _Pragma("unroll") for (int n = 0; n < 2; ++n) _Pragma("unroll") for (int k = 0; k < 2; ++k) dst[n][k] = *(const LAS half8*)(lds + PG8_SB(b, h) + boff + n * 2048 + k * 1024); } while (0)
; template <class Epi, class Sched, bool ALIGN_EPI = false, bool SP2 = false>
; __device__ __forceinline__ void gemm_phase(LAS unsigned char* lds, const Gemm g, const Sched& S, const Epi& E) {
;     ...
;         for (int t = 0; t < nt; t += 2) {
;             const bool last = (t == nt - 2);
;             const char* a1 = cA + (size_t)(t + 1) * kstep;
;             const char* a2 = last ? nA : cA + (size_t)(t + 2) * kstep; const char* b2 = last ? nB : cB + (size_t)(t + 2) * kstep;
;             const char* a3 = a2 + kstep; const char* b3 = b2 + kstep;
;             if (last && has_next) S.a_ready(nxt);
;             if constexpr (SP2) {
;             PG8_LDB(B0, 0, 0); PG8_LDB(B1, 0, 1); PG8_SCHED; PG8_LDA(At, 0, 0); PG8_STAGE(PG8_SA(1, 1), a1 + hstepA, voffA);
;             PG8_WAIT_V(8); PG8_WAIT_L(0); PG8_BAR; PG8_MMA(0, 0, At, B0); PG8_MMA(0, 1, At, B1); PG8_BAR; PG8_SCHED;
;             PG8_LDA(At, 0, 1); PG8_STAGE(PG8_SB(0, 0), b2, voffB); PG8_STAGE(PG8_SB(0, 1), b2 + hstepB, voffB); PG8_STAGE(PG8_SA(0, 0), a2, voffA);
;             PG8_WAIT_V(8); PG8_WAIT_L(0); PG8_BAR; PG8_MMA(1, 0, At, B0); PG8_MMA(1, 1, At, B1); PG8_BAR; PG8_SCHED;
;             PG8_LDB(B0, 1, 0); PG8_LDB(B1, 1, 1); PG8_SCHED; PG8_LDA(At, 1, 0); PG8_STAGE(PG8_SA(0, 1), a2 + hstepA, voffA);
;             PG8_WAIT_V(8); PG8_WAIT_L(0); PG8_BAR; PG8_MMA(0, 0, At, B0); PG8_MMA(0, 1, At, B1); PG8_BAR; PG8_SCHED;
;             PG8_LDA(At, 1, 1); PG8_STAGE(PG8_SB(1, 0), b3, voffB); PG8_STAGE(PG8_SB(1, 1), b3 + hstepB, voffB); PG8_STAGE(PG8_SA(1, 0), a3, voffA);
;             PG8_WAIT_V(8); PG8_WAIT_L(0); PG8_BAR; PG8_MMA(1, 0, At, B0); PG8_MMA(1, 1, At, B1); PG8_BAR; PG8_SCHED;
	s_setprio 0
	s_add_i32 s22, s63, s25
	v_lshl_add_u64 v[194:195], v[194:195], 0, s[96:97]
	s_mov_b32 m0, s22
	ds_read_b128 v[178:181], v144 offset:49152
	ds_read_b128 v[182:185], v144 offset:50176
	ds_read_b128 v[186:189], v144 offset:51200
	ds_read_b128 v[190:193], v144 offset:52224
	ds_read_b128 v[204:207], v144 offset:53248
	ds_read_b128 v[220:223], v144 offset:54272
	ds_read_b128 v[224:227], v144 offset:55296
	ds_read_b128 v[228:231], v144 offset:56320
	global_load_lds_dwordx4 v[194:195], off
	s_add_i32 m0, s22, 0x2000
	s_add_u32 s16, s16, 0x80080
	v_lshl_add_u64 v[194:195], v[196:197], 0, s[96:97]
	s_addc_u32 s17, s17, 0
	s_add_i32 s22, s64, s25
	global_load_lds_dwordx4 v[194:195], off
	v_lshl_add_u64 v[194:195], s[16:17], 0, v[2:3]
	s_mov_b32 m0, s22
	s_nop 0
	global_load_lds_dwordx4 v[194:195], off
	v_lshl_add_u64 v[194:195], s[16:17], 0, v[132:133]
	s_add_i32 m0, s22, 0x2000
	s_nop 0
	global_load_lds_dwordx4 v[194:195], off
	v_lshl_add_u64 v[194:195], v[208:209], 0, s[96:97]
	s_mov_b32 m0, s53
	s_nop 0
	global_load_lds_dwordx4 v[194:195], off
	v_lshl_add_u64 v[194:195], v[232:233], 0, s[96:97]
	s_mov_b32 m0, s54
	s_nop 0
	global_load_lds_dwordx4 v[194:195], off
	s_waitcnt vmcnt(8)
	s_waitcnt lgkmcnt(0)
	s_setprio 1
	s_barrier
	v_mfma_f32_16x16x32_f16 v[64:67], v[146:149], v[178:181], v[64:67]
	v_mfma_f32_16x16x32_f16 v[60:63], v[154:157], v[178:181], v[60:63]
	v_mfma_f32_16x16x32_f16 v[48:51], v[146:149], v[186:189], v[48:51]
	v_mfma_f32_16x16x32_f16 v[44:47], v[154:157], v[186:189], v[44:47]
	v_mfma_f32_16x16x32_f16 v[32:35], v[146:149], v[204:207], v[32:35]
	v_mfma_f32_16x16x32_f16 v[28:31], v[154:157], v[204:207], v[28:31]
	v_mfma_f32_16x16x32_f16 v[16:19], v[146:149], v[224:227], v[16:19]
	v_mfma_f32_16x16x32_f16 v[12:15], v[154:157], v[224:227], v[12:15]
	v_mfma_f32_16x16x32_f16 v[64:67], v[150:153], v[182:185], v[64:67]
	v_mfma_f32_16x16x32_f16 v[60:63], v[158:161], v[182:185], v[60:63]
	v_mfma_f32_16x16x32_f16 v[48:51], v[150:153], v[190:193], v[48:51]
	v_mfma_f32_16x16x32_f16 v[44:47], v[158:161], v[190:193], v[44:47]
	v_mfma_f32_16x16x32_f16 v[32:35], v[150:153], v[220:223], v[32:35]
	v_mfma_f32_16x16x32_f16 v[28:31], v[158:161], v[220:223], v[28:31]
	v_mfma_f32_16x16x32_f16 v[16:19], v[150:153], v[228:231], v[16:19]
	v_mfma_f32_16x16x32_f16 v[12:15], v[158:161], v[228:231], v[12:15]
	v_mfma_f32_16x16x32_f16 v[56:59], v[162:165], v[178:181], v[56:59]
	v_mfma_f32_16x16x32_f16 v[52:55], v[170:173], v[178:181], v[52:55]
	v_mfma_f32_16x16x32_f16 v[40:43], v[162:165], v[186:189], v[40:43]
	v_mfma_f32_16x16x32_f16 v[36:39], v[170:173], v[186:189], v[36:39]
	v_mfma_f32_16x16x32_f16 v[24:27], v[162:165], v[204:207], v[24:27]
	v_mfma_f32_16x16x32_f16 v[20:23], v[170:173], v[204:207], v[20:23]
	v_mfma_f32_16x16x32_f16 v[8:11], v[162:165], v[224:227], v[8:11]
	v_mfma_f32_16x16x32_f16 v[4:7], v[170:173], v[224:227], v[4:7]
	v_mfma_f32_16x16x32_f16 v[56:59], v[166:169], v[182:185], v[56:59]
	v_mfma_f32_16x16x32_f16 v[52:55], v[174:177], v[182:185], v[52:55]
	v_mfma_f32_16x16x32_f16 v[40:43], v[166:169], v[190:193], v[40:43]
	v_mfma_f32_16x16x32_f16 v[36:39], v[174:177], v[190:193], v[36:39]
	v_mfma_f32_16x16x32_f16 v[24:27], v[166:169], v[220:223], v[24:27]
	v_mfma_f32_16x16x32_f16 v[20:23], v[174:177], v[220:223], v[20:23]
	v_mfma_f32_16x16x32_f16 v[8:11], v[166:169], v[228:231], v[8:11]
	v_mfma_f32_16x16x32_f16 v[4:7], v[174:177], v[228:231], v[4:7]
	s_barrier
	s_setprio 0
	s_add_i32 s62, s62, 2
	s_add_u32 s46, s46, 0x100
	s_addc_u32 s47, s47, 0
	s_add_u32 s60, s60, 0x100
	s_addc_u32 s61, s61, 0
	s_cmp_gt_u32 s62, 29
	s_cbranch_scc0 .LBB0_1101
	s_and_b64 vcc, exec, s[10:11]
	s_cbranch_vccz .LBB0_1104
	s_barrier

; #define PG8_STAGE(bufoff, gbase, voff) do { _Pragma("unroll") for (int _i = 0; _i < 2; ++_i) \
;         __builtin_amdgcn_global_load_lds((const unsigned*)((const char*)(gbase) + (voff)[_i]), (LAS unsigned*)(lds + (bufoff) + ldsw + _i * 8192), 16, 0, 0); } while (0)
; #define PG8_LDA(dst, b, h) do { _Pragma("unroll") for (int m = 0; m < 4; ++m) _Pragma("unroll") for (int k = 0; k < 2; ++k) dst[m][k] = *(const LAS half8*)(lds + PG8_SA(b, h) + aoff + m * 2048 + k * 1024); } while (0)
; #define PG8_LDB(dst, b, h) do { _Pragma("unroll") for (int n = 0; n < 2; ++n) _Pragma("unroll") for (int k = 0; k < 2; ++k) dst[n][k] = *(const LAS half8*)(lds + PG8_SB(b, h) + boff + n * 2048 + k * 1024); } while (0)
; #define PG8_MMA(ai, bj, At, Bt) do { __builtin_amdgcn_s_setprio(1); _Pragma("unroll") for (int m = 0; m < 4; ++m) _Pragma("unroll") for (int n = 0; n < 2; ++n) _Pragma("unroll") for (int k = 0; k < 2; ++k) \
;         acc[ai][bj][m][n] = __builtin_amdgcn_mfma_f32_16x16x32_f16(Bt[n][k], At[m][k], acc[ai][bj][m][n], 0, 0, 0); __builtin_amdgcn_s_setprio(0); } while (0)
; #define PG8_WAIT_V(n) asm volatile("s_waitcnt vmcnt(" #n ")" ::: "memory")
; template <class Epi, class Sched, bool ALIGN_EPI = false, bool SP2 = false>
; __device__ __forceinline__ void gemm_phase(LAS unsigned char* lds, const Gemm g, const Sched& S, const Epi& E) {
;     ...
;             PG8_LDB(B0, 0, 0); PG8_LDB(B1, 0, 1); PG8_SCHED; PG8_LDA(At, 0, 0); PG8_STAGE(PG8_SA(1, 1), a1 + hstepA, voffA);
;             PG8_WAIT_V(8); PG8_WAIT_L(0); PG8_BAR; PG8_MMA(0, 0, At, B0); PG8_MMA(0, 1, At, B1); PG8_BAR; PG8_SCHED;
;             PG8_LDA(At, 0, 1); PG8_STAGE(PG8_SB(0, 0), b2, voffB); PG8_STAGE(PG8_SB(0, 1), b2 + hstepB, voffB); PG8_STAGE(PG8_SA(0, 0), a2, voffA);
;             PG8_WAIT_V(8); PG8_WAIT_L(0); PG8_BAR; PG8_MMA(1, 0, At, B0); PG8_MMA(1, 1, At, B1); PG8_BAR; PG8_SCHED;
;             PG8_LDB(B0, 1, 0); PG8_LDB(B1, 1, 1); PG8_SCHED; PG8_LDA(At, 1, 0); PG8_STAGE(PG8_SA(0, 1), a2 + hstepA, voffA);
;             PG8_WAIT_V(8); PG8_WAIT_L(0); PG8_BAR; PG8_MMA(0, 0, At, B0); PG8_MMA(0, 1, At, B1); PG8_BAR; PG8_SCHED;
;             PG8_LDA(At, 1, 1); PG8_STAGE(PG8_SB(1, 0), b3, voffB); PG8_STAGE(PG8_SB(1, 1), b3 + hstepB, voffB); PG8_STAGE(PG8_SA(1, 0), a3, voffA);
;             PG8_WAIT_V(8); PG8_WAIT_L(0); PG8_BAR; PG8_MMA(1, 0, At, B0); PG8_MMA(1, 1, At, B1); PG8_BAR; PG8_SCHED;
.LBB0_1708:
	s_add_u32 s8, s0, 0xfff80080
	s_addc_u32 s9, s1, -1
	s_add_i32 s22, 0, 0x10000
	s_cmp_eq_u32 s17, 28
	s_cselect_b32 s11, s2, s9
	s_cselect_b32 s10, s12, s8
	v_add_u32_e32 v2, s22, v189
	s_cselect_b32 s9, s13, s16
	s_cselect_b32 s8, s14, s15
	s_add_i32 s44, 0, 0x14000
	ds_read_b128 v[132:135], v2
	ds_read_b128 v[136:139], v2 offset:1024
	ds_read_b128 v[140:143], v2 offset:2048
	ds_read_b128 v[144:147], v2 offset:3072
	v_add_u32_e32 v2, s44, v189
	ds_read_b128 v[148:151], v2
	ds_read_b128 v[152:155], v2 offset:1024
	ds_read_b128 v[156:159], v2 offset:2048
	ds_read_b128 v[160:163], v2 offset:3072
	v_lshl_add_u64 v[194:195], s[0:1], 0, v[172:173]
	s_add_i32 m0, s57, 0xc000
	ds_read_b128 v[176:179], v193
	ds_read_b128 v[180:183], v193 offset:1024
	ds_read_b128 v[184:187], v193 offset:2048
	ds_read_b128 v[204:207], v193 offset:3072
	ds_read_b128 v[220:223], v193 offset:4096
	ds_read_b128 v[224:227], v193 offset:5120
	ds_read_b128 v[228:231], v193 offset:6144
	ds_read_b128 v[232:235], v193 offset:7168
	global_load_lds_dwordx4 v[194:195], off
	v_lshl_add_u64 v[194:195], s[0:1], 0, v[174:175]
	s_add_i32 m0, s57, 0xe000
	s_nop 0
	global_load_lds_dwordx4 v[194:195], off
	s_waitcnt vmcnt(8)
	s_waitcnt lgkmcnt(0)
	s_setprio 1
	s_barrier
	v_mfma_f32_16x16x32_f16 v[128:131], v[132:135], v[176:179], v[128:131]
	v_mfma_f32_16x16x32_f16 v[124:127], v[140:143], v[176:179], v[124:127]
	v_mfma_f32_16x16x32_f16 v[112:115], v[132:135], v[184:187], v[112:115]
	v_mfma_f32_16x16x32_f16 v[108:111], v[140:143], v[184:187], v[108:111]
	v_mfma_f32_16x16x32_f16 v[96:99], v[132:135], v[220:223], v[96:99]
	v_mfma_f32_16x16x32_f16 v[92:95], v[140:143], v[220:223], v[92:95]
	v_mfma_f32_16x16x32_f16 v[80:83], v[132:135], v[228:231], v[80:83]
	v_mfma_f32_16x16x32_f16 v[76:79], v[140:143], v[228:231], v[76:79]
	v_mfma_f32_16x16x32_f16 v[128:131], v[136:139], v[180:183], v[128:131]
	v_mfma_f32_16x16x32_f16 v[124:127], v[144:147], v[180:183], v[124:127]
	v_mfma_f32_16x16x32_f16 v[112:115], v[136:139], v[204:207], v[112:115]
	v_mfma_f32_16x16x32_f16 v[108:111], v[144:147], v[204:207], v[108:111]
	v_mfma_f32_16x16x32_f16 v[96:99], v[136:139], v[224:227], v[96:99]
	v_mfma_f32_16x16x32_f16 v[92:95], v[144:147], v[224:227], v[92:95]
	v_mfma_f32_16x16x32_f16 v[80:83], v[136:139], v[232:235], v[80:83]
	v_mfma_f32_16x16x32_f16 v[76:79], v[144:147], v[232:235], v[76:79]
	v_mfma_f32_16x16x32_f16 v[120:123], v[148:151], v[176:179], v[120:123]
	v_mfma_f32_16x16x32_f16 v[116:119], v[156:159], v[176:179], v[116:119]
	v_mfma_f32_16x16x32_f16 v[104:107], v[148:151], v[184:187], v[104:107]
	v_mfma_f32_16x16x32_f16 v[100:103], v[156:159], v[184:187], v[100:103]
	v_mfma_f32_16x16x32_f16 v[88:91], v[148:151], v[220:223], v[88:91]
	v_mfma_f32_16x16x32_f16 v[84:87], v[156:159], v[220:223], v[84:87]
	v_mfma_f32_16x16x32_f16 v[72:75], v[148:151], v[228:231], v[72:75]
	v_mfma_f32_16x16x32_f16 v[68:71], v[156:159], v[228:231], v[68:71]
	v_mfma_f32_16x16x32_f16 v[120:123], v[152:155], v[180:183], v[120:123]
	v_mfma_f32_16x16x32_f16 v[116:119], v[160:163], v[180:183], v[116:119]
	v_mfma_f32_16x16x32_f16 v[104:107], v[152:155], v[204:207], v[104:107]
	v_mfma_f32_16x16x32_f16 v[100:103], v[160:163], v[204:207], v[100:103]
	v_mfma_f32_16x16x32_f16 v[88:91], v[152:155], v[224:227], v[88:91]
	v_mfma_f32_16x16x32_f16 v[84:87], v[160:163], v[224:227], v[84:87]
	v_mfma_f32_16x16x32_f16 v[72:75], v[152:155], v[232:235], v[72:75]
	v_mfma_f32_16x16x32_f16 v[68:71], v[160:163], v[232:235], v[68:71]
	s_barrier
	s_setprio 0
	s_add_i32 s22, s22, s56
	v_lshl_add_u64 v[194:195], s[8:9], 0, v[168:169]
	s_mov_b32 m0, s22
	ds_read_b128 v[176:179], v193 offset:16384
	ds_read_b128 v[180:183], v193 offset:17408
	ds_read_b128 v[184:187], v193 offset:18432
	ds_read_b128 v[204:207], v193 offset:19456
	ds_read_b128 v[220:223], v193 offset:20480
	ds_read_b128 v[224:227], v193 offset:21504
	ds_read_b128 v[228:231], v193 offset:22528
	ds_read_b128 v[232:235], v193 offset:23552
	global_load_lds_dwordx4 v[194:195], off
	s_add_i32 m0, s22, 0x2000
	s_add_u32 s22, s8, 0x80000
	v_lshl_add_u64 v[196:197], s[8:9], 0, v[164:165]
	s_addc_u32 s23, s9, 0
	s_add_i32 s44, s44, s56
	global_load_lds_dwordx4 v[196:197], off
	v_lshl_add_u64 v[208:209], s[22:23], 0, v[168:169]
	s_mov_b32 m0, s44
	v_lshl_add_u64 v[236:237], s[10:11], 0, v[166:167]
	global_load_lds_dwordx4 v[208:209], off
	v_lshl_add_u64 v[208:209], s[22:23], 0, v[164:165]
	s_add_i32 m0, s44, 0x2000
	s_nop 0
	global_load_lds_dwordx4 v[208:209], off
	v_lshl_add_u64 v[208:209], s[10:11], 0, v[170:171]
	s_mov_b32 m0, s57
	s_nop 0
	global_load_lds_dwordx4 v[208:209], off
	s_mov_b32 m0, s58
	s_nop 0
	global_load_lds_dwordx4 v[236:237], off
	s_waitcnt vmcnt(8)
	s_waitcnt lgkmcnt(0)
	s_setprio 1
	s_barrier
; #define PG8_STAGE(bufoff, gbase, voff) do { _Pragma("unroll") for (int _i = 0; _i < 2; ++_i) \
;         __builtin_amdgcn_global_load_lds((const unsigned*)((const char*)(gbase) + (voff)[_i]), (LAS unsigned*)(lds + (bufoff) + ldsw + _i * 8192), 16, 0, 0); } while (0)
; #define PG8_LDA(dst, b, h) do { _Pragma("unroll") for (int m = 0; m < 4; ++m) _Pragma("unroll") for (int k = 0; k < 2; ++k) dst[m][k] = *(const LAS half8*)(lds + PG8_SA(b, h) + aoff + m * 2048 + k * 1024); } while (0)
; #define PG8_LDB(dst, b, h) do { _Pragma("unroll") for (int n = 0; n < 2; ++n) _Pragma("unroll") for (int k = 0; k < 2; ++k) dst[n][k] = *(const LAS half8*)(lds + PG8_SB(b, h) + boff + n * 2048 + k * 1024); } while (0)
; #define PG8_MMA(ai, bj, At, Bt) do { __builtin_amdgcn_s_setprio(1); _Pragma("unroll") for (int m = 0; m < 4; ++m) _Pragma("unroll") for (int n = 0; n < 2; ++n) _Pragma("unroll") for (int k = 0; k < 2; ++k) \
;         acc[ai][bj][m][n] = __builtin_amdgcn_mfma_f32_16x16x32_f16(Bt[n][k], At[m][k], acc[ai][bj][m][n], 0, 0, 0); __builtin_amdgcn_s_setprio(0); } while (0)
; #define PG8_WAIT_V(n) asm volatile("s_waitcnt vmcnt(" #n ")" ::: "memory")
; template <class Epi, class Sched, bool ALIGN_EPI = false, bool SP2 = false>
; __device__ __forceinline__ void gemm_phase(LAS unsigned char* lds, const Gemm g, const Sched& S, const Epi& E) {
;     ...
;             PG8_LDB(B0, 0, 0); PG8_LDB(B1, 0, 1); PG8_SCHED; PG8_LDA(At, 0, 0); PG8_STAGE(PG8_SA(1, 1), a1 + hstepA, voffA);
;             PG8_WAIT_V(8); PG8_WAIT_L(0); PG8_BAR; PG8_MMA(0, 0, At, B0); PG8_MMA(0, 1, At, B1); PG8_BAR; PG8_SCHED;
;             PG8_LDA(At, 0, 1); PG8_STAGE(PG8_SB(0, 0), b2, voffB); PG8_STAGE(PG8_SB(0, 1), b2 + hstepB, voffB); PG8_STAGE(PG8_SA(0, 0), a2, voffA);
;             PG8_WAIT_V(8); PG8_WAIT_L(0); PG8_BAR; PG8_MMA(1, 0, At, B0); PG8_MMA(1, 1, At, B1); PG8_BAR; PG8_SCHED;
;             PG8_LDB(B0, 1, 0); PG8_LDB(B1, 1, 1); PG8_SCHED; PG8_LDA(At, 1, 0); PG8_STAGE(PG8_SA(0, 1), a2 + hstepA, voffA);
;             PG8_WAIT_V(8); PG8_WAIT_L(0); PG8_BAR; PG8_MMA(0, 0, At, B0); PG8_MMA(0, 1, At, B1); PG8_BAR; PG8_SCHED;
;             PG8_LDA(At, 1, 1); PG8_STAGE(PG8_SB(1, 0), b3, voffB); PG8_STAGE(PG8_SB(1, 1), b3 + hstepB, voffB); PG8_STAGE(PG8_SA(1, 0), a3, voffA);
;             PG8_WAIT_V(8); PG8_WAIT_L(0); PG8_BAR; PG8_MMA(1, 0, At, B0); PG8_MMA(1, 1, At, B1); PG8_BAR; PG8_SCHED;
	v_mfma_f32_16x16x32_f16 v[64:67], v[132:135], v[176:179], v[64:67]
	v_mfma_f32_16x16x32_f16 v[60:63], v[140:143], v[176:179], v[60:63]
	v_mfma_f32_16x16x32_f16 v[48:51], v[132:135], v[184:187], v[48:51]
	v_mfma_f32_16x16x32_f16 v[44:47], v[140:143], v[184:187], v[44:47]
	v_mfma_f32_16x16x32_f16 v[32:35], v[132:135], v[220:223], v[32:35]
	v_mfma_f32_16x16x32_f16 v[28:31], v[140:143], v[220:223], v[28:31]
	v_mfma_f32_16x16x32_f16 v[16:19], v[132:135], v[228:231], v[16:19]
	v_mfma_f32_16x16x32_f16 v[12:15], v[140:143], v[228:231], v[12:15]
	v_mfma_f32_16x16x32_f16 v[64:67], v[136:139], v[180:183], v[64:67]
	v_mfma_f32_16x16x32_f16 v[60:63], v[144:147], v[180:183], v[60:63]
	v_mfma_f32_16x16x32_f16 v[48:51], v[136:139], v[204:207], v[48:51]
	v_mfma_f32_16x16x32_f16 v[44:47], v[144:147], v[204:207], v[44:47]
	v_mfma_f32_16x16x32_f16 v[32:35], v[136:139], v[224:227], v[32:35]
	v_mfma_f32_16x16x32_f16 v[28:31], v[144:147], v[224:227], v[28:31]
	v_mfma_f32_16x16x32_f16 v[16:19], v[136:139], v[232:235], v[16:19]
	v_mfma_f32_16x16x32_f16 v[12:15], v[144:147], v[232:235], v[12:15]
	v_mfma_f32_16x16x32_f16 v[56:59], v[148:151], v[176:179], v[56:59]
	v_mfma_f32_16x16x32_f16 v[52:55], v[156:159], v[176:179], v[52:55]
	v_mfma_f32_16x16x32_f16 v[40:43], v[148:151], v[184:187], v[40:43]
	v_mfma_f32_16x16x32_f16 v[36:39], v[156:159], v[184:187], v[36:39]
	v_mfma_f32_16x16x32_f16 v[24:27], v[148:151], v[220:223], v[24:27]
	v_mfma_f32_16x16x32_f16 v[20:23], v[156:159], v[220:223], v[20:23]
	v_mfma_f32_16x16x32_f16 v[8:11], v[148:151], v[228:231], v[8:11]
	v_mfma_f32_16x16x32_f16 v[4:7], v[156:159], v[228:231], v[4:7]
	v_mfma_f32_16x16x32_f16 v[56:59], v[152:155], v[180:183], v[56:59]
	v_mfma_f32_16x16x32_f16 v[52:55], v[160:163], v[180:183], v[52:55]
	v_mfma_f32_16x16x32_f16 v[40:43], v[152:155], v[204:207], v[40:43]
	v_mfma_f32_16x16x32_f16 v[36:39], v[160:163], v[204:207], v[36:39]
	v_mfma_f32_16x16x32_f16 v[24:27], v[152:155], v[224:227], v[24:27]
	v_mfma_f32_16x16x32_f16 v[20:23], v[160:163], v[224:227], v[20:23]
	v_mfma_f32_16x16x32_f16 v[8:11], v[152:155], v[232:235], v[8:11]
	v_mfma_f32_16x16x32_f16 v[4:7], v[160:163], v[232:235], v[4:7]
	s_barrier
	s_setprio 0
	s_add_i32 s22, 0, 0x18000
	v_add_u32_e32 v2, s22, v189
	s_add_i32 s23, 0, 0x1c000
	ds_read_b128 v[132:135], v2
	ds_read_b128 v[136:139], v2 offset:1024
	ds_read_b128 v[140:143], v2 offset:2048
	ds_read_b128 v[144:147], v2 offset:3072
	v_add_u32_e32 v2, s23, v189
	ds_read_b128 v[148:151], v2
	ds_read_b128 v[152:155], v2 offset:1024
	ds_read_b128 v[156:159], v2 offset:2048
	ds_read_b128 v[160:163], v2 offset:3072
	s_add_u32 s10, s10, 0x80000
	s_addc_u32 s11, s11, 0
	s_mov_b32 m0, s59
	v_lshl_add_u64 v[240:241], s[10:11], 0, v[170:171]
	ds_read_b128 v[176:179], v193 offset:32768
	ds_read_b128 v[180:183], v193 offset:33792
	ds_read_b128 v[184:187], v193 offset:34816
	ds_read_b128 v[204:207], v193 offset:35840
	ds_read_b128 v[220:223], v193 offset:36864
	ds_read_b128 v[224:227], v193 offset:37888
	ds_read_b128 v[228:231], v193 offset:38912
	ds_read_b128 v[232:235], v193 offset:39936
	global_load_lds_dwordx4 v[240:241], off
	v_lshl_add_u64 v[240:241], s[10:11], 0, v[166:167]
	s_mov_b32 m0, s60
	s_nop 0
	global_load_lds_dwordx4 v[240:241], off
	s_waitcnt vmcnt(8)
	s_waitcnt lgkmcnt(0)
	s_setprio 1
	s_barrier
	v_mfma_f32_16x16x32_f16 v[128:131], v[132:135], v[176:179], v[128:131]
	v_mfma_f32_16x16x32_f16 v[124:127], v[140:143], v[176:179], v[124:127]
	v_mfma_f32_16x16x32_f16 v[112:115], v[132:135], v[184:187], v[112:115]
	v_mfma_f32_16x16x32_f16 v[108:111], v[140:143], v[184:187], v[108:111]
	v_mfma_f32_16x16x32_f16 v[96:99], v[132:135], v[220:223], v[96:99]
	v_mfma_f32_16x16x32_f16 v[92:95], v[140:143], v[220:223], v[92:95]
	v_mfma_f32_16x16x32_f16 v[80:83], v[132:135], v[228:231], v[80:83]
	v_mfma_f32_16x16x32_f16 v[76:79], v[140:143], v[228:231], v[76:79]
	v_mfma_f32_16x16x32_f16 v[128:131], v[136:139], v[180:183], v[128:131]
	v_mfma_f32_16x16x32_f16 v[124:127], v[144:147], v[180:183], v[124:127]
	v_mfma_f32_16x16x32_f16 v[112:115], v[136:139], v[204:207], v[112:115]
	v_mfma_f32_16x16x32_f16 v[108:111], v[144:147], v[204:207], v[108:111]
	v_mfma_f32_16x16x32_f16 v[96:99], v[136:139], v[224:227], v[96:99]
	v_mfma_f32_16x16x32_f16 v[92:95], v[144:147], v[224:227], v[92:95]
	v_mfma_f32_16x16x32_f16 v[80:83], v[136:139], v[232:235], v[80:83]
	v_mfma_f32_16x16x32_f16 v[76:79], v[144:147], v[232:235], v[76:79]
	v_mfma_f32_16x16x32_f16 v[120:123], v[148:151], v[176:179], v[120:123]
	v_mfma_f32_16x16x32_f16 v[116:119], v[156:159], v[176:179], v[116:119]
	v_mfma_f32_16x16x32_f16 v[104:107], v[148:151], v[184:187], v[104:107]
	v_mfma_f32_16x16x32_f16 v[100:103], v[156:159], v[184:187], v[100:103]
	v_mfma_f32_16x16x32_f16 v[88:91], v[148:151], v[220:223], v[88:91]
	v_mfma_f32_16x16x32_f16 v[84:87], v[156:159], v[220:223], v[84:87]
	v_mfma_f32_16x16x32_f16 v[72:75], v[148:151], v[228:231], v[72:75]
	v_mfma_f32_16x16x32_f16 v[68:71], v[156:159], v[228:231], v[68:71]
	v_mfma_f32_16x16x32_f16 v[120:123], v[152:155], v[180:183], v[120:123]
	v_mfma_f32_16x16x32_f16 v[116:119], v[160:163], v[180:183], v[116:119]
	v_mfma_f32_16x16x32_f16 v[104:107], v[152:155], v[204:207], v[104:107]
	v_mfma_f32_16x16x32_f16 v[100:103], v[160:163], v[204:207], v[100:103]
	v_mfma_f32_16x16x32_f16 v[88:91], v[152:155], v[224:227], v[88:91]
	v_mfma_f32_16x16x32_f16 v[84:87], v[160:163], v[224:227], v[84:87]
	v_mfma_f32_16x16x32_f16 v[72:75], v[152:155], v[232:235], v[72:75]
	v_mfma_f32_16x16x32_f16 v[68:71], v[160:163], v[232:235], v[68:71]
	s_barrier
; #define PG8_STAGE(bufoff, gbase, voff) do { _Pragma("unroll") for (int _i = 0; _i < 2; ++_i) \
;         __builtin_amdgcn_global_load_lds((const unsigned*)((const char*)(gbase) + (voff)[_i]), (LAS unsigned*)(lds + (bufoff) + ldsw + _i * 8192), 16, 0, 0); } while (0)
; #define PG8_LDA(dst, b, h) do { _Pragma("unroll") for (int m = 0; m < 4; ++m) _Pragma("unroll") for (int k = 0; k < 2; ++k) dst[m][k] = *(const LAS half8*)(lds + PG8_SA(b, h) + aoff + m * 2048 + k * 1024); } while (0)
; #define PG8_LDB(dst, b, h) do { _Pragma("unroll") for (int n = 0; n < 2; ++n) _Pragma("unroll") for (int k = 0; k < 2; ++k) dst[n][k] = *(const LAS half8*)(lds + PG8_SB(b, h) + boff + n * 2048 + k * 1024); } while (0)
; template <class Epi, class Sched, bool ALIGN_EPI = false, bool SP2 = false>
; __device__ __forceinline__ void gemm_phase(LAS unsigned char* lds, const Gemm g, const Sched& S, const Epi& E) {
;     ...
;         for (int t = 0; t < nt; t += 2) {
;             const bool last = (t == nt - 2);
;             const char* a1 = cA + (size_t)(t + 1) * kstep;
;             const char* a2 = last ? nA : cA + (size_t)(t + 2) * kstep; const char* b2 = last ? nB : cB + (size_t)(t + 2) * kstep;
;             const char* a3 = a2 + kstep; const char* b3 = b2 + kstep;
;             if (last && has_next) S.a_ready(nxt);
;             if constexpr (SP2) {
;             PG8_LDB(B0, 0, 0); PG8_LDB(B1, 0, 1); PG8_SCHED; PG8_LDA(At, 0, 0); PG8_STAGE(PG8_SA(1, 1), a1 + hstepA, voffA);
;             PG8_WAIT_V(8); PG8_WAIT_L(0); PG8_BAR; PG8_MMA(0, 0, At, B0); PG8_MMA(0, 1, At, B1); PG8_BAR; PG8_SCHED;
;             PG8_LDA(At, 0, 1); PG8_STAGE(PG8_SB(0, 0), b2, voffB); PG8_STAGE(PG8_SB(0, 1), b2 + hstepB, voffB); PG8_STAGE(PG8_SA(0, 0), a2, voffA);
;             PG8_WAIT_V(8); PG8_WAIT_L(0); PG8_BAR; PG8_MMA(1, 0, At, B0); PG8_MMA(1, 1, At, B1); PG8_BAR; PG8_SCHED;
;             PG8_LDB(B0, 1, 0); PG8_LDB(B1, 1, 1); PG8_SCHED; PG8_LDA(At, 1, 0); PG8_STAGE(PG8_SA(0, 1), a2 + hstepA, voffA);
;             PG8_WAIT_V(8); PG8_WAIT_L(0); PG8_BAR; PG8_MMA(0, 0, At, B0); PG8_MMA(0, 1, At, B1); PG8_BAR; PG8_SCHED;
;             PG8_LDA(At, 1, 1); PG8_STAGE(PG8_SB(1, 0), b3, voffB); PG8_STAGE(PG8_SB(1, 1), b3 + hstepB, voffB); PG8_STAGE(PG8_SA(1, 0), a3, voffA);
;             PG8_WAIT_V(8); PG8_WAIT_L(0); PG8_BAR; PG8_MMA(1, 0, At, B0); PG8_MMA(1, 1, At, B1); PG8_BAR; PG8_SCHED;
	s_setprio 0
	s_add_i32 s10, s22, s56
	v_lshl_add_u64 v[194:195], v[194:195], 0, s[96:97]
	s_mov_b32 m0, s10
	ds_read_b128 v[176:179], v193 offset:49152
	ds_read_b128 v[180:183], v193 offset:50176
	ds_read_b128 v[184:187], v193 offset:51200
	ds_read_b128 v[204:207], v193 offset:52224
	ds_read_b128 v[220:223], v193 offset:53248
	ds_read_b128 v[224:227], v193 offset:54272
	ds_read_b128 v[228:231], v193 offset:55296
	ds_read_b128 v[232:235], v193 offset:56320
	global_load_lds_dwordx4 v[194:195], off
	s_add_i32 m0, s10, 0x2000
	s_add_u32 s8, s8, 0x80080
	v_lshl_add_u64 v[194:195], v[196:197], 0, s[96:97]
	s_addc_u32 s9, s9, 0
	s_add_i32 s10, s23, s56
	global_load_lds_dwordx4 v[194:195], off
	v_lshl_add_u64 v[194:195], s[8:9], 0, v[168:169]
	s_mov_b32 m0, s10
	s_nop 0
	global_load_lds_dwordx4 v[194:195], off
	v_lshl_add_u64 v[194:195], s[8:9], 0, v[164:165]
	s_add_i32 m0, s10, 0x2000
	s_nop 0
	global_load_lds_dwordx4 v[194:195], off
	v_lshl_add_u64 v[194:195], v[208:209], 0, s[96:97]
	s_mov_b32 m0, s62
	s_nop 0
	global_load_lds_dwordx4 v[194:195], off
	v_lshl_add_u64 v[194:195], v[236:237], 0, s[96:97]
	s_mov_b32 m0, s63
	s_nop 0
	global_load_lds_dwordx4 v[194:195], off
	s_waitcnt vmcnt(8)
	s_waitcnt lgkmcnt(0)
	s_setprio 1
	s_barrier
	v_mfma_f32_16x16x32_f16 v[64:67], v[132:135], v[176:179], v[64:67]
	v_mfma_f32_16x16x32_f16 v[60:63], v[140:143], v[176:179], v[60:63]
	v_mfma_f32_16x16x32_f16 v[48:51], v[132:135], v[184:187], v[48:51]
	v_mfma_f32_16x16x32_f16 v[44:47], v[140:143], v[184:187], v[44:47]
	v_mfma_f32_16x16x32_f16 v[32:35], v[132:135], v[220:223], v[32:35]
	v_mfma_f32_16x16x32_f16 v[28:31], v[140:143], v[220:223], v[28:31]
	v_mfma_f32_16x16x32_f16 v[16:19], v[132:135], v[228:231], v[16:19]
	v_mfma_f32_16x16x32_f16 v[12:15], v[140:143], v[228:231], v[12:15]
	v_mfma_f32_16x16x32_f16 v[64:67], v[136:139], v[180:183], v[64:67]
	v_mfma_f32_16x16x32_f16 v[60:63], v[144:147], v[180:183], v[60:63]
	v_mfma_f32_16x16x32_f16 v[48:51], v[136:139], v[204:207], v[48:51]
	v_mfma_f32_16x16x32_f16 v[44:47], v[144:147], v[204:207], v[44:47]
	v_mfma_f32_16x16x32_f16 v[32:35], v[136:139], v[224:227], v[32:35]
	v_mfma_f32_16x16x32_f16 v[28:31], v[144:147], v[224:227], v[28:31]
	v_mfma_f32_16x16x32_f16 v[16:19], v[136:139], v[232:235], v[16:19]
	v_mfma_f32_16x16x32_f16 v[12:15], v[144:147], v[232:235], v[12:15]
	v_mfma_f32_16x16x32_f16 v[56:59], v[148:151], v[176:179], v[56:59]
	v_mfma_f32_16x16x32_f16 v[52:55], v[156:159], v[176:179], v[52:55]
	v_mfma_f32_16x16x32_f16 v[40:43], v[148:151], v[184:187], v[40:43]
	v_mfma_f32_16x16x32_f16 v[36:39], v[156:159], v[184:187], v[36:39]
	v_mfma_f32_16x16x32_f16 v[24:27], v[148:151], v[220:223], v[24:27]
	v_mfma_f32_16x16x32_f16 v[20:23], v[156:159], v[220:223], v[20:23]
	v_mfma_f32_16x16x32_f16 v[8:11], v[148:151], v[228:231], v[8:11]
	v_mfma_f32_16x16x32_f16 v[4:7], v[156:159], v[228:231], v[4:7]
	v_mfma_f32_16x16x32_f16 v[56:59], v[152:155], v[180:183], v[56:59]
	v_mfma_f32_16x16x32_f16 v[52:55], v[160:163], v[180:183], v[52:55]
	v_mfma_f32_16x16x32_f16 v[40:43], v[152:155], v[204:207], v[40:43]
	v_mfma_f32_16x16x32_f16 v[36:39], v[160:163], v[204:207], v[36:39]
	v_mfma_f32_16x16x32_f16 v[24:27], v[152:155], v[224:227], v[24:27]
	v_mfma_f32_16x16x32_f16 v[20:23], v[160:163], v[224:227], v[20:23]
	v_mfma_f32_16x16x32_f16 v[8:11], v[152:155], v[232:235], v[8:11]
	v_mfma_f32_16x16x32_f16 v[4:7], v[160:163], v[232:235], v[4:7]
	s_barrier
	s_setprio 0
	s_add_i32 s17, s17, 2
	s_add_u32 s0, s0, 0x100
	s_addc_u32 s1, s1, 0
	s_add_u32 s15, s15, 0x100
	s_addc_u32 s16, s16, 0
	s_cmp_gt_u32 s17, 29
	s_cbranch_scc0 .LBB0_1708
	s_and_b64 vcc, exec, s[54:55]
	s_cbranch_vccz .LBB0_1711
	s_barrier

; #define PG8_STAGE(bufoff, gbase, voff) do { _Pragma("unroll") for (int _i = 0; _i < 2; ++_i) \
;         __builtin_amdgcn_global_load_lds((const unsigned*)((const char*)(gbase) + (voff)[_i]), (LAS unsigned*)(lds + (bufoff) + ldsw + _i * 8192), 16, 0, 0); } while (0)
; #define PG8_LDA(dst, b, h) do { _Pragma("unroll") for (int m = 0; m < 4; ++m) _Pragma("unroll") for (int k = 0; k < 2; ++k) dst[m][k] = *(const LAS half8*)(lds + PG8_SA(b, h) + aoff + m * 2048 + k * 1024); } while (0)
; #define PG8_LDB(dst, b, h) do { _Pragma("unroll") for (int n = 0; n < 2; ++n) _Pragma("unroll") for (int k = 0; k < 2; ++k) dst[n][k] = *(const LAS half8*)(lds + PG8_SB(b, h) + boff + n * 2048 + k * 1024); } while (0)
; #define PG8_MMA(ai, bj, At, Bt) do { __builtin_amdgcn_s_setprio(1); _Pragma("unroll") for (int m = 0; m < 4; ++m) _Pragma("unroll") for (int n = 0; n < 2; ++n) _Pragma("unroll") for (int k = 0; k < 2; ++k) \
;         acc[ai][bj][m][n] = __builtin_amdgcn_mfma_f32_16x16x32_f16(Bt[n][k], At[m][k], acc[ai][bj][m][n], 0, 0, 0); __builtin_amdgcn_s_setprio(0); } while (0)
; #define PG8_WAIT_V(n) asm volatile("s_waitcnt vmcnt(" #n ")" ::: "memory")
; template <class Epi, class Sched, bool ALIGN_EPI = false, bool SP2 = false>
; __device__ __forceinline__ void gemm_phase(LAS unsigned char* lds, const Gemm g, const Sched& S, const Epi& E) {
;     ...
;             PG8_LDB(B0, 0, 0); PG8_LDB(B1, 0, 1); PG8_SCHED; PG8_LDA(At, 0, 0); PG8_STAGE(PG8_SA(1, 1), a1 + hstepA, voffA);
;             PG8_WAIT_V(8); PG8_WAIT_L(0); PG8_BAR; PG8_MMA(0, 0, At, B0); PG8_MMA(0, 1, At, B1); PG8_BAR; PG8_SCHED;
;             PG8_LDA(At, 0, 1); PG8_STAGE(PG8_SB(0, 0), b2, voffB); PG8_STAGE(PG8_SB(0, 1), b2 + hstepB, voffB); PG8_STAGE(PG8_SA(0, 0), a2, voffA);
;             PG8_WAIT_V(8); PG8_WAIT_L(0); PG8_BAR; PG8_MMA(1, 0, At, B0); PG8_MMA(1, 1, At, B1); PG8_BAR; PG8_SCHED;
;             PG8_LDB(B0, 1, 0); PG8_LDB(B1, 1, 1); PG8_SCHED; PG8_LDA(At, 1, 0); PG8_STAGE(PG8_SA(0, 1), a2 + hstepA, voffA);
;             PG8_WAIT_V(8); PG8_WAIT_L(0); PG8_BAR; PG8_MMA(0, 0, At, B0); PG8_MMA(0, 1, At, B1); PG8_BAR; PG8_SCHED;
;             PG8_LDA(At, 1, 1); PG8_STAGE(PG8_SB(1, 0), b3, voffB); PG8_STAGE(PG8_SB(1, 1), b3 + hstepB, voffB); PG8_STAGE(PG8_SA(1, 0), a3, voffA);
;             PG8_WAIT_V(8); PG8_WAIT_L(0); PG8_BAR; PG8_MMA(1, 0, At, B0); PG8_MMA(1, 1, At, B1); PG8_BAR; PG8_SCHED;
.LBB0_2222:
	s_add_u32 s14, s62, s12
	s_addc_u32 s15, s63, s13
	s_add_u32 s14, s14, 0x100
	s_addc_u32 s15, s15, 0
	s_add_u32 s65, s2, s12
	s_addc_u32 s66, s59, s13
	s_add_i32 s67, 0, 0x10000
	s_cmpk_eq_i32 s12, 0x300
	s_cselect_b32 s17, s11, s15
	s_cselect_b32 s16, s10, s14
	v_add_u32_e32 v145, s67, v143
	s_cselect_b32 s15, s9, s66
	s_cselect_b32 s14, s8, s65
	s_add_i32 s65, 0, 0x14000
	ds_read_b128 v[146:149], v145
	ds_read_b128 v[150:153], v145 offset:1024
	ds_read_b128 v[154:157], v145 offset:2048
	ds_read_b128 v[158:161], v145 offset:3072
	v_add_u32_e32 v145, s65, v143
	ds_read_b128 v[162:165], v145
	ds_read_b128 v[166:169], v145 offset:1024
	ds_read_b128 v[170:173], v145 offset:2048
	ds_read_b128 v[174:177], v145 offset:3072
	v_lshl_add_u64 v[194:195], v[138:139], 0, s[12:13]
	s_add_i32 m0, s37, 0xc000
	ds_read_b128 v[178:181], v144
	ds_read_b128 v[182:185], v144 offset:1024
	ds_read_b128 v[186:189], v144 offset:2048
	ds_read_b128 v[190:193], v144 offset:3072
	ds_read_b128 v[204:207], v144 offset:4096
	ds_read_b128 v[220:223], v144 offset:5120
	ds_read_b128 v[224:227], v144 offset:6144
	ds_read_b128 v[228:231], v144 offset:7168
	global_load_lds_dwordx4 v[194:195], off
	v_lshl_add_u64 v[194:195], v[140:141], 0, s[12:13]
	s_add_i32 m0, s37, 0xe000
	s_nop 0
	global_load_lds_dwordx4 v[194:195], off
	s_waitcnt vmcnt(8)
	s_waitcnt lgkmcnt(0)
	s_setprio 1
	s_barrier
	v_mfma_f32_16x16x32_f16 v[128:131], v[146:149], v[178:181], v[128:131]
	v_mfma_f32_16x16x32_f16 v[124:127], v[154:157], v[178:181], v[124:127]
	v_mfma_f32_16x16x32_f16 v[120:123], v[146:149], v[186:189], v[120:123]
	v_mfma_f32_16x16x32_f16 v[116:119], v[154:157], v[186:189], v[116:119]
	v_mfma_f32_16x16x32_f16 v[108:111], v[146:149], v[204:207], v[108:111]
	v_mfma_f32_16x16x32_f16 v[100:103], v[154:157], v[204:207], v[100:103]
	v_mfma_f32_16x16x32_f16 v[92:95], v[146:149], v[224:227], v[92:95]
	v_mfma_f32_16x16x32_f16 v[84:87], v[154:157], v[224:227], v[84:87]
	v_mfma_f32_16x16x32_f16 v[128:131], v[150:153], v[182:185], v[128:131]
	v_mfma_f32_16x16x32_f16 v[124:127], v[158:161], v[182:185], v[124:127]
	v_mfma_f32_16x16x32_f16 v[120:123], v[150:153], v[190:193], v[120:123]
	v_mfma_f32_16x16x32_f16 v[116:119], v[158:161], v[190:193], v[116:119]
	v_mfma_f32_16x16x32_f16 v[108:111], v[150:153], v[220:223], v[108:111]
	v_mfma_f32_16x16x32_f16 v[100:103], v[158:161], v[220:223], v[100:103]
	v_mfma_f32_16x16x32_f16 v[92:95], v[150:153], v[228:231], v[92:95]
	v_mfma_f32_16x16x32_f16 v[84:87], v[158:161], v[228:231], v[84:87]
	v_mfma_f32_16x16x32_f16 v[112:115], v[162:165], v[178:181], v[112:115]
	v_mfma_f32_16x16x32_f16 v[104:107], v[170:173], v[178:181], v[104:107]
	v_mfma_f32_16x16x32_f16 v[96:99], v[162:165], v[186:189], v[96:99]
	v_mfma_f32_16x16x32_f16 v[88:91], v[170:173], v[186:189], v[88:91]
	v_mfma_f32_16x16x32_f16 v[80:83], v[162:165], v[204:207], v[80:83]
	v_mfma_f32_16x16x32_f16 v[76:79], v[170:173], v[204:207], v[76:79]
	v_mfma_f32_16x16x32_f16 v[72:75], v[162:165], v[224:227], v[72:75]
	v_mfma_f32_16x16x32_f16 v[68:71], v[170:173], v[224:227], v[68:71]
	v_mfma_f32_16x16x32_f16 v[112:115], v[166:169], v[182:185], v[112:115]
	v_mfma_f32_16x16x32_f16 v[104:107], v[174:177], v[182:185], v[104:107]
	v_mfma_f32_16x16x32_f16 v[96:99], v[166:169], v[190:193], v[96:99]
	v_mfma_f32_16x16x32_f16 v[88:91], v[174:177], v[190:193], v[88:91]
	v_mfma_f32_16x16x32_f16 v[80:83], v[166:169], v[220:223], v[80:83]
	v_mfma_f32_16x16x32_f16 v[76:79], v[174:177], v[220:223], v[76:79]
	v_mfma_f32_16x16x32_f16 v[72:75], v[166:169], v[228:231], v[72:75]
	v_mfma_f32_16x16x32_f16 v[68:71], v[174:177], v[228:231], v[68:71]
	s_barrier
	s_setprio 0
	s_add_i32 s66, s67, s25
	v_lshl_add_u64 v[194:195], s[14:15], 0, v[2:3]
	s_mov_b32 m0, s66
	ds_read_b128 v[178:181], v144 offset:16384
	ds_read_b128 v[182:185], v144 offset:17408
	ds_read_b128 v[186:189], v144 offset:18432
	ds_read_b128 v[190:193], v144 offset:19456
	ds_read_b128 v[204:207], v144 offset:20480
	ds_read_b128 v[220:223], v144 offset:21504
	ds_read_b128 v[224:227], v144 offset:22528
	ds_read_b128 v[228:231], v144 offset:23552
	global_load_lds_dwordx4 v[194:195], off
	s_add_i32 m0, s66, 0x2000
	s_add_u32 s66, s14, 0x80000
	v_lshl_add_u64 v[196:197], s[14:15], 0, v[132:133]
	s_addc_u32 s67, s15, 0
	s_add_i32 s65, s65, s25
	global_load_lds_dwordx4 v[196:197], off
	v_lshl_add_u64 v[208:209], s[66:67], 0, v[2:3]
	s_mov_b32 m0, s65
	v_lshl_add_u64 v[232:233], s[16:17], 0, v[134:135]
	global_load_lds_dwordx4 v[208:209], off
	v_lshl_add_u64 v[208:209], s[66:67], 0, v[132:133]
	s_add_i32 m0, s65, 0x2000
	s_nop 0
	global_load_lds_dwordx4 v[208:209], off
	v_lshl_add_u64 v[208:209], s[16:17], 0, v[136:137]
	s_mov_b32 m0, s37
	s_nop 0
	global_load_lds_dwordx4 v[208:209], off
	s_mov_b32 m0, s38
	s_nop 0
	global_load_lds_dwordx4 v[232:233], off
	s_waitcnt vmcnt(8)
	s_waitcnt lgkmcnt(0)
	s_setprio 1
	s_barrier
; #define PG8_STAGE(bufoff, gbase, voff) do { _Pragma("unroll") for (int _i = 0; _i < 2; ++_i) \
;         __builtin_amdgcn_global_load_lds((const unsigned*)((const char*)(gbase) + (voff)[_i]), (LAS unsigned*)(lds + (bufoff) + ldsw + _i * 8192), 16, 0, 0); } while (0)
; #define PG8_LDA(dst, b, h) do { _Pragma("unroll") for (int m = 0; m < 4; ++m) _Pragma("unroll") for (int k = 0; k < 2; ++k) dst[m][k] = *(const LAS half8*)(lds + PG8_SA(b, h) + aoff + m * 2048 + k * 1024); } while (0)
; #define PG8_LDB(dst, b, h) do { _Pragma("unroll") for (int n = 0; n < 2; ++n) _Pragma("unroll") for (int k = 0; k < 2; ++k) dst[n][k] = *(const LAS half8*)(lds + PG8_SB(b, h) + boff + n * 2048 + k * 1024); } while (0)
; #define PG8_MMA(ai, bj, At, Bt) do { __builtin_amdgcn_s_setprio(1); _Pragma("unroll") for (int m = 0; m < 4; ++m) _Pragma("unroll") for (int n = 0; n < 2; ++n) _Pragma("unroll") for (int k = 0; k < 2; ++k) \
;         acc[ai][bj][m][n] = __builtin_amdgcn_mfma_f32_16x16x32_f16(Bt[n][k], At[m][k], acc[ai][bj][m][n], 0, 0, 0); __builtin_amdgcn_s_setprio(0); } while (0)
; #define PG8_WAIT_V(n) asm volatile("s_waitcnt vmcnt(" #n ")" ::: "memory")
; template <class Epi, class Sched, bool ALIGN_EPI = false, bool SP2 = false>
; __device__ __forceinline__ void gemm_phase(LAS unsigned char* lds, const Gemm g, const Sched& S, const Epi& E) {
;     ...
;             PG8_LDB(B0, 0, 0); PG8_LDB(B1, 0, 1); PG8_SCHED; PG8_LDA(At, 0, 0); PG8_STAGE(PG8_SA(1, 1), a1 + hstepA, voffA);
;             PG8_WAIT_V(8); PG8_WAIT_L(0); PG8_BAR; PG8_MMA(0, 0, At, B0); PG8_MMA(0, 1, At, B1); PG8_BAR; PG8_SCHED;
;             PG8_LDA(At, 0, 1); PG8_STAGE(PG8_SB(0, 0), b2, voffB); PG8_STAGE(PG8_SB(0, 1), b2 + hstepB, voffB); PG8_STAGE(PG8_SA(0, 0), a2, voffA);
;             PG8_WAIT_V(8); PG8_WAIT_L(0); PG8_BAR; PG8_MMA(1, 0, At, B0); PG8_MMA(1, 1, At, B1); PG8_BAR; PG8_SCHED;
;             PG8_LDB(B0, 1, 0); PG8_LDB(B1, 1, 1); PG8_SCHED; PG8_LDA(At, 1, 0); PG8_STAGE(PG8_SA(0, 1), a2 + hstepA, voffA);
;             PG8_WAIT_V(8); PG8_WAIT_L(0); PG8_BAR; PG8_MMA(0, 0, At, B0); PG8_MMA(0, 1, At, B1); PG8_BAR; PG8_SCHED;
;             PG8_LDA(At, 1, 1); PG8_STAGE(PG8_SB(1, 0), b3, voffB); PG8_STAGE(PG8_SB(1, 1), b3 + hstepB, voffB); PG8_STAGE(PG8_SA(1, 0), a3, voffA);
;             PG8_WAIT_V(8); PG8_WAIT_L(0); PG8_BAR; PG8_MMA(1, 0, At, B0); PG8_MMA(1, 1, At, B1); PG8_BAR; PG8_SCHED;
	v_mfma_f32_16x16x32_f16 v[64:67], v[146:149], v[178:181], v[64:67]
	v_mfma_f32_16x16x32_f16 v[60:63], v[154:157], v[178:181], v[60:63]
	v_mfma_f32_16x16x32_f16 v[56:59], v[146:149], v[186:189], v[56:59]
	v_mfma_f32_16x16x32_f16 v[52:55], v[154:157], v[186:189], v[52:55]
	v_mfma_f32_16x16x32_f16 v[44:47], v[146:149], v[204:207], v[44:47]
	v_mfma_f32_16x16x32_f16 v[36:39], v[154:157], v[204:207], v[36:39]
	v_mfma_f32_16x16x32_f16 v[28:31], v[146:149], v[224:227], v[28:31]
	v_mfma_f32_16x16x32_f16 v[20:23], v[154:157], v[224:227], v[20:23]
	v_mfma_f32_16x16x32_f16 v[64:67], v[150:153], v[182:185], v[64:67]
	v_mfma_f32_16x16x32_f16 v[60:63], v[158:161], v[182:185], v[60:63]
	v_mfma_f32_16x16x32_f16 v[56:59], v[150:153], v[190:193], v[56:59]
	v_mfma_f32_16x16x32_f16 v[52:55], v[158:161], v[190:193], v[52:55]
	v_mfma_f32_16x16x32_f16 v[44:47], v[150:153], v[220:223], v[44:47]
	v_mfma_f32_16x16x32_f16 v[36:39], v[158:161], v[220:223], v[36:39]
	v_mfma_f32_16x16x32_f16 v[28:31], v[150:153], v[228:231], v[28:31]
	v_mfma_f32_16x16x32_f16 v[20:23], v[158:161], v[228:231], v[20:23]
	v_mfma_f32_16x16x32_f16 v[48:51], v[162:165], v[178:181], v[48:51]
	v_mfma_f32_16x16x32_f16 v[40:43], v[170:173], v[178:181], v[40:43]
	v_mfma_f32_16x16x32_f16 v[32:35], v[162:165], v[186:189], v[32:35]
	v_mfma_f32_16x16x32_f16 v[24:27], v[170:173], v[186:189], v[24:27]
	v_mfma_f32_16x16x32_f16 v[16:19], v[162:165], v[204:207], v[16:19]
	v_mfma_f32_16x16x32_f16 v[12:15], v[170:173], v[204:207], v[12:15]
	v_mfma_f32_16x16x32_f16 v[8:11], v[162:165], v[224:227], v[8:11]
	v_mfma_f32_16x16x32_f16 v[4:7], v[170:173], v[224:227], v[4:7]
	v_mfma_f32_16x16x32_f16 v[48:51], v[166:169], v[182:185], v[48:51]
	v_mfma_f32_16x16x32_f16 v[40:43], v[174:177], v[182:185], v[40:43]
	v_mfma_f32_16x16x32_f16 v[32:35], v[166:169], v[190:193], v[32:35]
	v_mfma_f32_16x16x32_f16 v[24:27], v[174:177], v[190:193], v[24:27]
	v_mfma_f32_16x16x32_f16 v[16:19], v[166:169], v[220:223], v[16:19]
	v_mfma_f32_16x16x32_f16 v[12:15], v[174:177], v[220:223], v[12:15]
	v_mfma_f32_16x16x32_f16 v[8:11], v[166:169], v[228:231], v[8:11]
	v_mfma_f32_16x16x32_f16 v[4:7], v[174:177], v[228:231], v[4:7]
	s_barrier
	s_setprio 0
	s_add_i32 s65, 0, 0x18000
	v_add_u32_e32 v145, s65, v143
	s_add_i32 s66, 0, 0x1c000
	ds_read_b128 v[146:149], v145
	ds_read_b128 v[150:153], v145 offset:1024
	ds_read_b128 v[154:157], v145 offset:2048
	ds_read_b128 v[158:161], v145 offset:3072
	v_add_u32_e32 v145, s66, v143
	ds_read_b128 v[162:165], v145
	ds_read_b128 v[166:169], v145 offset:1024
	ds_read_b128 v[170:173], v145 offset:2048
	ds_read_b128 v[174:177], v145 offset:3072
	s_add_u32 s16, s16, 0x80000
	s_addc_u32 s17, s17, 0
	s_mov_b32 m0, s39
	v_lshl_add_u64 v[234:235], s[16:17], 0, v[136:137]
	ds_read_b128 v[178:181], v144 offset:32768
	ds_read_b128 v[182:185], v144 offset:33792
	ds_read_b128 v[186:189], v144 offset:34816
	ds_read_b128 v[190:193], v144 offset:35840
	ds_read_b128 v[204:207], v144 offset:36864
	ds_read_b128 v[220:223], v144 offset:37888
	ds_read_b128 v[224:227], v144 offset:38912
	ds_read_b128 v[228:231], v144 offset:39936
	global_load_lds_dwordx4 v[234:235], off
	v_lshl_add_u64 v[234:235], s[16:17], 0, v[134:135]
	s_mov_b32 m0, s57
	s_nop 0
	global_load_lds_dwordx4 v[234:235], off
	s_waitcnt vmcnt(8)
	s_waitcnt lgkmcnt(0)
	s_setprio 1
	s_barrier
	v_mfma_f32_16x16x32_f16 v[128:131], v[146:149], v[178:181], v[128:131]
	v_mfma_f32_16x16x32_f16 v[124:127], v[154:157], v[178:181], v[124:127]
	v_mfma_f32_16x16x32_f16 v[120:123], v[146:149], v[186:189], v[120:123]
	v_mfma_f32_16x16x32_f16 v[116:119], v[154:157], v[186:189], v[116:119]
	v_mfma_f32_16x16x32_f16 v[108:111], v[146:149], v[204:207], v[108:111]
	v_mfma_f32_16x16x32_f16 v[100:103], v[154:157], v[204:207], v[100:103]
	v_mfma_f32_16x16x32_f16 v[92:95], v[146:149], v[224:227], v[92:95]
	v_mfma_f32_16x16x32_f16 v[84:87], v[154:157], v[224:227], v[84:87]
	v_mfma_f32_16x16x32_f16 v[128:131], v[150:153], v[182:185], v[128:131]
	v_mfma_f32_16x16x32_f16 v[124:127], v[158:161], v[182:185], v[124:127]
	v_mfma_f32_16x16x32_f16 v[120:123], v[150:153], v[190:193], v[120:123]
	v_mfma_f32_16x16x32_f16 v[116:119], v[158:161], v[190:193], v[116:119]
	v_mfma_f32_16x16x32_f16 v[108:111], v[150:153], v[220:223], v[108:111]
	v_mfma_f32_16x16x32_f16 v[100:103], v[158:161], v[220:223], v[100:103]
	v_mfma_f32_16x16x32_f16 v[92:95], v[150:153], v[228:231], v[92:95]
	v_mfma_f32_16x16x32_f16 v[84:87], v[158:161], v[228:231], v[84:87]
	v_mfma_f32_16x16x32_f16 v[112:115], v[162:165], v[178:181], v[112:115]
	v_mfma_f32_16x16x32_f16 v[104:107], v[170:173], v[178:181], v[104:107]
	v_mfma_f32_16x16x32_f16 v[96:99], v[162:165], v[186:189], v[96:99]
	v_mfma_f32_16x16x32_f16 v[88:91], v[170:173], v[186:189], v[88:91]
	v_mfma_f32_16x16x32_f16 v[80:83], v[162:165], v[204:207], v[80:83]
	v_mfma_f32_16x16x32_f16 v[76:79], v[170:173], v[204:207], v[76:79]
	v_mfma_f32_16x16x32_f16 v[72:75], v[162:165], v[224:227], v[72:75]
	v_mfma_f32_16x16x32_f16 v[68:71], v[170:173], v[224:227], v[68:71]
	v_mfma_f32_16x16x32_f16 v[112:115], v[166:169], v[182:185], v[112:115]
	v_mfma_f32_16x16x32_f16 v[104:107], v[174:177], v[182:185], v[104:107]
	v_mfma_f32_16x16x32_f16 v[96:99], v[166:169], v[190:193], v[96:99]
	v_mfma_f32_16x16x32_f16 v[88:91], v[174:177], v[190:193], v[88:91]
	v_mfma_f32_16x16x32_f16 v[80:83], v[166:169], v[220:223], v[80:83]
	v_mfma_f32_16x16x32_f16 v[76:79], v[174:177], v[220:223], v[76:79]
	v_mfma_f32_16x16x32_f16 v[72:75], v[166:169], v[228:231], v[72:75]
	v_mfma_f32_16x16x32_f16 v[68:71], v[174:177], v[228:231], v[68:71]
	s_barrier
; #define PG8_STAGE(bufoff, gbase, voff) do { _Pragma("unroll") for (int _i = 0; _i < 2; ++_i) \
;         __builtin_amdgcn_global_load_lds((const unsigned*)((const char*)(gbase) + (voff)[_i]), (LAS unsigned*)(lds + (bufoff) + ldsw + _i * 8192), 16, 0, 0); } while (0)
; #define PG8_LDA(dst, b, h) do { _Pragma("unroll") for (int m = 0; m < 4; ++m) _Pragma("unroll") for (int k = 0; k < 2; ++k) dst[m][k] = *(const LAS half8*)(lds + PG8_SA(b, h) + aoff + m * 2048 + k * 1024); } while (0)
; #define PG8_MMA(ai, bj, At, Bt) do { __builtin_amdgcn_s_setprio(1); _Pragma("unroll") for (int m = 0; m < 4; ++m) _Pragma("unroll") for (int n = 0; n < 2; ++n) _Pragma("unroll") for (int k = 0; k < 2; ++k) \
;         acc[ai][bj][m][n] = __builtin_amdgcn_mfma_f32_16x16x32_f16(Bt[n][k], At[m][k], acc[ai][bj][m][n], 0, 0, 0); __builtin_amdgcn_s_setprio(0); } while (0)
; #define PG8_WAIT_V(n) asm volatile("s_waitcnt vmcnt(" #n ")" ::: "memory")
; #define PG8_WAIT_L(n) asm volatile("s_waitcnt lgkmcnt(" #n ")" ::: "memory")
; #define PG8_BAR __builtin_amdgcn_s_barrier()
; #define PG8_SCHED __builtin_amdgcn_sched_barrier(0)
; template <class Epi, class Sched, bool ALIGN_EPI = false, bool SP2 = false>
; __device__ __forceinline__ void gemm_phase(LAS unsigned char* lds, const Gemm g, const Sched& S, const Epi& E) {
;     ...
;             PG8_LDA(At, 1, 1); PG8_STAGE(PG8_SB(1, 0), b3, voffB); PG8_STAGE(PG8_SB(1, 1), b3 + hstepB, voffB); PG8_STAGE(PG8_SA(1, 0), a3, voffA);
;             PG8_WAIT_V(8); PG8_WAIT_L(0); PG8_BAR; PG8_MMA(1, 0, At, B0); PG8_MMA(1, 1, At, B1); PG8_BAR; PG8_SCHED;
	s_setprio 0
	s_add_i32 s16, s65, s25
	v_lshl_add_u64 v[194:195], v[194:195], 0, s[96:97]
	s_mov_b32 m0, s16
	ds_read_b128 v[178:181], v144 offset:49152
	ds_read_b128 v[182:185], v144 offset:50176
	ds_read_b128 v[186:189], v144 offset:51200
	ds_read_b128 v[190:193], v144 offset:52224
	ds_read_b128 v[204:207], v144 offset:53248
	ds_read_b128 v[220:223], v144 offset:54272
	ds_read_b128 v[224:227], v144 offset:55296
	ds_read_b128 v[228:231], v144 offset:56320
	global_load_lds_dwordx4 v[194:195], off
	s_add_i32 m0, s16, 0x2000
	s_add_u32 s14, s14, 0x80080
	v_lshl_add_u64 v[194:195], v[196:197], 0, s[96:97]
	s_addc_u32 s15, s15, 0
	s_add_i32 s16, s66, s25
	global_load_lds_dwordx4 v[194:195], off
	v_lshl_add_u64 v[194:195], s[14:15], 0, v[2:3]
	s_mov_b32 m0, s16
	s_nop 0
	global_load_lds_dwordx4 v[194:195], off
	v_lshl_add_u64 v[194:195], s[14:15], 0, v[132:133]
	s_add_i32 m0, s16, 0x2000
	s_nop 0
	global_load_lds_dwordx4 v[194:195], off
	v_lshl_add_u64 v[194:195], v[208:209], 0, s[96:97]
	s_mov_b32 m0, s60
	s_nop 0
	global_load_lds_dwordx4 v[194:195], off
	v_lshl_add_u64 v[194:195], v[232:233], 0, s[96:97]
	s_mov_b32 m0, s61
	s_nop 0
	global_load_lds_dwordx4 v[194:195], off
	s_waitcnt vmcnt(8)
	s_waitcnt lgkmcnt(0)
	s_setprio 1
	s_barrier
	v_mfma_f32_16x16x32_f16 v[64:67], v[146:149], v[178:181], v[64:67]
	v_mfma_f32_16x16x32_f16 v[60:63], v[154:157], v[178:181], v[60:63]
	v_mfma_f32_16x16x32_f16 v[56:59], v[146:149], v[186:189], v[56:59]
	v_mfma_f32_16x16x32_f16 v[52:55], v[154:157], v[186:189], v[52:55]
	v_mfma_f32_16x16x32_f16 v[44:47], v[146:149], v[204:207], v[44:47]
	v_mfma_f32_16x16x32_f16 v[36:39], v[154:157], v[204:207], v[36:39]
	v_mfma_f32_16x16x32_f16 v[28:31], v[146:149], v[224:227], v[28:31]
	v_mfma_f32_16x16x32_f16 v[20:23], v[154:157], v[224:227], v[20:23]
	v_mfma_f32_16x16x32_f16 v[64:67], v[150:153], v[182:185], v[64:67]
	v_mfma_f32_16x16x32_f16 v[60:63], v[158:161], v[182:185], v[60:63]
	v_mfma_f32_16x16x32_f16 v[56:59], v[150:153], v[190:193], v[56:59]
	v_mfma_f32_16x16x32_f16 v[52:55], v[158:161], v[190:193], v[52:55]
	v_mfma_f32_16x16x32_f16 v[44:47], v[150:153], v[220:223], v[44:47]
	v_mfma_f32_16x16x32_f16 v[36:39], v[158:161], v[220:223], v[36:39]
	v_mfma_f32_16x16x32_f16 v[28:31], v[150:153], v[228:231], v[28:31]
	v_mfma_f32_16x16x32_f16 v[20:23], v[158:161], v[228:231], v[20:23]
	v_mfma_f32_16x16x32_f16 v[48:51], v[162:165], v[178:181], v[48:51]
	v_mfma_f32_16x16x32_f16 v[40:43], v[170:173], v[178:181], v[40:43]
	v_mfma_f32_16x16x32_f16 v[32:35], v[162:165], v[186:189], v[32:35]
	v_mfma_f32_16x16x32_f16 v[24:27], v[170:173], v[186:189], v[24:27]
	v_mfma_f32_16x16x32_f16 v[16:19], v[162:165], v[204:207], v[16:19]
	v_mfma_f32_16x16x32_f16 v[12:15], v[170:173], v[204:207], v[12:15]
	v_mfma_f32_16x16x32_f16 v[8:11], v[162:165], v[224:227], v[8:11]
	v_mfma_f32_16x16x32_f16 v[4:7], v[170:173], v[224:227], v[4:7]
	v_mfma_f32_16x16x32_f16 v[48:51], v[166:169], v[182:185], v[48:51]
	v_mfma_f32_16x16x32_f16 v[40:43], v[174:177], v[182:185], v[40:43]
	v_mfma_f32_16x16x32_f16 v[32:35], v[166:169], v[190:193], v[32:35]
	v_mfma_f32_16x16x32_f16 v[24:27], v[174:177], v[190:193], v[24:27]
	v_mfma_f32_16x16x32_f16 v[16:19], v[166:169], v[220:223], v[16:19]
	v_mfma_f32_16x16x32_f16 v[12:15], v[174:177], v[220:223], v[12:15]
	v_mfma_f32_16x16x32_f16 v[8:11], v[166:169], v[228:231], v[8:11]
	v_mfma_f32_16x16x32_f16 v[4:7], v[174:177], v[228:231], v[4:7]
	s_barrier
	s_setprio 0
	s_add_i32 s64, s64, 2
	s_add_u32 s12, s12, 0x100
	s_addc_u32 s13, s13, 0
	s_cmp_gt_u32 s64, 5
	s_cbranch_scc0 .LBB0_2222
	s_cmpk_lt_u32 s1, 0x100
	s_cbranch_scc0 .LBB0_2225
	s_barrier

; #define PG8_STAGE(bufoff, gbase, voff) do { _Pragma("unroll") for (int _i = 0; _i < 2; ++_i) \
;         __builtin_amdgcn_global_load_lds((const unsigned*)((const char*)(gbase) + (voff)[_i]), (LAS unsigned*)(lds + (bufoff) + ldsw + _i * 8192), 16, 0, 0); } while (0)
; #define PG8_LDA(dst, b, h) do { _Pragma("unroll") for (int m = 0; m < 4; ++m) _Pragma("unroll") for (int k = 0; k < 2; ++k) dst[m][k] = *(const LAS half8*)(lds + PG8_SA(b, h) + aoff + m * 2048 + k * 1024); } while (0)
; #define PG8_LDB(dst, b, h) do { _Pragma("unroll") for (int n = 0; n < 2; ++n) _Pragma("unroll") for (int k = 0; k < 2; ++k) dst[n][k] = *(const LAS half8*)(lds + PG8_SB(b, h) + boff + n * 2048 + k * 1024); } while (0)
; #define PG8_MMA(ai, bj, At, Bt) do { __builtin_amdgcn_s_setprio(1); _Pragma("unroll") for (int m = 0; m < 4; ++m) _Pragma("unroll") for (int n = 0; n < 2; ++n) _Pragma("unroll") for (int k = 0; k < 2; ++k) \
;         acc[ai][bj][m][n] = __builtin_amdgcn_mfma_f32_16x16x32_f16(Bt[n][k], At[m][k], acc[ai][bj][m][n], 0, 0, 0); __builtin_amdgcn_s_setprio(0); } while (0)
; #define PG8_WAIT_V(n) asm volatile("s_waitcnt vmcnt(" #n ")" ::: "memory")
; #define PG8_WAIT_L(n) asm volatile("s_waitcnt lgkmcnt(" #n ")" ::: "memory")
; #define PG8_BAR __builtin_amdgcn_s_barrier()
; #define PG8_SCHED __builtin_amdgcn_sched_barrier(0)
; template <class Epi, class Sched, bool ALIGN_EPI = false, bool SP2 = false>
; __device__ __forceinline__ void gemm_phase(LAS unsigned char* lds, const Gemm g, const Sched& S, const Epi& E) {
;     ...
;             const char* a1 = cA + (size_t)(t + 1) * kstep;
;             const char* a2 = last ? nA : cA + (size_t)(t + 2) * kstep; const char* b2 = last ? nB : cB + (size_t)(t + 2) * kstep;
;             const char* a3 = a2 + kstep; const char* b3 = b2 + kstep;
;             if (last && has_next) S.a_ready(nxt);
;             if constexpr (SP2) {
;             PG8_LDB(B0, 0, 0); PG8_LDB(B1, 0, 1); PG8_SCHED; PG8_LDA(At, 0, 0); PG8_STAGE(PG8_SA(1, 1), a1 + hstepA, voffA);
;             PG8_WAIT_V(8); PG8_WAIT_L(0); PG8_BAR; PG8_MMA(0, 0, At, B0); PG8_MMA(0, 1, At, B1); PG8_BAR; PG8_SCHED;
;             PG8_LDA(At, 0, 1); PG8_STAGE(PG8_SB(0, 0), b2, voffB); PG8_STAGE(PG8_SB(0, 1), b2 + hstepB, voffB); PG8_STAGE(PG8_SA(0, 0), a2, voffA);
.LBB0_2230:
	s_add_u32 s10, s39, s8
	s_addc_u32 s11, s57, s9
	s_add_u32 s10, s10, 0x3e900100
	s_addc_u32 s11, s11, 0
	s_add_u32 s63, s58, s8
	s_addc_u32 s64, s59, s9
	s_add_i32 s65, 0, 0x10000
	s_cmpk_eq_i32 s8, 0x300
	s_cselect_b32 s13, s7, s11
	s_cselect_b32 s12, s6, s10
	v_add_u32_e32 v145, s65, v143
	s_cselect_b32 s11, s1, s64
	s_cselect_b32 s10, s0, s63
	s_add_i32 s63, 0, 0x14000
	ds_read_b128 v[146:149], v145
	ds_read_b128 v[150:153], v145 offset:1024
	ds_read_b128 v[154:157], v145 offset:2048
	ds_read_b128 v[158:161], v145 offset:3072
	v_add_u32_e32 v145, s63, v143
	ds_read_b128 v[162:165], v145
	ds_read_b128 v[166:169], v145 offset:1024
	ds_read_b128 v[170:173], v145 offset:2048
	ds_read_b128 v[174:177], v145 offset:3072
	v_lshl_add_u64 v[194:195], v[138:139], 0, s[8:9]
	s_add_i32 m0, s24, 0xc000
	ds_read_b128 v[178:181], v144
	ds_read_b128 v[182:185], v144 offset:1024
	ds_read_b128 v[186:189], v144 offset:2048
	ds_read_b128 v[190:193], v144 offset:3072
	ds_read_b128 v[204:207], v144 offset:4096
	ds_read_b128 v[220:223], v144 offset:5120
	ds_read_b128 v[224:227], v144 offset:6144
	ds_read_b128 v[228:231], v144 offset:7168
	global_load_lds_dwordx4 v[194:195], off
	v_lshl_add_u64 v[194:195], v[140:141], 0, s[8:9]
	s_add_i32 m0, s24, 0xe000
	s_nop 0
	global_load_lds_dwordx4 v[194:195], off
	s_waitcnt vmcnt(8)
	s_waitcnt lgkmcnt(0)
	s_setprio 1
	s_barrier
	v_mfma_f32_16x16x32_f16 v[128:131], v[146:149], v[178:181], v[128:131]
	v_mfma_f32_16x16x32_f16 v[124:127], v[154:157], v[178:181], v[124:127]
	v_mfma_f32_16x16x32_f16 v[112:115], v[146:149], v[186:189], v[112:115]
	v_mfma_f32_16x16x32_f16 v[108:111], v[154:157], v[186:189], v[108:111]
	v_mfma_f32_16x16x32_f16 v[96:99], v[146:149], v[204:207], v[96:99]
	v_mfma_f32_16x16x32_f16 v[92:95], v[154:157], v[204:207], v[92:95]
	v_mfma_f32_16x16x32_f16 v[80:83], v[146:149], v[224:227], v[80:83]
	v_mfma_f32_16x16x32_f16 v[76:79], v[154:157], v[224:227], v[76:79]
	v_mfma_f32_16x16x32_f16 v[128:131], v[150:153], v[182:185], v[128:131]
	v_mfma_f32_16x16x32_f16 v[124:127], v[158:161], v[182:185], v[124:127]
	v_mfma_f32_16x16x32_f16 v[112:115], v[150:153], v[190:193], v[112:115]
	v_mfma_f32_16x16x32_f16 v[108:111], v[158:161], v[190:193], v[108:111]
	v_mfma_f32_16x16x32_f16 v[96:99], v[150:153], v[220:223], v[96:99]
	v_mfma_f32_16x16x32_f16 v[92:95], v[158:161], v[220:223], v[92:95]
	v_mfma_f32_16x16x32_f16 v[80:83], v[150:153], v[228:231], v[80:83]
	v_mfma_f32_16x16x32_f16 v[76:79], v[158:161], v[228:231], v[76:79]
	v_mfma_f32_16x16x32_f16 v[120:123], v[162:165], v[178:181], v[120:123]
	v_mfma_f32_16x16x32_f16 v[116:119], v[170:173], v[178:181], v[116:119]
	v_mfma_f32_16x16x32_f16 v[104:107], v[162:165], v[186:189], v[104:107]
	v_mfma_f32_16x16x32_f16 v[100:103], v[170:173], v[186:189], v[100:103]
	v_mfma_f32_16x16x32_f16 v[88:91], v[162:165], v[204:207], v[88:91]
	v_mfma_f32_16x16x32_f16 v[84:87], v[170:173], v[204:207], v[84:87]
	v_mfma_f32_16x16x32_f16 v[72:75], v[162:165], v[224:227], v[72:75]
	v_mfma_f32_16x16x32_f16 v[68:71], v[170:173], v[224:227], v[68:71]
	v_mfma_f32_16x16x32_f16 v[120:123], v[166:169], v[182:185], v[120:123]
	v_mfma_f32_16x16x32_f16 v[116:119], v[174:177], v[182:185], v[116:119]
	v_mfma_f32_16x16x32_f16 v[104:107], v[166:169], v[190:193], v[104:107]
	v_mfma_f32_16x16x32_f16 v[100:103], v[174:177], v[190:193], v[100:103]
	v_mfma_f32_16x16x32_f16 v[88:91], v[166:169], v[220:223], v[88:91]
	v_mfma_f32_16x16x32_f16 v[84:87], v[174:177], v[220:223], v[84:87]
	v_mfma_f32_16x16x32_f16 v[72:75], v[166:169], v[228:231], v[72:75]
	v_mfma_f32_16x16x32_f16 v[68:71], v[174:177], v[228:231], v[68:71]
	s_barrier
	s_setprio 0
	s_add_i32 s64, s65, s17
	v_lshl_add_u64 v[194:195], s[10:11], 0, v[2:3]
	s_mov_b32 m0, s64
	ds_read_b128 v[178:181], v144 offset:16384
	ds_read_b128 v[182:185], v144 offset:17408
	ds_read_b128 v[186:189], v144 offset:18432
	ds_read_b128 v[190:193], v144 offset:19456
	ds_read_b128 v[204:207], v144 offset:20480
	ds_read_b128 v[220:223], v144 offset:21504
	ds_read_b128 v[224:227], v144 offset:22528
	ds_read_b128 v[228:231], v144 offset:23552
	global_load_lds_dwordx4 v[194:195], off
	s_add_i32 m0, s64, 0x2000
	s_add_u32 s64, s10, 0x20000
	v_lshl_add_u64 v[196:197], s[10:11], 0, v[132:133]
	s_addc_u32 s65, s11, 0
	s_add_i32 s63, s63, s17
	global_load_lds_dwordx4 v[196:197], off
	v_lshl_add_u64 v[208:209], s[64:65], 0, v[2:3]
	s_mov_b32 m0, s63
	v_lshl_add_u64 v[232:233], s[12:13], 0, v[134:135]
	global_load_lds_dwordx4 v[208:209], off
	v_lshl_add_u64 v[208:209], s[64:65], 0, v[132:133]
	s_add_i32 m0, s63, 0x2000
	s_nop 0
	global_load_lds_dwordx4 v[208:209], off
	v_lshl_add_u64 v[208:209], s[12:13], 0, v[136:137]
	s_mov_b32 m0, s24
	s_nop 0
	global_load_lds_dwordx4 v[208:209], off
	s_mov_b32 m0, s25
	s_nop 0
	global_load_lds_dwordx4 v[232:233], off
	s_waitcnt vmcnt(8)
	s_waitcnt lgkmcnt(0)
	s_setprio 1
	s_barrier
; #define PG8_STAGE(bufoff, gbase, voff) do { _Pragma("unroll") for (int _i = 0; _i < 2; ++_i) \
;         __builtin_amdgcn_global_load_lds((const unsigned*)((const char*)(gbase) + (voff)[_i]), (LAS unsigned*)(lds + (bufoff) + ldsw + _i * 8192), 16, 0, 0); } while (0)
; #define PG8_LDA(dst, b, h) do { _Pragma("unroll") for (int m = 0; m < 4; ++m) _Pragma("unroll") for (int k = 0; k < 2; ++k) dst[m][k] = *(const LAS half8*)(lds + PG8_SA(b, h) + aoff + m * 2048 + k * 1024); } while (0)
; #define PG8_LDB(dst, b, h) do { _Pragma("unroll") for (int n = 0; n < 2; ++n) _Pragma("unroll") for (int k = 0; k < 2; ++k) dst[n][k] = *(const LAS half8*)(lds + PG8_SB(b, h) + boff + n * 2048 + k * 1024); } while (0)
; #define PG8_MMA(ai, bj, At, Bt) do { __builtin_amdgcn_s_setprio(1); _Pragma("unroll") for (int m = 0; m < 4; ++m) _Pragma("unroll") for (int n = 0; n < 2; ++n) _Pragma("unroll") for (int k = 0; k < 2; ++k) \
;         acc[ai][bj][m][n] = __builtin_amdgcn_mfma_f32_16x16x32_f16(Bt[n][k], At[m][k], acc[ai][bj][m][n], 0, 0, 0); __builtin_amdgcn_s_setprio(0); } while (0)
; #define PG8_WAIT_V(n) asm volatile("s_waitcnt vmcnt(" #n ")" ::: "memory")
; #define PG8_WAIT_L(n) asm volatile("s_waitcnt lgkmcnt(" #n ")" ::: "memory")
; #define PG8_BAR __builtin_amdgcn_s_barrier()
; #define PG8_SCHED __builtin_amdgcn_sched_barrier(0)
; template <class Epi, class Sched, bool ALIGN_EPI = false, bool SP2 = false>
; __device__ __forceinline__ void gemm_phase(LAS unsigned char* lds, const Gemm g, const Sched& S, const Epi& E) {
;     ...
;             PG8_WAIT_V(8); PG8_WAIT_L(0); PG8_BAR; PG8_MMA(1, 0, At, B0); PG8_MMA(1, 1, At, B1); PG8_BAR; PG8_SCHED;
;             PG8_LDB(B0, 1, 0); PG8_LDB(B1, 1, 1); PG8_SCHED; PG8_LDA(At, 1, 0); PG8_STAGE(PG8_SA(0, 1), a2 + hstepA, voffA);
;             PG8_WAIT_V(8); PG8_WAIT_L(0); PG8_BAR; PG8_MMA(0, 0, At, B0); PG8_MMA(0, 1, At, B1); PG8_BAR; PG8_SCHED;
	v_mfma_f32_16x16x32_f16 v[64:67], v[146:149], v[178:181], v[64:67]
	v_mfma_f32_16x16x32_f16 v[60:63], v[154:157], v[178:181], v[60:63]
	v_mfma_f32_16x16x32_f16 v[48:51], v[146:149], v[186:189], v[48:51]
	v_mfma_f32_16x16x32_f16 v[44:47], v[154:157], v[186:189], v[44:47]
	v_mfma_f32_16x16x32_f16 v[32:35], v[146:149], v[204:207], v[32:35]
	v_mfma_f32_16x16x32_f16 v[28:31], v[154:157], v[204:207], v[28:31]
	v_mfma_f32_16x16x32_f16 v[16:19], v[146:149], v[224:227], v[16:19]
	v_mfma_f32_16x16x32_f16 v[12:15], v[154:157], v[224:227], v[12:15]
	v_mfma_f32_16x16x32_f16 v[64:67], v[150:153], v[182:185], v[64:67]
	v_mfma_f32_16x16x32_f16 v[60:63], v[158:161], v[182:185], v[60:63]
	v_mfma_f32_16x16x32_f16 v[48:51], v[150:153], v[190:193], v[48:51]
	v_mfma_f32_16x16x32_f16 v[44:47], v[158:161], v[190:193], v[44:47]
	v_mfma_f32_16x16x32_f16 v[32:35], v[150:153], v[220:223], v[32:35]
	v_mfma_f32_16x16x32_f16 v[28:31], v[158:161], v[220:223], v[28:31]
	v_mfma_f32_16x16x32_f16 v[16:19], v[150:153], v[228:231], v[16:19]
	v_mfma_f32_16x16x32_f16 v[12:15], v[158:161], v[228:231], v[12:15]
	v_mfma_f32_16x16x32_f16 v[56:59], v[162:165], v[178:181], v[56:59]
	v_mfma_f32_16x16x32_f16 v[52:55], v[170:173], v[178:181], v[52:55]
	v_mfma_f32_16x16x32_f16 v[40:43], v[162:165], v[186:189], v[40:43]
	v_mfma_f32_16x16x32_f16 v[36:39], v[170:173], v[186:189], v[36:39]
	v_mfma_f32_16x16x32_f16 v[24:27], v[162:165], v[204:207], v[24:27]
	v_mfma_f32_16x16x32_f16 v[20:23], v[170:173], v[204:207], v[20:23]
	v_mfma_f32_16x16x32_f16 v[8:11], v[162:165], v[224:227], v[8:11]
	v_mfma_f32_16x16x32_f16 v[4:7], v[170:173], v[224:227], v[4:7]
	v_mfma_f32_16x16x32_f16 v[56:59], v[166:169], v[182:185], v[56:59]
	v_mfma_f32_16x16x32_f16 v[52:55], v[174:177], v[182:185], v[52:55]
	v_mfma_f32_16x16x32_f16 v[40:43], v[166:169], v[190:193], v[40:43]
	v_mfma_f32_16x16x32_f16 v[36:39], v[174:177], v[190:193], v[36:39]
	v_mfma_f32_16x16x32_f16 v[24:27], v[166:169], v[220:223], v[24:27]
	v_mfma_f32_16x16x32_f16 v[20:23], v[174:177], v[220:223], v[20:23]
	v_mfma_f32_16x16x32_f16 v[8:11], v[166:169], v[228:231], v[8:11]
	v_mfma_f32_16x16x32_f16 v[4:7], v[174:177], v[228:231], v[4:7]
	s_barrier
	s_setprio 0
	s_add_i32 s63, 0, 0x18000
	v_add_u32_e32 v145, s63, v143
	s_add_i32 s64, 0, 0x1c000
	ds_read_b128 v[146:149], v145
	ds_read_b128 v[150:153], v145 offset:1024
	ds_read_b128 v[154:157], v145 offset:2048
	ds_read_b128 v[158:161], v145 offset:3072
	v_add_u32_e32 v145, s64, v143
	ds_read_b128 v[162:165], v145
	ds_read_b128 v[166:169], v145 offset:1024
	ds_read_b128 v[170:173], v145 offset:2048
	ds_read_b128 v[174:177], v145 offset:3072
	s_add_u32 s12, s12, 0x20000
	s_addc_u32 s13, s13, 0
	s_mov_b32 m0, s37
	v_lshl_add_u64 v[234:235], s[12:13], 0, v[136:137]
	ds_read_b128 v[178:181], v144 offset:32768
	ds_read_b128 v[182:185], v144 offset:33792
	ds_read_b128 v[186:189], v144 offset:34816
	ds_read_b128 v[190:193], v144 offset:35840
	ds_read_b128 v[204:207], v144 offset:36864
	ds_read_b128 v[220:223], v144 offset:37888
	ds_read_b128 v[224:227], v144 offset:38912
	ds_read_b128 v[228:231], v144 offset:39936
	global_load_lds_dwordx4 v[234:235], off
	v_lshl_add_u64 v[234:235], s[12:13], 0, v[134:135]
	s_mov_b32 m0, s38
	s_nop 0
	global_load_lds_dwordx4 v[234:235], off
	s_waitcnt vmcnt(8)
	s_waitcnt lgkmcnt(0)
	s_setprio 1
	s_barrier
	v_mfma_f32_16x16x32_f16 v[128:131], v[146:149], v[178:181], v[128:131]
	v_mfma_f32_16x16x32_f16 v[124:127], v[154:157], v[178:181], v[124:127]
	v_mfma_f32_16x16x32_f16 v[112:115], v[146:149], v[186:189], v[112:115]
	v_mfma_f32_16x16x32_f16 v[108:111], v[154:157], v[186:189], v[108:111]
	v_mfma_f32_16x16x32_f16 v[96:99], v[146:149], v[204:207], v[96:99]
	v_mfma_f32_16x16x32_f16 v[92:95], v[154:157], v[204:207], v[92:95]
	v_mfma_f32_16x16x32_f16 v[80:83], v[146:149], v[224:227], v[80:83]
	v_mfma_f32_16x16x32_f16 v[76:79], v[154:157], v[224:227], v[76:79]
	v_mfma_f32_16x16x32_f16 v[128:131], v[150:153], v[182:185], v[128:131]
	v_mfma_f32_16x16x32_f16 v[124:127], v[158:161], v[182:185], v[124:127]
	v_mfma_f32_16x16x32_f16 v[112:115], v[150:153], v[190:193], v[112:115]
	v_mfma_f32_16x16x32_f16 v[108:111], v[158:161], v[190:193], v[108:111]
	v_mfma_f32_16x16x32_f16 v[96:99], v[150:153], v[220:223], v[96:99]
	v_mfma_f32_16x16x32_f16 v[92:95], v[158:161], v[220:223], v[92:95]
	v_mfma_f32_16x16x32_f16 v[80:83], v[150:153], v[228:231], v[80:83]
	v_mfma_f32_16x16x32_f16 v[76:79], v[158:161], v[228:231], v[76:79]
	v_mfma_f32_16x16x32_f16 v[120:123], v[162:165], v[178:181], v[120:123]
	v_mfma_f32_16x16x32_f16 v[116:119], v[170:173], v[178:181], v[116:119]
	v_mfma_f32_16x16x32_f16 v[104:107], v[162:165], v[186:189], v[104:107]
	v_mfma_f32_16x16x32_f16 v[100:103], v[170:173], v[186:189], v[100:103]
	v_mfma_f32_16x16x32_f16 v[88:91], v[162:165], v[204:207], v[88:91]
	v_mfma_f32_16x16x32_f16 v[84:87], v[170:173], v[204:207], v[84:87]
	v_mfma_f32_16x16x32_f16 v[72:75], v[162:165], v[224:227], v[72:75]
	v_mfma_f32_16x16x32_f16 v[68:71], v[170:173], v[224:227], v[68:71]
	v_mfma_f32_16x16x32_f16 v[120:123], v[166:169], v[182:185], v[120:123]
	v_mfma_f32_16x16x32_f16 v[116:119], v[174:177], v[182:185], v[116:119]
	v_mfma_f32_16x16x32_f16 v[104:107], v[166:169], v[190:193], v[104:107]
	v_mfma_f32_16x16x32_f16 v[100:103], v[174:177], v[190:193], v[100:103]
	v_mfma_f32_16x16x32_f16 v[88:91], v[166:169], v[220:223], v[88:91]
	v_mfma_f32_16x16x32_f16 v[84:87], v[174:177], v[220:223], v[84:87]
	v_mfma_f32_16x16x32_f16 v[72:75], v[166:169], v[228:231], v[72:75]
	v_mfma_f32_16x16x32_f16 v[68:71], v[174:177], v[228:231], v[68:71]
	s_barrier
; #define PG8_STAGE(bufoff, gbase, voff) do { _Pragma("unroll") for (int _i = 0; _i < 2; ++_i) \
;         __builtin_amdgcn_global_load_lds((const unsigned*)((const char*)(gbase) + (voff)[_i]), (LAS unsigned*)(lds + (bufoff) + ldsw + _i * 8192), 16, 0, 0); } while (0)
; #define PG8_LDA(dst, b, h) do { _Pragma("unroll") for (int m = 0; m < 4; ++m) _Pragma("unroll") for (int k = 0; k < 2; ++k) dst[m][k] = *(const LAS half8*)(lds + PG8_SA(b, h) + aoff + m * 2048 + k * 1024); } while (0)
; #define PG8_MMA(ai, bj, At, Bt) do { __builtin_amdgcn_s_setprio(1); _Pragma("unroll") for (int m = 0; m < 4; ++m) _Pragma("unroll") for (int n = 0; n < 2; ++n) _Pragma("unroll") for (int k = 0; k < 2; ++k) \
;         acc[ai][bj][m][n] = __builtin_amdgcn_mfma_f32_16x16x32_f16(Bt[n][k], At[m][k], acc[ai][bj][m][n], 0, 0, 0); __builtin_amdgcn_s_setprio(0); } while (0)
; #define PG8_WAIT_V(n) asm volatile("s_waitcnt vmcnt(" #n ")" ::: "memory")
; #define PG8_WAIT_L(n) asm volatile("s_waitcnt lgkmcnt(" #n ")" ::: "memory")
; #define PG8_BAR __builtin_amdgcn_s_barrier()
; #define PG8_SCHED __builtin_amdgcn_sched_barrier(0)
; template <class Epi, class Sched, bool ALIGN_EPI = false, bool SP2 = false>
; __device__ __forceinline__ void gemm_phase(LAS unsigned char* lds, const Gemm g, const Sched& S, const Epi& E) {
;     ...
;             PG8_LDA(At, 1, 1); PG8_STAGE(PG8_SB(1, 0), b3, voffB); PG8_STAGE(PG8_SB(1, 1), b3 + hstepB, voffB); PG8_STAGE(PG8_SA(1, 0), a3, voffA);
;             PG8_WAIT_V(8); PG8_WAIT_L(0); PG8_BAR; PG8_MMA(1, 0, At, B0); PG8_MMA(1, 1, At, B1); PG8_BAR; PG8_SCHED;
	s_setprio 0
	s_add_i32 s12, s63, s17
	v_lshl_add_u64 v[194:195], v[194:195], 0, s[96:97]
	s_mov_b32 m0, s12
	ds_read_b128 v[178:181], v144 offset:49152
	ds_read_b128 v[182:185], v144 offset:50176
	ds_read_b128 v[186:189], v144 offset:51200
	ds_read_b128 v[190:193], v144 offset:52224
	ds_read_b128 v[204:207], v144 offset:53248
	ds_read_b128 v[220:223], v144 offset:54272
	ds_read_b128 v[224:227], v144 offset:55296
	ds_read_b128 v[228:231], v144 offset:56320
	global_load_lds_dwordx4 v[194:195], off
	s_add_i32 m0, s12, 0x2000
	s_add_u32 s10, s10, 0x20080
	v_lshl_add_u64 v[194:195], v[196:197], 0, s[96:97]
	s_addc_u32 s11, s11, 0
	s_add_i32 s12, s64, s17
	global_load_lds_dwordx4 v[194:195], off
	v_lshl_add_u64 v[194:195], s[10:11], 0, v[2:3]
	s_mov_b32 m0, s12
	s_nop 0
	global_load_lds_dwordx4 v[194:195], off
	v_lshl_add_u64 v[194:195], s[10:11], 0, v[132:133]
	s_add_i32 m0, s12, 0x2000
	s_nop 0
	global_load_lds_dwordx4 v[194:195], off
	v_lshl_add_u64 v[194:195], v[208:209], 0, s[96:97]
	s_mov_b32 m0, s60
	s_nop 0
	global_load_lds_dwordx4 v[194:195], off
	v_lshl_add_u64 v[194:195], v[232:233], 0, s[96:97]
	s_mov_b32 m0, s61
	s_nop 0
	global_load_lds_dwordx4 v[194:195], off
	s_waitcnt vmcnt(8)
	s_waitcnt lgkmcnt(0)
	s_setprio 1
	s_barrier
	v_mfma_f32_16x16x32_f16 v[64:67], v[146:149], v[178:181], v[64:67]
	v_mfma_f32_16x16x32_f16 v[60:63], v[154:157], v[178:181], v[60:63]
	v_mfma_f32_16x16x32_f16 v[48:51], v[146:149], v[186:189], v[48:51]
	v_mfma_f32_16x16x32_f16 v[44:47], v[154:157], v[186:189], v[44:47]
	v_mfma_f32_16x16x32_f16 v[32:35], v[146:149], v[204:207], v[32:35]
	v_mfma_f32_16x16x32_f16 v[28:31], v[154:157], v[204:207], v[28:31]
	v_mfma_f32_16x16x32_f16 v[16:19], v[146:149], v[224:227], v[16:19]
	v_mfma_f32_16x16x32_f16 v[12:15], v[154:157], v[224:227], v[12:15]
	v_mfma_f32_16x16x32_f16 v[64:67], v[150:153], v[182:185], v[64:67]
	v_mfma_f32_16x16x32_f16 v[60:63], v[158:161], v[182:185], v[60:63]
	v_mfma_f32_16x16x32_f16 v[48:51], v[150:153], v[190:193], v[48:51]
	v_mfma_f32_16x16x32_f16 v[44:47], v[158:161], v[190:193], v[44:47]
	v_mfma_f32_16x16x32_f16 v[32:35], v[150:153], v[220:223], v[32:35]
	v_mfma_f32_16x16x32_f16 v[28:31], v[158:161], v[220:223], v[28:31]
	v_mfma_f32_16x16x32_f16 v[16:19], v[150:153], v[228:231], v[16:19]
	v_mfma_f32_16x16x32_f16 v[12:15], v[158:161], v[228:231], v[12:15]
	v_mfma_f32_16x16x32_f16 v[56:59], v[162:165], v[178:181], v[56:59]
	v_mfma_f32_16x16x32_f16 v[52:55], v[170:173], v[178:181], v[52:55]
	v_mfma_f32_16x16x32_f16 v[40:43], v[162:165], v[186:189], v[40:43]
	v_mfma_f32_16x16x32_f16 v[36:39], v[170:173], v[186:189], v[36:39]
	v_mfma_f32_16x16x32_f16 v[24:27], v[162:165], v[204:207], v[24:27]
	v_mfma_f32_16x16x32_f16 v[20:23], v[170:173], v[204:207], v[20:23]
	v_mfma_f32_16x16x32_f16 v[8:11], v[162:165], v[224:227], v[8:11]
	v_mfma_f32_16x16x32_f16 v[4:7], v[170:173], v[224:227], v[4:7]
	v_mfma_f32_16x16x32_f16 v[56:59], v[166:169], v[182:185], v[56:59]
	v_mfma_f32_16x16x32_f16 v[52:55], v[174:177], v[182:185], v[52:55]
	v_mfma_f32_16x16x32_f16 v[40:43], v[166:169], v[190:193], v[40:43]
	v_mfma_f32_16x16x32_f16 v[36:39], v[174:177], v[190:193], v[36:39]
	v_mfma_f32_16x16x32_f16 v[24:27], v[166:169], v[220:223], v[24:27]
	v_mfma_f32_16x16x32_f16 v[20:23], v[174:177], v[220:223], v[20:23]
	v_mfma_f32_16x16x32_f16 v[8:11], v[166:169], v[228:231], v[8:11]
	v_mfma_f32_16x16x32_f16 v[4:7], v[174:177], v[228:231], v[4:7]
	s_barrier
	s_setprio 0
	s_add_i32 s62, s62, 2
	s_add_u32 s8, s8, 0x100
	s_addc_u32 s9, s9, 0
	s_cmp_gt_u32 s62, 5
	s_cbranch_scc0 .LBB0_2230
	s_cmpk_lt_u32 s16, 0x100
	s_cbranch_scc0 .LBB0_2233
	s_barrier

; #define PG8_STAGE(bufoff, gbase, voff) do { _Pragma("unroll") for (int _i = 0; _i < 2; ++_i) \
;         __builtin_amdgcn_global_load_lds((const unsigned*)((const char*)(gbase) + (voff)[_i]), (LAS unsigned*)(lds + (bufoff) + ldsw + _i * 8192), 16, 0, 0); } while (0)
; #define PG8_LDA(dst, b, h) do { _Pragma("unroll") for (int m = 0; m < 4; ++m) _Pragma("unroll") for (int k = 0; k < 2; ++k) dst[m][k] = *(const LAS half8*)(lds + PG8_SA(b, h) + aoff + m * 2048 + k * 1024); } while (0)
; #define PG8_LDB(dst, b, h) do { _Pragma("unroll") for (int n = 0; n < 2; ++n) _Pragma("unroll") for (int k = 0; k < 2; ++k) dst[n][k] = *(const LAS half8*)(lds + PG8_SB(b, h) + boff + n * 2048 + k * 1024); } while (0)
; #define PG8_MMA(ai, bj, At, Bt) do { __builtin_amdgcn_s_setprio(1); _Pragma("unroll") for (int m = 0; m < 4; ++m) _Pragma("unroll") for (int n = 0; n < 2; ++n) _Pragma("unroll") for (int k = 0; k < 2; ++k) \
;         acc[ai][bj][m][n] = __builtin_amdgcn_mfma_f32_16x16x32_f16(Bt[n][k], At[m][k], acc[ai][bj][m][n], 0, 0, 0); __builtin_amdgcn_s_setprio(0); } while (0)
; #define PG8_WAIT_V(n) asm volatile("s_waitcnt vmcnt(" #n ")" ::: "memory")
; #define PG8_WAIT_L(n) asm volatile("s_waitcnt lgkmcnt(" #n ")" ::: "memory")
; #define PG8_BAR __builtin_amdgcn_s_barrier()
; #define PG8_SCHED __builtin_amdgcn_sched_barrier(0)
; template <class Epi, class Sched, bool ALIGN_EPI = false, bool SP2 = false>
; __device__ __forceinline__ void gemm_phase(LAS unsigned char* lds, const Gemm g, const Sched& S, const Epi& E) {
;     ...
;             const char* a1 = cA + (size_t)(t + 1) * kstep;
;             const char* a2 = last ? nA : cA + (size_t)(t + 2) * kstep; const char* b2 = last ? nB : cB + (size_t)(t + 2) * kstep;
;             const char* a3 = a2 + kstep; const char* b3 = b2 + kstep;
;             if (last && has_next) S.a_ready(nxt);
;             if constexpr (SP2) {
;             PG8_LDB(B0, 0, 0); PG8_LDB(B1, 0, 1); PG8_SCHED; PG8_LDA(At, 0, 0); PG8_STAGE(PG8_SA(1, 1), a1 + hstepA, voffA);
;             PG8_WAIT_V(8); PG8_WAIT_L(0); PG8_BAR; PG8_MMA(0, 0, At, B0); PG8_MMA(0, 1, At, B1); PG8_BAR; PG8_SCHED;
;             PG8_LDA(At, 0, 1); PG8_STAGE(PG8_SB(0, 0), b2, voffB); PG8_STAGE(PG8_SB(0, 1), b2 + hstepB, voffB); PG8_STAGE(PG8_SA(0, 0), a2, voffA);
.LBB0_2239:
	s_add_u32 s14, s58, s12
	s_addc_u32 s15, s59, s13
	s_add_u32 s14, s14, 0x3e100100
	s_addc_u32 s15, s15, 0
	s_add_u32 s63, s60, s12
	s_addc_u32 s64, s61, s13
	s_add_i32 s65, 0, 0x10000
	s_cmpk_eq_i32 s12, 0x300
	s_cselect_b32 s17, s11, s15
	s_cselect_b32 s16, s10, s14
	v_add_u32_e32 v145, s65, v143
	s_cselect_b32 s15, s9, s64
	s_cselect_b32 s14, s8, s63
	s_add_i32 s63, 0, 0x14000
	ds_read_b128 v[146:149], v145
	ds_read_b128 v[150:153], v145 offset:1024
	ds_read_b128 v[154:157], v145 offset:2048
	ds_read_b128 v[158:161], v145 offset:3072
	v_add_u32_e32 v145, s63, v143
	ds_read_b128 v[162:165], v145
	ds_read_b128 v[166:169], v145 offset:1024
	ds_read_b128 v[170:173], v145 offset:2048
	ds_read_b128 v[174:177], v145 offset:3072
	v_lshl_add_u64 v[194:195], v[138:139], 0, s[12:13]
	s_add_i32 m0, s1, 0xc000
	ds_read_b128 v[178:181], v144
	ds_read_b128 v[182:185], v144 offset:1024
	ds_read_b128 v[186:189], v144 offset:2048
	ds_read_b128 v[190:193], v144 offset:3072
	ds_read_b128 v[204:207], v144 offset:4096
	ds_read_b128 v[220:223], v144 offset:5120
	ds_read_b128 v[224:227], v144 offset:6144
	ds_read_b128 v[228:231], v144 offset:7168
	global_load_lds_dwordx4 v[194:195], off
	v_lshl_add_u64 v[194:195], v[140:141], 0, s[12:13]
	s_add_i32 m0, s1, 0xe000
	s_nop 0
	global_load_lds_dwordx4 v[194:195], off
	s_waitcnt vmcnt(8)
	s_waitcnt lgkmcnt(0)
	s_setprio 1
	s_barrier
	v_mfma_f32_16x16x32_f16 v[128:131], v[146:149], v[178:181], v[128:131]
	v_mfma_f32_16x16x32_f16 v[124:127], v[154:157], v[178:181], v[124:127]
	v_mfma_f32_16x16x32_f16 v[112:115], v[146:149], v[186:189], v[112:115]
	v_mfma_f32_16x16x32_f16 v[108:111], v[154:157], v[186:189], v[108:111]
	v_mfma_f32_16x16x32_f16 v[96:99], v[146:149], v[204:207], v[96:99]
	v_mfma_f32_16x16x32_f16 v[92:95], v[154:157], v[204:207], v[92:95]
	v_mfma_f32_16x16x32_f16 v[80:83], v[146:149], v[224:227], v[80:83]
	v_mfma_f32_16x16x32_f16 v[76:79], v[154:157], v[224:227], v[76:79]
	v_mfma_f32_16x16x32_f16 v[128:131], v[150:153], v[182:185], v[128:131]
	v_mfma_f32_16x16x32_f16 v[124:127], v[158:161], v[182:185], v[124:127]
	v_mfma_f32_16x16x32_f16 v[112:115], v[150:153], v[190:193], v[112:115]
	v_mfma_f32_16x16x32_f16 v[108:111], v[158:161], v[190:193], v[108:111]
	v_mfma_f32_16x16x32_f16 v[96:99], v[150:153], v[220:223], v[96:99]
	v_mfma_f32_16x16x32_f16 v[92:95], v[158:161], v[220:223], v[92:95]
	v_mfma_f32_16x16x32_f16 v[80:83], v[150:153], v[228:231], v[80:83]
	v_mfma_f32_16x16x32_f16 v[76:79], v[158:161], v[228:231], v[76:79]
	v_mfma_f32_16x16x32_f16 v[120:123], v[162:165], v[178:181], v[120:123]
	v_mfma_f32_16x16x32_f16 v[116:119], v[170:173], v[178:181], v[116:119]
	v_mfma_f32_16x16x32_f16 v[104:107], v[162:165], v[186:189], v[104:107]
	v_mfma_f32_16x16x32_f16 v[100:103], v[170:173], v[186:189], v[100:103]
	v_mfma_f32_16x16x32_f16 v[88:91], v[162:165], v[204:207], v[88:91]
	v_mfma_f32_16x16x32_f16 v[84:87], v[170:173], v[204:207], v[84:87]
	v_mfma_f32_16x16x32_f16 v[72:75], v[162:165], v[224:227], v[72:75]
	v_mfma_f32_16x16x32_f16 v[68:71], v[170:173], v[224:227], v[68:71]
	v_mfma_f32_16x16x32_f16 v[120:123], v[166:169], v[182:185], v[120:123]
	v_mfma_f32_16x16x32_f16 v[116:119], v[174:177], v[182:185], v[116:119]
	v_mfma_f32_16x16x32_f16 v[104:107], v[166:169], v[190:193], v[104:107]
	v_mfma_f32_16x16x32_f16 v[100:103], v[174:177], v[190:193], v[100:103]
	v_mfma_f32_16x16x32_f16 v[88:91], v[166:169], v[220:223], v[88:91]
	v_mfma_f32_16x16x32_f16 v[84:87], v[174:177], v[220:223], v[84:87]
	v_mfma_f32_16x16x32_f16 v[72:75], v[166:169], v[228:231], v[72:75]
	v_mfma_f32_16x16x32_f16 v[68:71], v[174:177], v[228:231], v[68:71]
	s_barrier
	s_setprio 0
	s_add_i32 s64, s65, s24
	v_lshl_add_u64 v[194:195], s[14:15], 0, v[2:3]
	s_mov_b32 m0, s64
	ds_read_b128 v[178:181], v144 offset:16384
	ds_read_b128 v[182:185], v144 offset:17408
	ds_read_b128 v[186:189], v144 offset:18432
	ds_read_b128 v[190:193], v144 offset:19456
	ds_read_b128 v[204:207], v144 offset:20480
	ds_read_b128 v[220:223], v144 offset:21504
	ds_read_b128 v[224:227], v144 offset:22528
	ds_read_b128 v[228:231], v144 offset:23552
	global_load_lds_dwordx4 v[194:195], off
	s_add_i32 m0, s64, 0x2000
	s_add_u32 s64, s14, 0x20000
	v_lshl_add_u64 v[196:197], s[14:15], 0, v[132:133]
	s_addc_u32 s65, s15, 0
	s_add_i32 s63, s63, s24
	global_load_lds_dwordx4 v[196:197], off
	v_lshl_add_u64 v[208:209], s[64:65], 0, v[2:3]
	s_mov_b32 m0, s63
	v_lshl_add_u64 v[232:233], s[16:17], 0, v[134:135]
	global_load_lds_dwordx4 v[208:209], off
	v_lshl_add_u64 v[208:209], s[64:65], 0, v[132:133]
	s_add_i32 m0, s63, 0x2000
	s_nop 0
	global_load_lds_dwordx4 v[208:209], off
	v_lshl_add_u64 v[208:209], s[16:17], 0, v[136:137]
	s_mov_b32 m0, s1
	s_nop 0
	global_load_lds_dwordx4 v[208:209], off
	s_mov_b32 m0, s7
	s_nop 0
	global_load_lds_dwordx4 v[232:233], off
	s_waitcnt vmcnt(8)
	s_waitcnt lgkmcnt(0)
	s_setprio 1
	s_barrier
; #define PG8_STAGE(bufoff, gbase, voff) do { _Pragma("unroll") for (int _i = 0; _i < 2; ++_i) \
;         __builtin_amdgcn_global_load_lds((const unsigned*)((const char*)(gbase) + (voff)[_i]), (LAS unsigned*)(lds + (bufoff) + ldsw + _i * 8192), 16, 0, 0); } while (0)
; #define PG8_LDA(dst, b, h) do { _Pragma("unroll") for (int m = 0; m < 4; ++m) _Pragma("unroll") for (int k = 0; k < 2; ++k) dst[m][k] = *(const LAS half8*)(lds + PG8_SA(b, h) + aoff + m * 2048 + k * 1024); } while (0)
; #define PG8_LDB(dst, b, h) do { _Pragma("unroll") for (int n = 0; n < 2; ++n) _Pragma("unroll") for (int k = 0; k < 2; ++k) dst[n][k] = *(const LAS half8*)(lds + PG8_SB(b, h) + boff + n * 2048 + k * 1024); } while (0)
; #define PG8_MMA(ai, bj, At, Bt) do { __builtin_amdgcn_s_setprio(1); _Pragma("unroll") for (int m = 0; m < 4; ++m) _Pragma("unroll") for (int n = 0; n < 2; ++n) _Pragma("unroll") for (int k = 0; k < 2; ++k) \
;         acc[ai][bj][m][n] = __builtin_amdgcn_mfma_f32_16x16x32_f16(Bt[n][k], At[m][k], acc[ai][bj][m][n], 0, 0, 0); __builtin_amdgcn_s_setprio(0); } while (0)
; #define PG8_WAIT_V(n) asm volatile("s_waitcnt vmcnt(" #n ")" ::: "memory")
; #define PG8_WAIT_L(n) asm volatile("s_waitcnt lgkmcnt(" #n ")" ::: "memory")
; #define PG8_BAR __builtin_amdgcn_s_barrier()
; #define PG8_SCHED __builtin_amdgcn_sched_barrier(0)
; template <class Epi, class Sched, bool ALIGN_EPI = false, bool SP2 = false>
; __device__ __forceinline__ void gemm_phase(LAS unsigned char* lds, const Gemm g, const Sched& S, const Epi& E) {
;     ...
;             PG8_WAIT_V(8); PG8_WAIT_L(0); PG8_BAR; PG8_MMA(1, 0, At, B0); PG8_MMA(1, 1, At, B1); PG8_BAR; PG8_SCHED;
;             PG8_LDB(B0, 1, 0); PG8_LDB(B1, 1, 1); PG8_SCHED; PG8_LDA(At, 1, 0); PG8_STAGE(PG8_SA(0, 1), a2 + hstepA, voffA);
;             PG8_WAIT_V(8); PG8_WAIT_L(0); PG8_BAR; PG8_MMA(0, 0, At, B0); PG8_MMA(0, 1, At, B1); PG8_BAR; PG8_SCHED;
	v_mfma_f32_16x16x32_f16 v[64:67], v[146:149], v[178:181], v[64:67]
	v_mfma_f32_16x16x32_f16 v[60:63], v[154:157], v[178:181], v[60:63]
	v_mfma_f32_16x16x32_f16 v[48:51], v[146:149], v[186:189], v[48:51]
	v_mfma_f32_16x16x32_f16 v[44:47], v[154:157], v[186:189], v[44:47]
	v_mfma_f32_16x16x32_f16 v[32:35], v[146:149], v[204:207], v[32:35]
	v_mfma_f32_16x16x32_f16 v[28:31], v[154:157], v[204:207], v[28:31]
	v_mfma_f32_16x16x32_f16 v[16:19], v[146:149], v[224:227], v[16:19]
	v_mfma_f32_16x16x32_f16 v[12:15], v[154:157], v[224:227], v[12:15]
	v_mfma_f32_16x16x32_f16 v[64:67], v[150:153], v[182:185], v[64:67]
	v_mfma_f32_16x16x32_f16 v[60:63], v[158:161], v[182:185], v[60:63]
	v_mfma_f32_16x16x32_f16 v[48:51], v[150:153], v[190:193], v[48:51]
	v_mfma_f32_16x16x32_f16 v[44:47], v[158:161], v[190:193], v[44:47]
	v_mfma_f32_16x16x32_f16 v[32:35], v[150:153], v[220:223], v[32:35]
	v_mfma_f32_16x16x32_f16 v[28:31], v[158:161], v[220:223], v[28:31]
	v_mfma_f32_16x16x32_f16 v[16:19], v[150:153], v[228:231], v[16:19]
	v_mfma_f32_16x16x32_f16 v[12:15], v[158:161], v[228:231], v[12:15]
	v_mfma_f32_16x16x32_f16 v[56:59], v[162:165], v[178:181], v[56:59]
	v_mfma_f32_16x16x32_f16 v[52:55], v[170:173], v[178:181], v[52:55]
	v_mfma_f32_16x16x32_f16 v[40:43], v[162:165], v[186:189], v[40:43]
	v_mfma_f32_16x16x32_f16 v[36:39], v[170:173], v[186:189], v[36:39]
	v_mfma_f32_16x16x32_f16 v[24:27], v[162:165], v[204:207], v[24:27]
	v_mfma_f32_16x16x32_f16 v[20:23], v[170:173], v[204:207], v[20:23]
	v_mfma_f32_16x16x32_f16 v[8:11], v[162:165], v[224:227], v[8:11]
	v_mfma_f32_16x16x32_f16 v[4:7], v[170:173], v[224:227], v[4:7]
	v_mfma_f32_16x16x32_f16 v[56:59], v[166:169], v[182:185], v[56:59]
	v_mfma_f32_16x16x32_f16 v[52:55], v[174:177], v[182:185], v[52:55]
	v_mfma_f32_16x16x32_f16 v[40:43], v[166:169], v[190:193], v[40:43]
	v_mfma_f32_16x16x32_f16 v[36:39], v[174:177], v[190:193], v[36:39]
	v_mfma_f32_16x16x32_f16 v[24:27], v[166:169], v[220:223], v[24:27]
	v_mfma_f32_16x16x32_f16 v[20:23], v[174:177], v[220:223], v[20:23]
	v_mfma_f32_16x16x32_f16 v[8:11], v[166:169], v[228:231], v[8:11]
	v_mfma_f32_16x16x32_f16 v[4:7], v[174:177], v[228:231], v[4:7]
	s_barrier
	s_setprio 0
	s_add_i32 s63, 0, 0x18000
	v_add_u32_e32 v145, s63, v143
	s_add_i32 s64, 0, 0x1c000
	ds_read_b128 v[146:149], v145
	ds_read_b128 v[150:153], v145 offset:1024
	ds_read_b128 v[154:157], v145 offset:2048
	ds_read_b128 v[158:161], v145 offset:3072
	v_add_u32_e32 v145, s64, v143
	ds_read_b128 v[162:165], v145
	ds_read_b128 v[166:169], v145 offset:1024
	ds_read_b128 v[170:173], v145 offset:2048
	ds_read_b128 v[174:177], v145 offset:3072
	s_add_u32 s16, s16, 0x20000
	s_addc_u32 s17, s17, 0
	s_mov_b32 m0, s37
	v_lshl_add_u64 v[234:235], s[16:17], 0, v[136:137]
	ds_read_b128 v[178:181], v144 offset:32768
	ds_read_b128 v[182:185], v144 offset:33792
	ds_read_b128 v[186:189], v144 offset:34816
	ds_read_b128 v[190:193], v144 offset:35840
	ds_read_b128 v[204:207], v144 offset:36864
	ds_read_b128 v[220:223], v144 offset:37888
	ds_read_b128 v[224:227], v144 offset:38912
	ds_read_b128 v[228:231], v144 offset:39936
	global_load_lds_dwordx4 v[234:235], off
	v_lshl_add_u64 v[234:235], s[16:17], 0, v[134:135]
	s_mov_b32 m0, s38
	s_nop 0
	global_load_lds_dwordx4 v[234:235], off
	s_waitcnt vmcnt(8)
	s_waitcnt lgkmcnt(0)
	s_setprio 1
	s_barrier
	v_mfma_f32_16x16x32_f16 v[128:131], v[146:149], v[178:181], v[128:131]
	v_mfma_f32_16x16x32_f16 v[124:127], v[154:157], v[178:181], v[124:127]
	v_mfma_f32_16x16x32_f16 v[112:115], v[146:149], v[186:189], v[112:115]
	v_mfma_f32_16x16x32_f16 v[108:111], v[154:157], v[186:189], v[108:111]
	v_mfma_f32_16x16x32_f16 v[96:99], v[146:149], v[204:207], v[96:99]
	v_mfma_f32_16x16x32_f16 v[92:95], v[154:157], v[204:207], v[92:95]
	v_mfma_f32_16x16x32_f16 v[80:83], v[146:149], v[224:227], v[80:83]
	v_mfma_f32_16x16x32_f16 v[76:79], v[154:157], v[224:227], v[76:79]
	v_mfma_f32_16x16x32_f16 v[128:131], v[150:153], v[182:185], v[128:131]
	v_mfma_f32_16x16x32_f16 v[124:127], v[158:161], v[182:185], v[124:127]
	v_mfma_f32_16x16x32_f16 v[112:115], v[150:153], v[190:193], v[112:115]
	v_mfma_f32_16x16x32_f16 v[108:111], v[158:161], v[190:193], v[108:111]
	v_mfma_f32_16x16x32_f16 v[96:99], v[150:153], v[220:223], v[96:99]
	v_mfma_f32_16x16x32_f16 v[92:95], v[158:161], v[220:223], v[92:95]
	v_mfma_f32_16x16x32_f16 v[80:83], v[150:153], v[228:231], v[80:83]
	v_mfma_f32_16x16x32_f16 v[76:79], v[158:161], v[228:231], v[76:79]
	v_mfma_f32_16x16x32_f16 v[120:123], v[162:165], v[178:181], v[120:123]
	v_mfma_f32_16x16x32_f16 v[116:119], v[170:173], v[178:181], v[116:119]
	v_mfma_f32_16x16x32_f16 v[104:107], v[162:165], v[186:189], v[104:107]
	v_mfma_f32_16x16x32_f16 v[100:103], v[170:173], v[186:189], v[100:103]
	v_mfma_f32_16x16x32_f16 v[88:91], v[162:165], v[204:207], v[88:91]
	v_mfma_f32_16x16x32_f16 v[84:87], v[170:173], v[204:207], v[84:87]
	v_mfma_f32_16x16x32_f16 v[72:75], v[162:165], v[224:227], v[72:75]
	v_mfma_f32_16x16x32_f16 v[68:71], v[170:173], v[224:227], v[68:71]
	v_mfma_f32_16x16x32_f16 v[120:123], v[166:169], v[182:185], v[120:123]
	v_mfma_f32_16x16x32_f16 v[116:119], v[174:177], v[182:185], v[116:119]
	v_mfma_f32_16x16x32_f16 v[104:107], v[166:169], v[190:193], v[104:107]
	v_mfma_f32_16x16x32_f16 v[100:103], v[174:177], v[190:193], v[100:103]
	v_mfma_f32_16x16x32_f16 v[88:91], v[166:169], v[220:223], v[88:91]
	v_mfma_f32_16x16x32_f16 v[84:87], v[174:177], v[220:223], v[84:87]
	v_mfma_f32_16x16x32_f16 v[72:75], v[166:169], v[228:231], v[72:75]
	v_mfma_f32_16x16x32_f16 v[68:71], v[174:177], v[228:231], v[68:71]
	s_barrier
; #define PG8_STAGE(bufoff, gbase, voff) do { _Pragma("unroll") for (int _i = 0; _i < 2; ++_i) \
;         __builtin_amdgcn_global_load_lds((const unsigned*)((const char*)(gbase) + (voff)[_i]), (LAS unsigned*)(lds + (bufoff) + ldsw + _i * 8192), 16, 0, 0); } while (0)
; #define PG8_LDA(dst, b, h) do { _Pragma("unroll") for (int m = 0; m < 4; ++m) _Pragma("unroll") for (int k = 0; k < 2; ++k) dst[m][k] = *(const LAS half8*)(lds + PG8_SA(b, h) + aoff + m * 2048 + k * 1024); } while (0)
; #define PG8_MMA(ai, bj, At, Bt) do { __builtin_amdgcn_s_setprio(1); _Pragma("unroll") for (int m = 0; m < 4; ++m) _Pragma("unroll") for (int n = 0; n < 2; ++n) _Pragma("unroll") for (int k = 0; k < 2; ++k) \
;         acc[ai][bj][m][n] = __builtin_amdgcn_mfma_f32_16x16x32_f16(Bt[n][k], At[m][k], acc[ai][bj][m][n], 0, 0, 0); __builtin_amdgcn_s_setprio(0); } while (0)
; #define PG8_WAIT_V(n) asm volatile("s_waitcnt vmcnt(" #n ")" ::: "memory")
; #define PG8_WAIT_L(n) asm volatile("s_waitcnt lgkmcnt(" #n ")" ::: "memory")
; #define PG8_BAR __builtin_amdgcn_s_barrier()
; #define PG8_SCHED __builtin_amdgcn_sched_barrier(0)
; template <class Epi, class Sched, bool ALIGN_EPI = false, bool SP2 = false>
; __device__ __forceinline__ void gemm_phase(LAS unsigned char* lds, const Gemm g, const Sched& S, const Epi& E) {
;     ...
;             PG8_LDA(At, 1, 1); PG8_STAGE(PG8_SB(1, 0), b3, voffB); PG8_STAGE(PG8_SB(1, 1), b3 + hstepB, voffB); PG8_STAGE(PG8_SA(1, 0), a3, voffA);
;             PG8_WAIT_V(8); PG8_WAIT_L(0); PG8_BAR; PG8_MMA(1, 0, At, B0); PG8_MMA(1, 1, At, B1); PG8_BAR; PG8_SCHED;
	s_setprio 0
	s_add_i32 s16, s63, s24
	v_lshl_add_u64 v[194:195], v[194:195], 0, s[96:97]
	s_mov_b32 m0, s16
	ds_read_b128 v[178:181], v144 offset:49152
	ds_read_b128 v[182:185], v144 offset:50176
	ds_read_b128 v[186:189], v144 offset:51200
	ds_read_b128 v[190:193], v144 offset:52224
	ds_read_b128 v[204:207], v144 offset:53248
	ds_read_b128 v[220:223], v144 offset:54272
	ds_read_b128 v[224:227], v144 offset:55296
	ds_read_b128 v[228:231], v144 offset:56320
	global_load_lds_dwordx4 v[194:195], off
	s_add_i32 m0, s16, 0x2000
	s_add_u32 s14, s14, 0x20080
	v_lshl_add_u64 v[194:195], v[196:197], 0, s[96:97]
	s_addc_u32 s15, s15, 0
	s_add_i32 s16, s64, s24
	global_load_lds_dwordx4 v[194:195], off
	v_lshl_add_u64 v[194:195], s[14:15], 0, v[2:3]
	s_mov_b32 m0, s16
	s_nop 0
	global_load_lds_dwordx4 v[194:195], off
	v_lshl_add_u64 v[194:195], s[14:15], 0, v[132:133]
	s_add_i32 m0, s16, 0x2000
	s_nop 0
	global_load_lds_dwordx4 v[194:195], off
	v_lshl_add_u64 v[194:195], v[208:209], 0, s[96:97]
	s_mov_b32 m0, s39
	s_nop 0
	global_load_lds_dwordx4 v[194:195], off
	v_lshl_add_u64 v[194:195], v[232:233], 0, s[96:97]
	s_mov_b32 m0, s57
	s_nop 0
	global_load_lds_dwordx4 v[194:195], off
	s_waitcnt vmcnt(8)
	s_waitcnt lgkmcnt(0)
	s_setprio 1
	s_barrier
	v_mfma_f32_16x16x32_f16 v[64:67], v[146:149], v[178:181], v[64:67]
	v_mfma_f32_16x16x32_f16 v[60:63], v[154:157], v[178:181], v[60:63]
	v_mfma_f32_16x16x32_f16 v[48:51], v[146:149], v[186:189], v[48:51]
	v_mfma_f32_16x16x32_f16 v[44:47], v[154:157], v[186:189], v[44:47]
	v_mfma_f32_16x16x32_f16 v[32:35], v[146:149], v[204:207], v[32:35]
	v_mfma_f32_16x16x32_f16 v[28:31], v[154:157], v[204:207], v[28:31]
	v_mfma_f32_16x16x32_f16 v[16:19], v[146:149], v[224:227], v[16:19]
	v_mfma_f32_16x16x32_f16 v[12:15], v[154:157], v[224:227], v[12:15]
	v_mfma_f32_16x16x32_f16 v[64:67], v[150:153], v[182:185], v[64:67]
	v_mfma_f32_16x16x32_f16 v[60:63], v[158:161], v[182:185], v[60:63]
	v_mfma_f32_16x16x32_f16 v[48:51], v[150:153], v[190:193], v[48:51]
	v_mfma_f32_16x16x32_f16 v[44:47], v[158:161], v[190:193], v[44:47]
	v_mfma_f32_16x16x32_f16 v[32:35], v[150:153], v[220:223], v[32:35]
	v_mfma_f32_16x16x32_f16 v[28:31], v[158:161], v[220:223], v[28:31]
	v_mfma_f32_16x16x32_f16 v[16:19], v[150:153], v[228:231], v[16:19]
	v_mfma_f32_16x16x32_f16 v[12:15], v[158:161], v[228:231], v[12:15]
	v_mfma_f32_16x16x32_f16 v[56:59], v[162:165], v[178:181], v[56:59]
	v_mfma_f32_16x16x32_f16 v[52:55], v[170:173], v[178:181], v[52:55]
	v_mfma_f32_16x16x32_f16 v[40:43], v[162:165], v[186:189], v[40:43]
	v_mfma_f32_16x16x32_f16 v[36:39], v[170:173], v[186:189], v[36:39]
	v_mfma_f32_16x16x32_f16 v[24:27], v[162:165], v[204:207], v[24:27]
	v_mfma_f32_16x16x32_f16 v[20:23], v[170:173], v[204:207], v[20:23]
	v_mfma_f32_16x16x32_f16 v[8:11], v[162:165], v[224:227], v[8:11]
	v_mfma_f32_16x16x32_f16 v[4:7], v[170:173], v[224:227], v[4:7]
	v_mfma_f32_16x16x32_f16 v[56:59], v[166:169], v[182:185], v[56:59]
	v_mfma_f32_16x16x32_f16 v[52:55], v[174:177], v[182:185], v[52:55]
	v_mfma_f32_16x16x32_f16 v[40:43], v[166:169], v[190:193], v[40:43]
	v_mfma_f32_16x16x32_f16 v[36:39], v[174:177], v[190:193], v[36:39]
	v_mfma_f32_16x16x32_f16 v[24:27], v[166:169], v[220:223], v[24:27]
	v_mfma_f32_16x16x32_f16 v[20:23], v[174:177], v[220:223], v[20:23]
	v_mfma_f32_16x16x32_f16 v[8:11], v[166:169], v[228:231], v[8:11]
	v_mfma_f32_16x16x32_f16 v[4:7], v[174:177], v[228:231], v[4:7]
	s_barrier
	s_setprio 0
	s_add_i32 s62, s62, 2
	s_add_u32 s12, s12, 0x100
	s_addc_u32 s13, s13, 0
	s_cmp_gt_u32 s62, 5
	s_cbranch_scc0 .LBB0_2239
	s_cmpk_lt_u32 s2, 0x100
	s_cbranch_scc0 .LBB0_2242
	s_barrier

; #define PG8_STAGE(bufoff, gbase, voff) do { _Pragma("unroll") for (int _i = 0; _i < 2; ++_i) \
;         __builtin_amdgcn_global_load_lds((const unsigned*)((const char*)(gbase) + (voff)[_i]), (LAS unsigned*)(lds + (bufoff) + ldsw + _i * 8192), 16, 0, 0); } while (0)
; #define PG8_LDA(dst, b, h) do { _Pragma("unroll") for (int m = 0; m < 4; ++m) _Pragma("unroll") for (int k = 0; k < 2; ++k) dst[m][k] = *(const LAS half8*)(lds + PG8_SA(b, h) + aoff + m * 2048 + k * 1024); } while (0)
; #define PG8_LDB(dst, b, h) do { _Pragma("unroll") for (int n = 0; n < 2; ++n) _Pragma("unroll") for (int k = 0; k < 2; ++k) dst[n][k] = *(const LAS half8*)(lds + PG8_SB(b, h) + boff + n * 2048 + k * 1024); } while (0)
; #define PG8_MMA(ai, bj, At, Bt) do { __builtin_amdgcn_s_setprio(1); _Pragma("unroll") for (int m = 0; m < 4; ++m) _Pragma("unroll") for (int n = 0; n < 2; ++n) _Pragma("unroll") for (int k = 0; k < 2; ++k) \
;         acc[ai][bj][m][n] = __builtin_amdgcn_mfma_f32_16x16x32_f16(Bt[n][k], At[m][k], acc[ai][bj][m][n], 0, 0, 0); __builtin_amdgcn_s_setprio(0); } while (0)
; #define PG8_WAIT_V(n) asm volatile("s_waitcnt vmcnt(" #n ")" ::: "memory")
; #define PG8_WAIT_L(n) asm volatile("s_waitcnt lgkmcnt(" #n ")" ::: "memory")
; #define PG8_BAR __builtin_amdgcn_s_barrier()
; #define PG8_SCHED __builtin_amdgcn_sched_barrier(0)
; template <class Epi, class Sched, bool ALIGN_EPI = false, bool SP2 = false>
; __device__ __forceinline__ void gemm_phase(LAS unsigned char* lds, const Gemm g, const Sched& S, const Epi& E) {
;     ...
;             const char* a1 = cA + (size_t)(t + 1) * kstep;
;             const char* a2 = last ? nA : cA + (size_t)(t + 2) * kstep; const char* b2 = last ? nB : cB + (size_t)(t + 2) * kstep;
;             const char* a3 = a2 + kstep; const char* b3 = b2 + kstep;
;             if (last && has_next) S.a_ready(nxt);
;             if constexpr (SP2) {
;             PG8_LDB(B0, 0, 0); PG8_LDB(B1, 0, 1); PG8_SCHED; PG8_LDA(At, 0, 0); PG8_STAGE(PG8_SA(1, 1), a1 + hstepA, voffA);
;             PG8_WAIT_V(8); PG8_WAIT_L(0); PG8_BAR; PG8_MMA(0, 0, At, B0); PG8_MMA(0, 1, At, B1); PG8_BAR; PG8_SCHED;
;             PG8_LDA(At, 0, 1); PG8_STAGE(PG8_SB(0, 0), b2, voffB); PG8_STAGE(PG8_SB(0, 1), b2 + hstepB, voffB); PG8_STAGE(PG8_SA(0, 0), a2, voffA);
.LBB0_5097:
	s_add_i32 s69, s12, 2
	s_add_u32 s70, s10, 0x80
	s_addc_u32 s13, s11, 0
	s_add_i32 s80, 0, 0x10000
	s_cmp_eq_u32 s61, s12
	s_cselect_b32 s13, s9, s13
	s_cselect_b32 s12, s8, s70
	v_add_u32_e32 v142, s80, v144
	s_cselect_b32 s71, s39, s68
	s_cselect_b32 s70, s38, s67
	s_add_i32 s81, 0, 0x14000
	ds_read_b128 v[138:141], v142
	ds_read_b128 v[148:151], v142 offset:1024
	ds_read_b128 v[152:155], v142 offset:2048
	ds_read_b128 v[156:159], v142 offset:3072
	v_add_u32_e32 v142, s81, v144
	ds_read_b128 v[160:163], v142
	ds_read_b128 v[164:167], v142 offset:1024
	ds_read_b128 v[168:171], v142 offset:2048
	ds_read_b128 v[172:175], v142 offset:3072
	v_lshl_add_u64 v[142:143], s[10:11], 0, v[134:135]
	s_add_i32 m0, s16, 0xc000
	ds_read_b128 v[176:179], v146
	ds_read_b128 v[180:183], v146 offset:1024
	ds_read_b128 v[184:187], v146 offset:2048
	ds_read_b128 v[188:191], v146 offset:3072
	ds_read_b128 v[192:195], v146 offset:4096
	ds_read_b128 v[204:207], v146 offset:5120
	ds_read_b128 v[220:223], v146 offset:6144
	ds_read_b128 v[224:227], v146 offset:7168
	global_load_lds_dwordx4 v[142:143], off
	v_lshl_add_u64 v[142:143], s[10:11], 0, v[136:137]
	s_add_i32 m0, s16, 0xe000
	s_nop 0
	global_load_lds_dwordx4 v[142:143], off
	s_waitcnt vmcnt(8)
	s_waitcnt lgkmcnt(0)
	s_setprio 1
	s_barrier
	v_mfma_f32_16x16x32_f16 v[128:131], v[138:141], v[176:179], v[128:131]
	v_mfma_f32_16x16x32_f16 v[124:127], v[152:155], v[176:179], v[124:127]
	v_mfma_f32_16x16x32_f16 v[112:115], v[138:141], v[184:187], v[112:115]
	v_mfma_f32_16x16x32_f16 v[108:111], v[152:155], v[184:187], v[108:111]
	v_mfma_f32_16x16x32_f16 v[96:99], v[138:141], v[192:195], v[96:99]
	v_mfma_f32_16x16x32_f16 v[92:95], v[152:155], v[192:195], v[92:95]
	v_mfma_f32_16x16x32_f16 v[80:83], v[138:141], v[220:223], v[80:83]
	v_mfma_f32_16x16x32_f16 v[76:79], v[152:155], v[220:223], v[76:79]
	v_mfma_f32_16x16x32_f16 v[128:131], v[148:151], v[180:183], v[128:131]
	v_mfma_f32_16x16x32_f16 v[124:127], v[156:159], v[180:183], v[124:127]
	v_mfma_f32_16x16x32_f16 v[112:115], v[148:151], v[188:191], v[112:115]
	v_mfma_f32_16x16x32_f16 v[108:111], v[156:159], v[188:191], v[108:111]
	v_mfma_f32_16x16x32_f16 v[96:99], v[148:151], v[204:207], v[96:99]
	v_mfma_f32_16x16x32_f16 v[92:95], v[156:159], v[204:207], v[92:95]
	v_mfma_f32_16x16x32_f16 v[80:83], v[148:151], v[224:227], v[80:83]
	v_mfma_f32_16x16x32_f16 v[76:79], v[156:159], v[224:227], v[76:79]
	v_mfma_f32_16x16x32_f16 v[120:123], v[160:163], v[176:179], v[120:123]
	v_mfma_f32_16x16x32_f16 v[116:119], v[168:171], v[176:179], v[116:119]
	v_mfma_f32_16x16x32_f16 v[104:107], v[160:163], v[184:187], v[104:107]
	v_mfma_f32_16x16x32_f16 v[100:103], v[168:171], v[184:187], v[100:103]
	v_mfma_f32_16x16x32_f16 v[88:91], v[160:163], v[192:195], v[88:91]
	v_mfma_f32_16x16x32_f16 v[84:87], v[168:171], v[192:195], v[84:87]
	v_mfma_f32_16x16x32_f16 v[72:75], v[160:163], v[220:223], v[72:75]
	v_mfma_f32_16x16x32_f16 v[68:71], v[168:171], v[220:223], v[68:71]
	v_mfma_f32_16x16x32_f16 v[120:123], v[164:167], v[180:183], v[120:123]
	v_mfma_f32_16x16x32_f16 v[116:119], v[172:175], v[180:183], v[116:119]
	v_mfma_f32_16x16x32_f16 v[104:107], v[164:167], v[188:191], v[104:107]
	v_mfma_f32_16x16x32_f16 v[100:103], v[172:175], v[188:191], v[100:103]
	v_mfma_f32_16x16x32_f16 v[88:91], v[164:167], v[204:207], v[88:91]
	v_mfma_f32_16x16x32_f16 v[84:87], v[172:175], v[204:207], v[84:87]
	v_mfma_f32_16x16x32_f16 v[72:75], v[164:167], v[224:227], v[72:75]
	v_mfma_f32_16x16x32_f16 v[68:71], v[172:175], v[224:227], v[68:71]
	s_barrier
	s_setprio 0
	s_add_i32 s80, s80, s15
	v_lshl_add_u64 v[142:143], s[70:71], 0, v[2:3]
	s_mov_b32 m0, s80
	ds_read_b128 v[176:179], v146 offset:16384
	ds_read_b128 v[180:183], v146 offset:17408
	ds_read_b128 v[184:187], v146 offset:18432
	ds_read_b128 v[188:191], v146 offset:19456
	ds_read_b128 v[192:195], v146 offset:20480
	ds_read_b128 v[204:207], v146 offset:21504
	ds_read_b128 v[220:223], v146 offset:22528
	ds_read_b128 v[224:227], v146 offset:23552
	global_load_lds_dwordx4 v[142:143], off
	s_add_i32 m0, s80, 0x2000
	v_lshl_add_u64 v[196:197], s[70:71], 0, v[132:133]
	s_add_u32 s70, s70, s2
	s_addc_u32 s71, s71, 0
	s_add_i32 s80, s81, s15
	global_load_lds_dwordx4 v[196:197], off
	v_lshl_add_u64 v[208:209], s[70:71], 0, v[2:3]
	s_mov_b32 m0, s80
	v_lshl_add_u64 v[228:229], s[70:71], 0, v[132:133]
	global_load_lds_dwordx4 v[208:209], off
	s_add_i32 m0, s80, 0x2000
	v_lshl_add_u64 v[230:231], s[12:13], 0, v[2:3]
	global_load_lds_dwordx4 v[228:229], off
	s_mov_b32 m0, s16
	v_lshl_add_u64 v[232:233], s[12:13], 0, v[132:133]
	global_load_lds_dwordx4 v[230:231], off
	s_mov_b32 m0, s17
	s_nop 0
	global_load_lds_dwordx4 v[232:233], off
	s_waitcnt vmcnt(8)
	s_waitcnt lgkmcnt(0)
	s_setprio 1
	s_barrier
; #define PG8_STAGE(bufoff, gbase, voff) do { _Pragma("unroll") for (int _i = 0; _i < 2; ++_i) \
;         __builtin_amdgcn_global_load_lds((const unsigned*)((const char*)(gbase) + (voff)[_i]), (LAS unsigned*)(lds + (bufoff) + ldsw + _i * 8192), 16, 0, 0); } while (0)
; #define PG8_LDA(dst, b, h) do { _Pragma("unroll") for (int m = 0; m < 4; ++m) _Pragma("unroll") for (int k = 0; k < 2; ++k) dst[m][k] = *(const LAS half8*)(lds + PG8_SA(b, h) + aoff + m * 2048 + k * 1024); } while (0)
; #define PG8_LDB(dst, b, h) do { _Pragma("unroll") for (int n = 0; n < 2; ++n) _Pragma("unroll") for (int k = 0; k < 2; ++k) dst[n][k] = *(const LAS half8*)(lds + PG8_SB(b, h) + boff + n * 2048 + k * 1024); } while (0)
; #define PG8_MMA(ai, bj, At, Bt) do { __builtin_amdgcn_s_setprio(1); _Pragma("unroll") for (int m = 0; m < 4; ++m) _Pragma("unroll") for (int n = 0; n < 2; ++n) _Pragma("unroll") for (int k = 0; k < 2; ++k) \
;         acc[ai][bj][m][n] = __builtin_amdgcn_mfma_f32_16x16x32_f16(Bt[n][k], At[m][k], acc[ai][bj][m][n], 0, 0, 0); __builtin_amdgcn_s_setprio(0); } while (0)
; #define PG8_WAIT_V(n) asm volatile("s_waitcnt vmcnt(" #n ")" ::: "memory")
; #define PG8_WAIT_L(n) asm volatile("s_waitcnt lgkmcnt(" #n ")" ::: "memory")
; #define PG8_BAR __builtin_amdgcn_s_barrier()
; #define PG8_SCHED __builtin_amdgcn_sched_barrier(0)
; template <class Epi, class Sched, bool ALIGN_EPI = false, bool SP2 = false>
; __device__ __forceinline__ void gemm_phase(LAS unsigned char* lds, const Gemm g, const Sched& S, const Epi& E) {
;     ...
;             PG8_WAIT_V(8); PG8_WAIT_L(0); PG8_BAR; PG8_MMA(1, 0, At, B0); PG8_MMA(1, 1, At, B1); PG8_BAR; PG8_SCHED;
;             PG8_LDB(B0, 1, 0); PG8_LDB(B1, 1, 1); PG8_SCHED; PG8_LDA(At, 1, 0); PG8_STAGE(PG8_SA(0, 1), a2 + hstepA, voffA);
;             PG8_WAIT_V(8); PG8_WAIT_L(0); PG8_BAR; PG8_MMA(0, 0, At, B0); PG8_MMA(0, 1, At, B1); PG8_BAR; PG8_SCHED;
	v_mfma_f32_16x16x32_f16 v[64:67], v[138:141], v[176:179], v[64:67]
	v_mfma_f32_16x16x32_f16 v[60:63], v[152:155], v[176:179], v[60:63]
	v_mfma_f32_16x16x32_f16 v[48:51], v[138:141], v[184:187], v[48:51]
	v_mfma_f32_16x16x32_f16 v[44:47], v[152:155], v[184:187], v[44:47]
	v_mfma_f32_16x16x32_f16 v[32:35], v[138:141], v[192:195], v[32:35]
	v_mfma_f32_16x16x32_f16 v[28:31], v[152:155], v[192:195], v[28:31]
	v_mfma_f32_16x16x32_f16 v[16:19], v[138:141], v[220:223], v[16:19]
	v_mfma_f32_16x16x32_f16 v[12:15], v[152:155], v[220:223], v[12:15]
	v_mfma_f32_16x16x32_f16 v[64:67], v[148:151], v[180:183], v[64:67]
	v_mfma_f32_16x16x32_f16 v[60:63], v[156:159], v[180:183], v[60:63]
	v_mfma_f32_16x16x32_f16 v[48:51], v[148:151], v[188:191], v[48:51]
	v_mfma_f32_16x16x32_f16 v[44:47], v[156:159], v[188:191], v[44:47]
	v_mfma_f32_16x16x32_f16 v[32:35], v[148:151], v[204:207], v[32:35]
	v_mfma_f32_16x16x32_f16 v[28:31], v[156:159], v[204:207], v[28:31]
	v_mfma_f32_16x16x32_f16 v[16:19], v[148:151], v[224:227], v[16:19]
	v_mfma_f32_16x16x32_f16 v[12:15], v[156:159], v[224:227], v[12:15]
	v_mfma_f32_16x16x32_f16 v[56:59], v[160:163], v[176:179], v[56:59]
	v_mfma_f32_16x16x32_f16 v[52:55], v[168:171], v[176:179], v[52:55]
	v_mfma_f32_16x16x32_f16 v[40:43], v[160:163], v[184:187], v[40:43]
	v_mfma_f32_16x16x32_f16 v[36:39], v[168:171], v[184:187], v[36:39]
	v_mfma_f32_16x16x32_f16 v[24:27], v[160:163], v[192:195], v[24:27]
	v_mfma_f32_16x16x32_f16 v[20:23], v[168:171], v[192:195], v[20:23]
	v_mfma_f32_16x16x32_f16 v[8:11], v[160:163], v[220:223], v[8:11]
	v_mfma_f32_16x16x32_f16 v[4:7], v[168:171], v[220:223], v[4:7]
	v_mfma_f32_16x16x32_f16 v[56:59], v[164:167], v[180:183], v[56:59]
	v_mfma_f32_16x16x32_f16 v[52:55], v[172:175], v[180:183], v[52:55]
	v_mfma_f32_16x16x32_f16 v[40:43], v[164:167], v[188:191], v[40:43]
	v_mfma_f32_16x16x32_f16 v[36:39], v[172:175], v[188:191], v[36:39]
	v_mfma_f32_16x16x32_f16 v[24:27], v[164:167], v[204:207], v[24:27]
	v_mfma_f32_16x16x32_f16 v[20:23], v[172:175], v[204:207], v[20:23]
	v_mfma_f32_16x16x32_f16 v[8:11], v[164:167], v[224:227], v[8:11]
	v_mfma_f32_16x16x32_f16 v[4:7], v[172:175], v[224:227], v[4:7]
	s_barrier
	s_setprio 0
	s_add_i32 s70, 0, 0x18000
	v_add_u32_e32 v147, s70, v144
	s_add_i32 s71, 0, 0x1c000
	ds_read_b128 v[138:141], v147
	ds_read_b128 v[148:151], v147 offset:1024
	ds_read_b128 v[152:155], v147 offset:2048
	ds_read_b128 v[156:159], v147 offset:3072
	v_add_u32_e32 v147, s71, v144
	ds_read_b128 v[160:163], v147
	ds_read_b128 v[164:167], v147 offset:1024
	ds_read_b128 v[168:171], v147 offset:2048
	ds_read_b128 v[172:175], v147 offset:3072
	s_add_u32 s12, s12, s2
	s_addc_u32 s13, s13, 0
	s_mov_b32 m0, s22
	v_lshl_add_u64 v[234:235], s[12:13], 0, v[2:3]
	ds_read_b128 v[176:179], v146 offset:32768
	ds_read_b128 v[180:183], v146 offset:33792
	ds_read_b128 v[184:187], v146 offset:34816
	ds_read_b128 v[188:191], v146 offset:35840
	ds_read_b128 v[192:195], v146 offset:36864
	ds_read_b128 v[204:207], v146 offset:37888
	ds_read_b128 v[220:223], v146 offset:38912
	ds_read_b128 v[224:227], v146 offset:39936
	global_load_lds_dwordx4 v[234:235], off
	v_lshl_add_u64 v[234:235], s[12:13], 0, v[132:133]
	s_mov_b32 m0, s23
	s_nop 0
	global_load_lds_dwordx4 v[234:235], off
	s_waitcnt vmcnt(8)
	s_waitcnt lgkmcnt(0)
	s_setprio 1
	s_barrier
	v_mfma_f32_16x16x32_f16 v[128:131], v[138:141], v[176:179], v[128:131]
	v_mfma_f32_16x16x32_f16 v[124:127], v[152:155], v[176:179], v[124:127]
	v_mfma_f32_16x16x32_f16 v[112:115], v[138:141], v[184:187], v[112:115]
	v_mfma_f32_16x16x32_f16 v[108:111], v[152:155], v[184:187], v[108:111]
	v_mfma_f32_16x16x32_f16 v[96:99], v[138:141], v[192:195], v[96:99]
	v_mfma_f32_16x16x32_f16 v[92:95], v[152:155], v[192:195], v[92:95]
	v_mfma_f32_16x16x32_f16 v[80:83], v[138:141], v[220:223], v[80:83]
	v_mfma_f32_16x16x32_f16 v[76:79], v[152:155], v[220:223], v[76:79]
	v_mfma_f32_16x16x32_f16 v[128:131], v[148:151], v[180:183], v[128:131]
	v_mfma_f32_16x16x32_f16 v[124:127], v[156:159], v[180:183], v[124:127]
	v_mfma_f32_16x16x32_f16 v[112:115], v[148:151], v[188:191], v[112:115]
	v_mfma_f32_16x16x32_f16 v[108:111], v[156:159], v[188:191], v[108:111]
	v_mfma_f32_16x16x32_f16 v[96:99], v[148:151], v[204:207], v[96:99]
	v_mfma_f32_16x16x32_f16 v[92:95], v[156:159], v[204:207], v[92:95]
	v_mfma_f32_16x16x32_f16 v[80:83], v[148:151], v[224:227], v[80:83]
	v_mfma_f32_16x16x32_f16 v[76:79], v[156:159], v[224:227], v[76:79]
	v_mfma_f32_16x16x32_f16 v[120:123], v[160:163], v[176:179], v[120:123]
	v_mfma_f32_16x16x32_f16 v[116:119], v[168:171], v[176:179], v[116:119]
	v_mfma_f32_16x16x32_f16 v[104:107], v[160:163], v[184:187], v[104:107]
	v_mfma_f32_16x16x32_f16 v[100:103], v[168:171], v[184:187], v[100:103]
	v_mfma_f32_16x16x32_f16 v[88:91], v[160:163], v[192:195], v[88:91]
	v_mfma_f32_16x16x32_f16 v[84:87], v[168:171], v[192:195], v[84:87]
	v_mfma_f32_16x16x32_f16 v[72:75], v[160:163], v[220:223], v[72:75]
	v_mfma_f32_16x16x32_f16 v[68:71], v[168:171], v[220:223], v[68:71]
	v_mfma_f32_16x16x32_f16 v[120:123], v[164:167], v[180:183], v[120:123]
	v_mfma_f32_16x16x32_f16 v[116:119], v[172:175], v[180:183], v[116:119]
	v_mfma_f32_16x16x32_f16 v[104:107], v[164:167], v[188:191], v[104:107]
	v_mfma_f32_16x16x32_f16 v[100:103], v[172:175], v[188:191], v[100:103]
	v_mfma_f32_16x16x32_f16 v[88:91], v[164:167], v[204:207], v[88:91]
	v_mfma_f32_16x16x32_f16 v[84:87], v[172:175], v[204:207], v[84:87]
	v_mfma_f32_16x16x32_f16 v[72:75], v[164:167], v[224:227], v[72:75]
	v_mfma_f32_16x16x32_f16 v[68:71], v[172:175], v[224:227], v[68:71]
	s_barrier
; #define PG8_STAGE(bufoff, gbase, voff) do { _Pragma("unroll") for (int _i = 0; _i < 2; ++_i) \
;         __builtin_amdgcn_global_load_lds((const unsigned*)((const char*)(gbase) + (voff)[_i]), (LAS unsigned*)(lds + (bufoff) + ldsw + _i * 8192), 16, 0, 0); } while (0)
; #define PG8_LDA(dst, b, h) do { _Pragma("unroll") for (int m = 0; m < 4; ++m) _Pragma("unroll") for (int k = 0; k < 2; ++k) dst[m][k] = *(const LAS half8*)(lds + PG8_SA(b, h) + aoff + m * 2048 + k * 1024); } while (0)
; #define PG8_MMA(ai, bj, At, Bt) do { __builtin_amdgcn_s_setprio(1); _Pragma("unroll") for (int m = 0; m < 4; ++m) _Pragma("unroll") for (int n = 0; n < 2; ++n) _Pragma("unroll") for (int k = 0; k < 2; ++k) \
;         acc[ai][bj][m][n] = __builtin_amdgcn_mfma_f32_16x16x32_f16(Bt[n][k], At[m][k], acc[ai][bj][m][n], 0, 0, 0); __builtin_amdgcn_s_setprio(0); } while (0)
; #define PG8_WAIT_V(n) asm volatile("s_waitcnt vmcnt(" #n ")" ::: "memory")
; #define PG8_WAIT_L(n) asm volatile("s_waitcnt lgkmcnt(" #n ")" ::: "memory")
; #define PG8_BAR __builtin_amdgcn_s_barrier()
; #define PG8_SCHED __builtin_amdgcn_sched_barrier(0)
; template <class Epi, class Sched, bool ALIGN_EPI = false, bool SP2 = false>
; __device__ __forceinline__ void gemm_phase(LAS unsigned char* lds, const Gemm g, const Sched& S, const Epi& E) {
;     ...
;             PG8_LDA(At, 1, 1); PG8_STAGE(PG8_SB(1, 0), b3, voffB); PG8_STAGE(PG8_SB(1, 1), b3 + hstepB, voffB); PG8_STAGE(PG8_SA(1, 0), a3, voffA);
;             PG8_WAIT_V(8); PG8_WAIT_L(0); PG8_BAR; PG8_MMA(1, 0, At, B0); PG8_MMA(1, 1, At, B1); PG8_BAR; PG8_SCHED;
	s_setprio 0
	s_add_i32 s12, s70, s15
	v_lshl_add_u64 v[142:143], v[142:143], 0, s[96:97]
	s_mov_b32 m0, s12
	ds_read_b128 v[176:179], v146 offset:49152
	ds_read_b128 v[180:183], v146 offset:50176
	ds_read_b128 v[184:187], v146 offset:51200
	ds_read_b128 v[188:191], v146 offset:52224
	ds_read_b128 v[192:195], v146 offset:53248
	ds_read_b128 v[204:207], v146 offset:54272
	ds_read_b128 v[220:223], v146 offset:55296
	ds_read_b128 v[224:227], v146 offset:56320
	global_load_lds_dwordx4 v[142:143], off
	v_lshl_add_u64 v[142:143], v[196:197], 0, s[96:97]
	s_add_i32 m0, s12, 0x2000
	s_add_i32 s12, s71, s15
	global_load_lds_dwordx4 v[142:143], off
	v_lshl_add_u64 v[142:143], v[208:209], 0, s[96:97]
	s_mov_b32 m0, s12
	s_nop 0
	global_load_lds_dwordx4 v[142:143], off
	v_lshl_add_u64 v[142:143], v[228:229], 0, s[96:97]
	s_add_i32 m0, s12, 0x2000
	s_nop 0
	global_load_lds_dwordx4 v[142:143], off
	v_lshl_add_u64 v[142:143], v[230:231], 0, s[96:97]
	s_mov_b32 m0, s25
	s_nop 0
	global_load_lds_dwordx4 v[142:143], off
	v_lshl_add_u64 v[142:143], v[232:233], 0, s[96:97]
	s_mov_b32 m0, s37
	s_nop 0
	global_load_lds_dwordx4 v[142:143], off
	s_waitcnt vmcnt(8)
	s_waitcnt lgkmcnt(0)
	s_setprio 1
	s_barrier
	v_mfma_f32_16x16x32_f16 v[64:67], v[138:141], v[176:179], v[64:67]
	v_mfma_f32_16x16x32_f16 v[60:63], v[152:155], v[176:179], v[60:63]
	v_mfma_f32_16x16x32_f16 v[48:51], v[138:141], v[184:187], v[48:51]
	v_mfma_f32_16x16x32_f16 v[44:47], v[152:155], v[184:187], v[44:47]
	v_mfma_f32_16x16x32_f16 v[32:35], v[138:141], v[192:195], v[32:35]
	v_mfma_f32_16x16x32_f16 v[28:31], v[152:155], v[192:195], v[28:31]
	v_mfma_f32_16x16x32_f16 v[16:19], v[138:141], v[220:223], v[16:19]
	v_mfma_f32_16x16x32_f16 v[12:15], v[152:155], v[220:223], v[12:15]
	v_mfma_f32_16x16x32_f16 v[64:67], v[148:151], v[180:183], v[64:67]
	v_mfma_f32_16x16x32_f16 v[60:63], v[156:159], v[180:183], v[60:63]
	v_mfma_f32_16x16x32_f16 v[48:51], v[148:151], v[188:191], v[48:51]
	v_mfma_f32_16x16x32_f16 v[44:47], v[156:159], v[188:191], v[44:47]
	v_mfma_f32_16x16x32_f16 v[32:35], v[148:151], v[204:207], v[32:35]
	v_mfma_f32_16x16x32_f16 v[28:31], v[156:159], v[204:207], v[28:31]
	v_mfma_f32_16x16x32_f16 v[16:19], v[148:151], v[224:227], v[16:19]
	v_mfma_f32_16x16x32_f16 v[12:15], v[156:159], v[224:227], v[12:15]
	v_mfma_f32_16x16x32_f16 v[56:59], v[160:163], v[176:179], v[56:59]
	v_mfma_f32_16x16x32_f16 v[52:55], v[168:171], v[176:179], v[52:55]
	v_mfma_f32_16x16x32_f16 v[40:43], v[160:163], v[184:187], v[40:43]
	v_mfma_f32_16x16x32_f16 v[36:39], v[168:171], v[184:187], v[36:39]
	v_mfma_f32_16x16x32_f16 v[24:27], v[160:163], v[192:195], v[24:27]
	v_mfma_f32_16x16x32_f16 v[20:23], v[168:171], v[192:195], v[20:23]
	v_mfma_f32_16x16x32_f16 v[8:11], v[160:163], v[220:223], v[8:11]
	v_mfma_f32_16x16x32_f16 v[4:7], v[168:171], v[220:223], v[4:7]
	v_mfma_f32_16x16x32_f16 v[56:59], v[164:167], v[180:183], v[56:59]
	v_mfma_f32_16x16x32_f16 v[52:55], v[172:175], v[180:183], v[52:55]
	v_mfma_f32_16x16x32_f16 v[40:43], v[164:167], v[188:191], v[40:43]
	v_mfma_f32_16x16x32_f16 v[36:39], v[172:175], v[188:191], v[36:39]
	v_mfma_f32_16x16x32_f16 v[24:27], v[164:167], v[204:207], v[24:27]
	v_mfma_f32_16x16x32_f16 v[20:23], v[172:175], v[204:207], v[20:23]
	v_mfma_f32_16x16x32_f16 v[8:11], v[164:167], v[224:227], v[8:11]
	v_mfma_f32_16x16x32_f16 v[4:7], v[172:175], v[224:227], v[4:7]
	s_barrier
	s_setprio 0
	s_add_u32 s10, s10, 0x100
	s_addc_u32 s11, s11, 0
	s_add_u32 s67, s67, 0x100
	s_addc_u32 s68, s68, 0
	s_cmp_ge_u32 s69, s24
	s_mov_b32 s12, s69
	s_cbranch_scc0 .LBB0_5097
	s_and_b64 vcc, exec, s[56:57]
	s_cbranch_vccz .LBB0_5100
	s_barrier

; #define PG8_STAGE(bufoff, gbase, voff) do { _Pragma("unroll") for (int _i = 0; _i < 2; ++_i) \
;         __builtin_amdgcn_global_load_lds((const unsigned*)((const char*)(gbase) + (voff)[_i]), (LAS unsigned*)(lds + (bufoff) + ldsw + _i * 8192), 16, 0, 0); } while (0)
; #define PG8_LDA(dst, b, h) do { _Pragma("unroll") for (int m = 0; m < 4; ++m) _Pragma("unroll") for (int k = 0; k < 2; ++k) dst[m][k] = *(const LAS half8*)(lds + PG8_SA(b, h) + aoff + m * 2048 + k * 1024); } while (0)
; #define PG8_LDB(dst, b, h) do { _Pragma("unroll") for (int n = 0; n < 2; ++n) _Pragma("unroll") for (int k = 0; k < 2; ++k) dst[n][k] = *(const LAS half8*)(lds + PG8_SB(b, h) + boff + n * 2048 + k * 1024); } while (0)
; #define PG8_MMA(ai, bj, At, Bt) do { __builtin_amdgcn_s_setprio(1); _Pragma("unroll") for (int m = 0; m < 4; ++m) _Pragma("unroll") for (int n = 0; n < 2; ++n) _Pragma("unroll") for (int k = 0; k < 2; ++k) \
;         acc[ai][bj][m][n] = __builtin_amdgcn_mfma_f32_16x16x32_f16(Bt[n][k], At[m][k], acc[ai][bj][m][n], 0, 0, 0); __builtin_amdgcn_s_setprio(0); } while (0)
; #define PG8_WAIT_V(n) asm volatile("s_waitcnt vmcnt(" #n ")" ::: "memory")
; #define PG8_WAIT_L(n) asm volatile("s_waitcnt lgkmcnt(" #n ")" ::: "memory")
; #define PG8_BAR __builtin_amdgcn_s_barrier()
; #define PG8_SCHED __builtin_amdgcn_sched_barrier(0)
; template <class Epi, class Sched, bool ALIGN_EPI = false, bool SP2 = false>
; __device__ __forceinline__ void gemm_phase(LAS unsigned char* lds, const Gemm g, const Sched& S, const Epi& E) {
;     ...
;             const char* a1 = cA + (size_t)(t + 1) * kstep;
;             const char* a2 = last ? nA : cA + (size_t)(t + 2) * kstep; const char* b2 = last ? nB : cB + (size_t)(t + 2) * kstep;
;             const char* a3 = a2 + kstep; const char* b3 = b2 + kstep;
;             if (last && has_next) S.a_ready(nxt);
;             if constexpr (SP2) {
;             PG8_LDB(B0, 0, 0); PG8_LDB(B1, 0, 1); PG8_SCHED; PG8_LDA(At, 0, 0); PG8_STAGE(PG8_SA(1, 1), a1 + hstepA, voffA);
;             PG8_WAIT_V(8); PG8_WAIT_L(0); PG8_BAR; PG8_MMA(0, 0, At, B0); PG8_MMA(0, 1, At, B1); PG8_BAR; PG8_SCHED;
;             PG8_LDA(At, 0, 1); PG8_STAGE(PG8_SB(0, 0), b2, voffB); PG8_STAGE(PG8_SB(0, 1), b2 + hstepB, voffB); PG8_STAGE(PG8_SA(0, 0), a2, voffA);
.LBB0_5227:
	s_add_i32 s41, s41, 2
	s_add_u32 s16, s8, s22
	s_addc_u32 s17, s9, s23
	s_add_u32 s16, s16, 0x100
	s_addc_u32 s17, s17, 0
	s_add_u32 s80, s13, s22
	s_addc_u32 s81, s40, s23
	s_add_i32 s86, 0, 0x10000
	s_cmp_eq_u32 s68, s22
	s_cselect_b32 s17, s15, s17
	s_cselect_b32 s16, s14, s16
	s_cselect_b32 s81, s11, s81
	s_cselect_b32 s80, s10, s80
	s_add_i32 s88, 0, 0x14000
	v_add_u32_e32 v160, s86, v146
	v_add_u32_e32 v176, s88, v146
	ds_read_b128 v[148:151], v160
	ds_read_b128 v[152:155], v160 offset:1024
	ds_read_b128 v[156:159], v160 offset:2048
	ds_read_b128 v[160:163], v160 offset:3072
	ds_read_b128 v[164:167], v176
	ds_read_b128 v[168:171], v176 offset:1024
	ds_read_b128 v[172:175], v176 offset:2048
	ds_read_b128 v[176:179], v176 offset:3072
	v_lshl_add_u64 v[196:197], v[142:143], 0, s[22:23]
	s_add_i32 m0, s61, 0xc000
	ds_read_b128 v[180:183], v147
	ds_read_b128 v[184:187], v147 offset:1024
	ds_read_b128 v[188:191], v147 offset:2048
	ds_read_b128 v[192:195], v147 offset:3072
	ds_read_b128 v[206:209], v147 offset:4096
	ds_read_b128 v[220:223], v147 offset:5120
	ds_read_b128 v[224:227], v147 offset:6144
	ds_read_b128 v[228:231], v147 offset:7168
	global_load_lds_dwordx4 v[196:197], off
	v_lshl_add_u64 v[196:197], v[144:145], 0, s[22:23]
	s_add_i32 m0, s61, 0xe000
	s_nop 0
	global_load_lds_dwordx4 v[196:197], off
	s_waitcnt vmcnt(8)
	s_waitcnt lgkmcnt(0)
	s_setprio 1
	s_barrier
	v_mfma_f32_16x16x32_f16 v[128:131], v[148:151], v[180:183], v[128:131]
	v_mfma_f32_16x16x32_f16 v[124:127], v[156:159], v[180:183], v[124:127]
	v_mfma_f32_16x16x32_f16 v[112:115], v[148:151], v[188:191], v[112:115]
	v_mfma_f32_16x16x32_f16 v[108:111], v[156:159], v[188:191], v[108:111]
	v_mfma_f32_16x16x32_f16 v[96:99], v[148:151], v[206:209], v[96:99]
	v_mfma_f32_16x16x32_f16 v[92:95], v[156:159], v[206:209], v[92:95]
	v_mfma_f32_16x16x32_f16 v[80:83], v[148:151], v[224:227], v[80:83]
	v_mfma_f32_16x16x32_f16 v[76:79], v[156:159], v[224:227], v[76:79]
	v_mfma_f32_16x16x32_f16 v[128:131], v[152:155], v[184:187], v[128:131]
	v_mfma_f32_16x16x32_f16 v[124:127], v[160:163], v[184:187], v[124:127]
	v_mfma_f32_16x16x32_f16 v[112:115], v[152:155], v[192:195], v[112:115]
	v_mfma_f32_16x16x32_f16 v[108:111], v[160:163], v[192:195], v[108:111]
	v_mfma_f32_16x16x32_f16 v[96:99], v[152:155], v[220:223], v[96:99]
	v_mfma_f32_16x16x32_f16 v[92:95], v[160:163], v[220:223], v[92:95]
	v_mfma_f32_16x16x32_f16 v[80:83], v[152:155], v[228:231], v[80:83]
	v_mfma_f32_16x16x32_f16 v[76:79], v[160:163], v[228:231], v[76:79]
	v_mfma_f32_16x16x32_f16 v[120:123], v[164:167], v[180:183], v[120:123]
	v_mfma_f32_16x16x32_f16 v[116:119], v[172:175], v[180:183], v[116:119]
	v_mfma_f32_16x16x32_f16 v[104:107], v[164:167], v[188:191], v[104:107]
	v_mfma_f32_16x16x32_f16 v[100:103], v[172:175], v[188:191], v[100:103]
	v_mfma_f32_16x16x32_f16 v[88:91], v[164:167], v[206:209], v[88:91]
	v_mfma_f32_16x16x32_f16 v[84:87], v[172:175], v[206:209], v[84:87]
	v_mfma_f32_16x16x32_f16 v[72:75], v[164:167], v[224:227], v[72:75]
	v_mfma_f32_16x16x32_f16 v[68:71], v[172:175], v[224:227], v[68:71]
	v_mfma_f32_16x16x32_f16 v[120:123], v[168:171], v[184:187], v[120:123]
	v_mfma_f32_16x16x32_f16 v[116:119], v[176:179], v[184:187], v[116:119]
	v_mfma_f32_16x16x32_f16 v[104:107], v[168:171], v[192:195], v[104:107]
	v_mfma_f32_16x16x32_f16 v[100:103], v[176:179], v[192:195], v[100:103]
	v_mfma_f32_16x16x32_f16 v[88:91], v[168:171], v[220:223], v[88:91]
	v_mfma_f32_16x16x32_f16 v[84:87], v[176:179], v[220:223], v[84:87]
	v_mfma_f32_16x16x32_f16 v[72:75], v[168:171], v[228:231], v[72:75]
	v_mfma_f32_16x16x32_f16 v[68:71], v[176:179], v[228:231], v[68:71]
	s_barrier
	s_setprio 0
	s_add_i32 s86, s86, s59
	v_lshl_add_u64 v[196:197], s[80:81], 0, v[2:3]
	s_mov_b32 m0, s86
	ds_read_b128 v[180:183], v147 offset:16384
	ds_read_b128 v[184:187], v147 offset:17408
	ds_read_b128 v[188:191], v147 offset:18432
	ds_read_b128 v[192:195], v147 offset:19456
	ds_read_b128 v[206:209], v147 offset:20480
	ds_read_b128 v[220:223], v147 offset:21504
	ds_read_b128 v[224:227], v147 offset:22528
	ds_read_b128 v[228:231], v147 offset:23552
	global_load_lds_dwordx4 v[196:197], off
	s_add_i32 m0, s86, 0x2000
	v_lshl_add_u64 v[232:233], s[80:81], 0, v[132:133]
	s_add_u32 s80, s80, s2
	s_addc_u32 s81, s81, 0
	s_add_i32 s86, s88, s59
	global_load_lds_dwordx4 v[232:233], off
	v_lshl_add_u64 v[234:235], s[80:81], 0, v[2:3]
	s_mov_b32 m0, s86
	v_lshl_add_u64 v[236:237], s[80:81], 0, v[132:133]
	global_load_lds_dwordx4 v[234:235], off
	s_add_i32 m0, s86, 0x2000
	v_lshl_add_u64 v[240:241], s[16:17], 0, v[136:137]
	global_load_lds_dwordx4 v[236:237], off
	s_mov_b32 m0, s61
	v_lshl_add_u64 v[242:243], s[16:17], 0, v[134:135]
	global_load_lds_dwordx4 v[240:241], off
	s_mov_b32 m0, s62
	s_nop 0
	global_load_lds_dwordx4 v[242:243], off
	s_waitcnt vmcnt(8)
	s_waitcnt lgkmcnt(0)
	s_setprio 1
	s_barrier
; #define PG8_STAGE(bufoff, gbase, voff) do { _Pragma("unroll") for (int _i = 0; _i < 2; ++_i) \
;         __builtin_amdgcn_global_load_lds((const unsigned*)((const char*)(gbase) + (voff)[_i]), (LAS unsigned*)(lds + (bufoff) + ldsw + _i * 8192), 16, 0, 0); } while (0)
; #define PG8_LDA(dst, b, h) do { _Pragma("unroll") for (int m = 0; m < 4; ++m) _Pragma("unroll") for (int k = 0; k < 2; ++k) dst[m][k] = *(const LAS half8*)(lds + PG8_SA(b, h) + aoff + m * 2048 + k * 1024); } while (0)
; #define PG8_LDB(dst, b, h) do { _Pragma("unroll") for (int n = 0; n < 2; ++n) _Pragma("unroll") for (int k = 0; k < 2; ++k) dst[n][k] = *(const LAS half8*)(lds + PG8_SB(b, h) + boff + n * 2048 + k * 1024); } while (0)
; #define PG8_MMA(ai, bj, At, Bt) do { __builtin_amdgcn_s_setprio(1); _Pragma("unroll") for (int m = 0; m < 4; ++m) _Pragma("unroll") for (int n = 0; n < 2; ++n) _Pragma("unroll") for (int k = 0; k < 2; ++k) \
;         acc[ai][bj][m][n] = __builtin_amdgcn_mfma_f32_16x16x32_f16(Bt[n][k], At[m][k], acc[ai][bj][m][n], 0, 0, 0); __builtin_amdgcn_s_setprio(0); } while (0)
; #define PG8_WAIT_V(n) asm volatile("s_waitcnt vmcnt(" #n ")" ::: "memory")
; #define PG8_WAIT_L(n) asm volatile("s_waitcnt lgkmcnt(" #n ")" ::: "memory")
; #define PG8_BAR __builtin_amdgcn_s_barrier()
; #define PG8_SCHED __builtin_amdgcn_sched_barrier(0)
; template <class Epi, class Sched, bool ALIGN_EPI = false, bool SP2 = false>
; __device__ __forceinline__ void gemm_phase(LAS unsigned char* lds, const Gemm g, const Sched& S, const Epi& E) {
;     ...
;             PG8_WAIT_V(8); PG8_WAIT_L(0); PG8_BAR; PG8_MMA(1, 0, At, B0); PG8_MMA(1, 1, At, B1); PG8_BAR; PG8_SCHED;
;             PG8_LDB(B0, 1, 0); PG8_LDB(B1, 1, 1); PG8_SCHED; PG8_LDA(At, 1, 0); PG8_STAGE(PG8_SA(0, 1), a2 + hstepA, voffA);
;             PG8_WAIT_V(8); PG8_WAIT_L(0); PG8_BAR; PG8_MMA(0, 0, At, B0); PG8_MMA(0, 1, At, B1); PG8_BAR; PG8_SCHED;
	v_mfma_f32_16x16x32_f16 v[64:67], v[148:151], v[180:183], v[64:67]
	v_mfma_f32_16x16x32_f16 v[60:63], v[156:159], v[180:183], v[60:63]
	v_mfma_f32_16x16x32_f16 v[48:51], v[148:151], v[188:191], v[48:51]
	v_mfma_f32_16x16x32_f16 v[44:47], v[156:159], v[188:191], v[44:47]
	v_mfma_f32_16x16x32_f16 v[32:35], v[148:151], v[206:209], v[32:35]
	v_mfma_f32_16x16x32_f16 v[28:31], v[156:159], v[206:209], v[28:31]
	v_mfma_f32_16x16x32_f16 v[16:19], v[148:151], v[224:227], v[16:19]
	v_mfma_f32_16x16x32_f16 v[12:15], v[156:159], v[224:227], v[12:15]
	v_mfma_f32_16x16x32_f16 v[64:67], v[152:155], v[184:187], v[64:67]
	v_mfma_f32_16x16x32_f16 v[60:63], v[160:163], v[184:187], v[60:63]
	v_mfma_f32_16x16x32_f16 v[48:51], v[152:155], v[192:195], v[48:51]
	v_mfma_f32_16x16x32_f16 v[44:47], v[160:163], v[192:195], v[44:47]
	v_mfma_f32_16x16x32_f16 v[32:35], v[152:155], v[220:223], v[32:35]
	v_mfma_f32_16x16x32_f16 v[28:31], v[160:163], v[220:223], v[28:31]
	v_mfma_f32_16x16x32_f16 v[16:19], v[152:155], v[228:231], v[16:19]
	v_mfma_f32_16x16x32_f16 v[12:15], v[160:163], v[228:231], v[12:15]
	v_mfma_f32_16x16x32_f16 v[56:59], v[164:167], v[180:183], v[56:59]
	v_mfma_f32_16x16x32_f16 v[52:55], v[172:175], v[180:183], v[52:55]
	v_mfma_f32_16x16x32_f16 v[40:43], v[164:167], v[188:191], v[40:43]
	v_mfma_f32_16x16x32_f16 v[36:39], v[172:175], v[188:191], v[36:39]
	v_mfma_f32_16x16x32_f16 v[24:27], v[164:167], v[206:209], v[24:27]
	v_mfma_f32_16x16x32_f16 v[20:23], v[172:175], v[206:209], v[20:23]
	v_mfma_f32_16x16x32_f16 v[8:11], v[164:167], v[224:227], v[8:11]
	v_mfma_f32_16x16x32_f16 v[4:7], v[172:175], v[224:227], v[4:7]
	v_mfma_f32_16x16x32_f16 v[56:59], v[168:171], v[184:187], v[56:59]
	v_mfma_f32_16x16x32_f16 v[52:55], v[176:179], v[184:187], v[52:55]
	v_mfma_f32_16x16x32_f16 v[40:43], v[168:171], v[192:195], v[40:43]
	v_mfma_f32_16x16x32_f16 v[36:39], v[176:179], v[192:195], v[36:39]
	v_mfma_f32_16x16x32_f16 v[24:27], v[168:171], v[220:223], v[24:27]
	v_mfma_f32_16x16x32_f16 v[20:23], v[176:179], v[220:223], v[20:23]
	v_mfma_f32_16x16x32_f16 v[8:11], v[168:171], v[228:231], v[8:11]
	v_mfma_f32_16x16x32_f16 v[4:7], v[176:179], v[228:231], v[4:7]
	s_barrier
	s_setprio 0
	s_add_i32 s80, 0, 0x18000
	s_add_i32 s81, 0, 0x1c000
	v_add_u32_e32 v160, s80, v146
	v_add_u32_e32 v176, s81, v146
	ds_read_b128 v[148:151], v160
	ds_read_b128 v[152:155], v160 offset:1024
	ds_read_b128 v[156:159], v160 offset:2048
	ds_read_b128 v[160:163], v160 offset:3072
	ds_read_b128 v[164:167], v176
	ds_read_b128 v[168:171], v176 offset:1024
	ds_read_b128 v[172:175], v176 offset:2048
	ds_read_b128 v[176:179], v176 offset:3072
	s_add_u32 s16, s16, s2
	s_addc_u32 s17, s17, 0
	s_mov_b32 m0, s63
	v_lshl_add_u64 v[244:245], s[16:17], 0, v[136:137]
	ds_read_b128 v[180:183], v147 offset:32768
	ds_read_b128 v[184:187], v147 offset:33792
	ds_read_b128 v[188:191], v147 offset:34816
	ds_read_b128 v[192:195], v147 offset:35840
	ds_read_b128 v[206:209], v147 offset:36864
	ds_read_b128 v[220:223], v147 offset:37888
	ds_read_b128 v[224:227], v147 offset:38912
	ds_read_b128 v[228:231], v147 offset:39936
	global_load_lds_dwordx4 v[244:245], off
	v_lshl_add_u64 v[244:245], s[16:17], 0, v[134:135]
	s_mov_b32 m0, s64
	s_nop 0
	global_load_lds_dwordx4 v[244:245], off
	s_waitcnt vmcnt(8)
	s_waitcnt lgkmcnt(0)
	s_setprio 1
	s_barrier
	v_mfma_f32_16x16x32_f16 v[128:131], v[148:151], v[180:183], v[128:131]
	v_mfma_f32_16x16x32_f16 v[124:127], v[156:159], v[180:183], v[124:127]
	v_mfma_f32_16x16x32_f16 v[112:115], v[148:151], v[188:191], v[112:115]
	v_mfma_f32_16x16x32_f16 v[108:111], v[156:159], v[188:191], v[108:111]
	v_mfma_f32_16x16x32_f16 v[96:99], v[148:151], v[206:209], v[96:99]
	v_mfma_f32_16x16x32_f16 v[92:95], v[156:159], v[206:209], v[92:95]
	v_mfma_f32_16x16x32_f16 v[80:83], v[148:151], v[224:227], v[80:83]
	v_mfma_f32_16x16x32_f16 v[76:79], v[156:159], v[224:227], v[76:79]
	v_mfma_f32_16x16x32_f16 v[128:131], v[152:155], v[184:187], v[128:131]
	v_mfma_f32_16x16x32_f16 v[124:127], v[160:163], v[184:187], v[124:127]
	v_mfma_f32_16x16x32_f16 v[112:115], v[152:155], v[192:195], v[112:115]
	v_mfma_f32_16x16x32_f16 v[108:111], v[160:163], v[192:195], v[108:111]
	v_mfma_f32_16x16x32_f16 v[96:99], v[152:155], v[220:223], v[96:99]
	v_mfma_f32_16x16x32_f16 v[92:95], v[160:163], v[220:223], v[92:95]
	v_mfma_f32_16x16x32_f16 v[80:83], v[152:155], v[228:231], v[80:83]
	v_mfma_f32_16x16x32_f16 v[76:79], v[160:163], v[228:231], v[76:79]
	v_mfma_f32_16x16x32_f16 v[120:123], v[164:167], v[180:183], v[120:123]
	v_mfma_f32_16x16x32_f16 v[116:119], v[172:175], v[180:183], v[116:119]
	v_mfma_f32_16x16x32_f16 v[104:107], v[164:167], v[188:191], v[104:107]
	v_mfma_f32_16x16x32_f16 v[100:103], v[172:175], v[188:191], v[100:103]
	v_mfma_f32_16x16x32_f16 v[88:91], v[164:167], v[206:209], v[88:91]
	v_mfma_f32_16x16x32_f16 v[84:87], v[172:175], v[206:209], v[84:87]
	v_mfma_f32_16x16x32_f16 v[72:75], v[164:167], v[224:227], v[72:75]
	v_mfma_f32_16x16x32_f16 v[68:71], v[172:175], v[224:227], v[68:71]
	v_mfma_f32_16x16x32_f16 v[120:123], v[168:171], v[184:187], v[120:123]
	v_mfma_f32_16x16x32_f16 v[116:119], v[176:179], v[184:187], v[116:119]
	v_mfma_f32_16x16x32_f16 v[104:107], v[168:171], v[192:195], v[104:107]
	v_mfma_f32_16x16x32_f16 v[100:103], v[176:179], v[192:195], v[100:103]
	v_mfma_f32_16x16x32_f16 v[88:91], v[168:171], v[220:223], v[88:91]
	v_mfma_f32_16x16x32_f16 v[84:87], v[176:179], v[220:223], v[84:87]
	v_mfma_f32_16x16x32_f16 v[72:75], v[168:171], v[228:231], v[72:75]
	v_mfma_f32_16x16x32_f16 v[68:71], v[176:179], v[228:231], v[68:71]
	s_barrier
; #define PG8_STAGE(bufoff, gbase, voff) do { _Pragma("unroll") for (int _i = 0; _i < 2; ++_i) \
;         __builtin_amdgcn_global_load_lds((const unsigned*)((const char*)(gbase) + (voff)[_i]), (LAS unsigned*)(lds + (bufoff) + ldsw + _i * 8192), 16, 0, 0); } while (0)
; #define PG8_LDA(dst, b, h) do { _Pragma("unroll") for (int m = 0; m < 4; ++m) _Pragma("unroll") for (int k = 0; k < 2; ++k) dst[m][k] = *(const LAS half8*)(lds + PG8_SA(b, h) + aoff + m * 2048 + k * 1024); } while (0)
; #define PG8_MMA(ai, bj, At, Bt) do { __builtin_amdgcn_s_setprio(1); _Pragma("unroll") for (int m = 0; m < 4; ++m) _Pragma("unroll") for (int n = 0; n < 2; ++n) _Pragma("unroll") for (int k = 0; k < 2; ++k) \
;         acc[ai][bj][m][n] = __builtin_amdgcn_mfma_f32_16x16x32_f16(Bt[n][k], At[m][k], acc[ai][bj][m][n], 0, 0, 0); __builtin_amdgcn_s_setprio(0); } while (0)
; #define PG8_WAIT_V(n) asm volatile("s_waitcnt vmcnt(" #n ")" ::: "memory")
; #define PG8_WAIT_L(n) asm volatile("s_waitcnt lgkmcnt(" #n ")" ::: "memory")
; #define PG8_BAR __builtin_amdgcn_s_barrier()
; #define PG8_SCHED __builtin_amdgcn_sched_barrier(0)
; template <class Epi, class Sched, bool ALIGN_EPI = false, bool SP2 = false>
; __device__ __forceinline__ void gemm_phase(LAS unsigned char* lds, const Gemm g, const Sched& S, const Epi& E) {
;     ...
;             PG8_LDA(At, 1, 1); PG8_STAGE(PG8_SB(1, 0), b3, voffB); PG8_STAGE(PG8_SB(1, 1), b3 + hstepB, voffB); PG8_STAGE(PG8_SA(1, 0), a3, voffA);
;             PG8_WAIT_V(8); PG8_WAIT_L(0); PG8_BAR; PG8_MMA(1, 0, At, B0); PG8_MMA(1, 1, At, B1); PG8_BAR; PG8_SCHED;
;     ...
;         if (!has_next) break;
; #pragma unroll
;         for (int a = 0; a < 2; ++a)
; #pragma unroll
;             for (int b = 0; b < 2; ++b)
; #pragma unroll
;                 for (int m = 0; m < 4; ++m)
; #pragma unroll
;                     for (int n = 0; n < 2; ++n) acc[a][b][m][n] = (f32x4){0.f, 0.f, 0.f, 0.f};
;         cur = nxt; cA = nA; cB = nB; ++ui;
	s_setprio 0
	s_add_i32 s16, s80, s59
	v_lshl_add_u64 v[196:197], v[196:197], 0, s[96:97]
	s_mov_b32 m0, s16
	ds_read_b128 v[180:183], v147 offset:49152
	ds_read_b128 v[184:187], v147 offset:50176
	ds_read_b128 v[188:191], v147 offset:51200
	ds_read_b128 v[192:195], v147 offset:52224
	ds_read_b128 v[206:209], v147 offset:53248
	ds_read_b128 v[220:223], v147 offset:54272
	ds_read_b128 v[224:227], v147 offset:55296
	ds_read_b128 v[228:231], v147 offset:56320
	global_load_lds_dwordx4 v[196:197], off
	v_lshl_add_u64 v[196:197], v[232:233], 0, s[96:97]
	s_add_i32 m0, s16, 0x2000
	s_add_i32 s16, s81, s59
	global_load_lds_dwordx4 v[196:197], off
	v_lshl_add_u64 v[196:197], v[234:235], 0, s[96:97]
	s_mov_b32 m0, s16
	s_nop 0
	global_load_lds_dwordx4 v[196:197], off
	v_lshl_add_u64 v[196:197], v[236:237], 0, s[96:97]
	s_add_i32 m0, s16, 0x2000
	s_nop 0
	global_load_lds_dwordx4 v[196:197], off
	v_lshl_add_u64 v[196:197], v[240:241], 0, s[96:97]
	s_mov_b32 m0, s65
	s_nop 0
	global_load_lds_dwordx4 v[196:197], off
	v_lshl_add_u64 v[196:197], v[242:243], 0, s[96:97]
	s_mov_b32 m0, s66
	s_nop 0
	global_load_lds_dwordx4 v[196:197], off
	s_waitcnt vmcnt(8)
	s_waitcnt lgkmcnt(0)
	s_setprio 1
	s_barrier
	v_mfma_f32_16x16x32_f16 v[64:67], v[148:151], v[180:183], v[64:67]
	v_mfma_f32_16x16x32_f16 v[60:63], v[156:159], v[180:183], v[60:63]
	v_mfma_f32_16x16x32_f16 v[48:51], v[148:151], v[188:191], v[48:51]
	v_mfma_f32_16x16x32_f16 v[44:47], v[156:159], v[188:191], v[44:47]
	v_mfma_f32_16x16x32_f16 v[32:35], v[148:151], v[206:209], v[32:35]
	v_mfma_f32_16x16x32_f16 v[28:31], v[156:159], v[206:209], v[28:31]
	v_mfma_f32_16x16x32_f16 v[16:19], v[148:151], v[224:227], v[16:19]
	v_mfma_f32_16x16x32_f16 v[12:15], v[156:159], v[224:227], v[12:15]
	v_mfma_f32_16x16x32_f16 v[64:67], v[152:155], v[184:187], v[64:67]
	v_mfma_f32_16x16x32_f16 v[60:63], v[160:163], v[184:187], v[60:63]
	v_mfma_f32_16x16x32_f16 v[48:51], v[152:155], v[192:195], v[48:51]
	v_mfma_f32_16x16x32_f16 v[44:47], v[160:163], v[192:195], v[44:47]
	v_mfma_f32_16x16x32_f16 v[32:35], v[152:155], v[220:223], v[32:35]
	v_mfma_f32_16x16x32_f16 v[28:31], v[160:163], v[220:223], v[28:31]
	v_mfma_f32_16x16x32_f16 v[16:19], v[152:155], v[228:231], v[16:19]
	v_mfma_f32_16x16x32_f16 v[12:15], v[160:163], v[228:231], v[12:15]
	v_mfma_f32_16x16x32_f16 v[56:59], v[164:167], v[180:183], v[56:59]
	v_mfma_f32_16x16x32_f16 v[52:55], v[172:175], v[180:183], v[52:55]
	v_mfma_f32_16x16x32_f16 v[40:43], v[164:167], v[188:191], v[40:43]
	v_mfma_f32_16x16x32_f16 v[36:39], v[172:175], v[188:191], v[36:39]
	v_mfma_f32_16x16x32_f16 v[24:27], v[164:167], v[206:209], v[24:27]
	v_mfma_f32_16x16x32_f16 v[20:23], v[172:175], v[206:209], v[20:23]
	v_mfma_f32_16x16x32_f16 v[8:11], v[164:167], v[224:227], v[8:11]
	v_mfma_f32_16x16x32_f16 v[4:7], v[172:175], v[224:227], v[4:7]
	v_mfma_f32_16x16x32_f16 v[56:59], v[168:171], v[184:187], v[56:59]
	v_mfma_f32_16x16x32_f16 v[52:55], v[176:179], v[184:187], v[52:55]
	v_mfma_f32_16x16x32_f16 v[40:43], v[168:171], v[192:195], v[40:43]
	v_mfma_f32_16x16x32_f16 v[36:39], v[176:179], v[192:195], v[36:39]
	v_mfma_f32_16x16x32_f16 v[24:27], v[168:171], v[220:223], v[24:27]
	v_mfma_f32_16x16x32_f16 v[20:23], v[176:179], v[220:223], v[20:23]
	v_mfma_f32_16x16x32_f16 v[8:11], v[168:171], v[228:231], v[8:11]
	v_mfma_f32_16x16x32_f16 v[4:7], v[176:179], v[228:231], v[4:7]
	s_barrier
	s_setprio 0
	s_add_u32 s22, s22, 0x100
	s_addc_u32 s23, s23, 0
	s_cmp_ge_u32 s41, s67
	s_cbranch_scc0 .LBB0_5227
	s_add_u32 s16, s13, 0xffffff00
	s_addc_u32 s17, s40, -1
	s_and_b64 vcc, exec, s[38:39]
	s_cbranch_vccnz .LBB0_5214
	v_mov_b32_e32 v4, 0
	s_mov_b32 s6, s70
	s_mov_b32 s37, s71
	s_mov_b64 s[8:9], s[14:15]
	s_mov_b32 s69, s12
	v_mov_b32_e32 v5, v4
	v_mov_b32_e32 v6, v4
	v_mov_b32_e32 v7, v4
	v_mov_b32_e32 v8, v4
	v_mov_b32_e32 v9, v4
	v_mov_b32_e32 v10, v4
	v_mov_b32_e32 v11, v4
	v_mov_b32_e32 v20, v4
	v_mov_b32_e32 v21, v4
	v_mov_b32_e32 v22, v4
	v_mov_b32_e32 v23, v4
	v_mov_b32_e32 v24, v4
	v_mov_b32_e32 v25, v4
	v_mov_b32_e32 v26, v4
	v_mov_b32_e32 v27, v4
	v_mov_b32_e32 v36, v4
	v_mov_b32_e32 v37, v4
	v_mov_b32_e32 v38, v4
	v_mov_b32_e32 v39, v4
	v_mov_b32_e32 v40, v4
	v_mov_b32_e32 v41, v4
	v_mov_b32_e32 v42, v4
	v_mov_b32_e32 v43, v4
	v_mov_b32_e32 v52, v4
	v_mov_b32_e32 v53, v4
	v_mov_b32_e32 v54, v4
	v_mov_b32_e32 v55, v4
	v_mov_b32_e32 v56, v4
	v_mov_b32_e32 v57, v4
	v_mov_b32_e32 v58, v4
	v_mov_b32_e32 v59, v4
	v_mov_b32_e32 v12, v4
	v_mov_b32_e32 v13, v4
	v_mov_b32_e32 v14, v4
	v_mov_b32_e32 v15, v4
	v_mov_b32_e32 v16, v4
	v_mov_b32_e32 v17, v4
	v_mov_b32_e32 v18, v4
	v_mov_b32_e32 v19, v4
	v_mov_b32_e32 v28, v4
	v_mov_b32_e32 v29, v4
	v_mov_b32_e32 v30, v4
	v_mov_b32_e32 v31, v4
	v_mov_b32_e32 v32, v4
	v_mov_b32_e32 v33, v4
	v_mov_b32_e32 v34, v4
	v_mov_b32_e32 v35, v4
	v_mov_b32_e32 v44, v4
	v_mov_b32_e32 v45, v4
	v_mov_b32_e32 v46, v4
	v_mov_b32_e32 v47, v4
	v_mov_b32_e32 v48, v4
	v_mov_b32_e32 v49, v4
	v_mov_b32_e32 v50, v4
	v_mov_b32_e32 v51, v4
	v_mov_b32_e32 v60, v4
	v_mov_b32_e32 v61, v4
	v_mov_b32_e32 v62, v4
	v_mov_b32_e32 v63, v4
	v_mov_b32_e32 v64, v4
	v_mov_b32_e32 v65, v4
	v_mov_b32_e32 v66, v4
	v_mov_b32_e32 v67, v4
	v_mov_b32_e32 v68, v4
	v_mov_b32_e32 v69, v4
	v_mov_b32_e32 v70, v4
	v_mov_b32_e32 v71, v4
	v_mov_b32_e32 v72, v4
	v_mov_b32_e32 v73, v4
	v_mov_b32_e32 v74, v4
	v_mov_b32_e32 v75, v4
	v_mov_b32_e32 v84, v4
	v_mov_b32_e32 v85, v4
	v_mov_b32_e32 v86, v4
	v_mov_b32_e32 v87, v4
	v_mov_b32_e32 v88, v4
	v_mov_b32_e32 v89, v4
	v_mov_b32_e32 v90, v4
	v_mov_b32_e32 v91, v4
	v_mov_b32_e32 v100, v4
	v_mov_b32_e32 v101, v4
	v_mov_b32_e32 v102, v4
	v_mov_b32_e32 v103, v4
	v_mov_b32_e32 v104, v4
	v_mov_b32_e32 v105, v4
	v_mov_b32_e32 v106, v4
	v_mov_b32_e32 v107, v4
	v_mov_b32_e32 v116, v4
	v_mov_b32_e32 v117, v4
	v_mov_b32_e32 v118, v4
	v_mov_b32_e32 v119, v4
	v_mov_b32_e32 v120, v4
	v_mov_b32_e32 v121, v4
	v_mov_b32_e32 v122, v4
	v_mov_b32_e32 v123, v4
	v_mov_b32_e32 v76, v4
	v_mov_b32_e32 v77, v4
	v_mov_b32_e32 v78, v4
	v_mov_b32_e32 v79, v4
	v_mov_b32_e32 v80, v4
	v_mov_b32_e32 v81, v4
	v_mov_b32_e32 v82, v4
	v_mov_b32_e32 v83, v4
	v_mov_b32_e32 v92, v4
	v_mov_b32_e32 v93, v4
	v_mov_b32_e32 v94, v4
	v_mov_b32_e32 v95, v4
	v_mov_b32_e32 v96, v4
	v_mov_b32_e32 v97, v4
	v_mov_b32_e32 v98, v4
	v_mov_b32_e32 v99, v4
	v_mov_b32_e32 v108, v4
	v_mov_b32_e32 v109, v4
	v_mov_b32_e32 v110, v4
	v_mov_b32_e32 v111, v4
	v_mov_b32_e32 v112, v4
	v_mov_b32_e32 v113, v4
	v_mov_b32_e32 v114, v4
	v_mov_b32_e32 v115, v4
	v_mov_b32_e32 v124, v4
	v_mov_b32_e32 v125, v4
	v_mov_b32_e32 v126, v4
	v_mov_b32_e32 v127, v4
	v_mov_b32_e32 v128, v4
	v_mov_b32_e32 v129, v4
	v_mov_b32_e32 v130, v4
	v_mov_b32_e32 v131, v4
	s_andn2_b64 vcc, exec, s[0:1]
	s_cbranch_vccnz .LBB0_5215
